# early barrier k=4 tail prio 2 on all GEMM loops + dropped s_nop 0 between same-accumulator int8 MFMAs and mid-segment setprio pairs
# speedup vs baseline: 1.0064x; 1.0023x over previous
.LBB0_308:
	ds_read_b128 v[142:145], v191
	ds_read_b128 v[138:141], v191 offset:1024
	ds_read_b128 v[134:137], v191 offset:2048
	ds_read_b128 v[130:133], v191 offset:3072
	s_add_u32 s46, s44, 0xfff80080
	s_addc_u32 s47, s45, -1
	s_cmp_eq_u32 s37, 28
	s_cselect_b32 s49, s0, s47
	s_cselect_b32 s48, s1, s46
	s_cselect_b32 s47, s7, s31
	s_cselect_b32 s46, s14, s15
	v_lshl_add_u64 v[166:167], s[44:45], 0, v[162:163]
	s_add_i32 m0, s9, 0xc000
	ds_read_b128 v[170:173], v192
	ds_read_b128 v[174:177], v192 offset:1024
	s_waitcnt lgkmcnt(0)
	ds_read_b128 v[178:181], v192 offset:2048
	ds_read_b128 v[182:185], v192 offset:3072
	ds_read_b128 v[204:207], v192 offset:4096
	ds_read_b128 v[208:211], v192 offset:5120
	ds_read_b128 v[212:215], v192 offset:6144
	ds_read_b128 v[216:219], v192 offset:7168
	global_load_lds_dwordx4 v[166:167], off
	v_lshl_add_u64 v[166:167], s[44:45], 0, v[164:165]
	s_add_i32 m0, s9, 0xe000
	s_nop 0
	global_load_lds_dwordx4 v[166:167], off
	s_waitcnt lgkmcnt(8)
	s_barrier
	s_waitcnt lgkmcnt(0)
	s_setprio 1
	s_waitcnt lgkmcnt(0)
	v_mfma_i32_16x16x64_i8 v[126:129], v[142:145], v[170:173], v[126:129]
	v_mfma_i32_16x16x64_i8 v[126:129], v[138:141], v[174:177], v[126:129]
	v_mfma_i32_16x16x64_i8 v[122:125], v[134:137], v[170:173], v[122:125]
	v_mfma_i32_16x16x64_i8 v[122:125], v[130:133], v[174:177], v[122:125]
	v_mfma_i32_16x16x64_i8 v[110:113], v[142:145], v[178:181], v[110:113]
	v_mfma_i32_16x16x64_i8 v[110:113], v[138:141], v[182:185], v[110:113]
	v_mfma_i32_16x16x64_i8 v[106:109], v[134:137], v[178:181], v[106:109]
	v_mfma_i32_16x16x64_i8 v[106:109], v[130:133], v[182:185], v[106:109]
	v_mfma_i32_16x16x64_i8 v[94:97], v[142:145], v[204:207], v[94:97]
	v_mfma_i32_16x16x64_i8 v[94:97], v[138:141], v[208:211], v[94:97]
	v_mfma_i32_16x16x64_i8 v[90:93], v[134:137], v[204:207], v[90:93]
	v_mfma_i32_16x16x64_i8 v[90:93], v[130:133], v[208:211], v[90:93]
	s_barrier
	s_setprio 2
	v_mfma_i32_16x16x64_i8 v[78:81], v[142:145], v[212:215], v[78:81]
	v_mfma_i32_16x16x64_i8 v[78:81], v[138:141], v[216:219], v[78:81]
	v_mfma_i32_16x16x64_i8 v[74:77], v[134:137], v[212:215], v[74:77]
	v_mfma_i32_16x16x64_i8 v[74:77], v[130:133], v[216:219], v[74:77]
	s_setprio 0
	s_add_i32 s50, s55, s8
	v_lshl_add_u64 v[166:167], s[46:47], 0, v[148:149]
	s_mov_b32 m0, s50
	ds_read_b128 v[220:223], v193
	ds_read_b128 v[224:227], v193 offset:1024
	ds_read_b128 v[234:237], v193 offset:2048
	ds_read_b128 v[238:241], v193 offset:3072
	global_load_lds_dwordx4 v[166:167], off
	v_lshl_add_u64 v[168:169], s[46:47], 0, v[152:153]
	s_add_i32 m0, s50, 0x2000
	s_nop 0
	global_load_lds_dwordx4 v[168:169], off
	s_barrier
	s_waitcnt lgkmcnt(0)
	s_setprio 1
	s_waitcnt lgkmcnt(0)
	v_mfma_i32_16x16x64_i8 v[118:121], v[220:223], v[170:173], v[118:121]
	v_mfma_i32_16x16x64_i8 v[118:121], v[224:227], v[174:177], v[118:121]
	v_mfma_i32_16x16x64_i8 v[114:117], v[234:237], v[170:173], v[114:117]
	v_mfma_i32_16x16x64_i8 v[114:117], v[238:241], v[174:177], v[114:117]
	v_mfma_i32_16x16x64_i8 v[102:105], v[220:223], v[178:181], v[102:105]
	v_mfma_i32_16x16x64_i8 v[102:105], v[224:227], v[182:185], v[102:105]
	v_mfma_i32_16x16x64_i8 v[98:101], v[234:237], v[178:181], v[98:101]
	v_mfma_i32_16x16x64_i8 v[98:101], v[238:241], v[182:185], v[98:101]
	v_mfma_i32_16x16x64_i8 v[86:89], v[220:223], v[204:207], v[86:89]
	v_mfma_i32_16x16x64_i8 v[86:89], v[224:227], v[208:211], v[86:89]
	v_mfma_i32_16x16x64_i8 v[82:85], v[234:237], v[204:207], v[82:85]
	v_mfma_i32_16x16x64_i8 v[82:85], v[238:241], v[208:211], v[82:85]
	s_barrier
	s_setprio 2
	v_mfma_i32_16x16x64_i8 v[70:73], v[220:223], v[212:215], v[70:73]
	v_mfma_i32_16x16x64_i8 v[70:73], v[224:227], v[216:219], v[70:73]
	v_mfma_i32_16x16x64_i8 v[66:69], v[234:237], v[212:215], v[66:69]
	v_mfma_i32_16x16x64_i8 v[66:69], v[238:241], v[216:219], v[66:69]
	s_setprio 0
	s_mov_b32 m0, s9
	v_lshl_add_u64 v[170:171], s[48:49], 0, v[146:147]
	ds_read_b128 v[174:177], v192 offset:16384
	ds_read_b128 v[178:181], v192 offset:17408
	ds_read_b128 v[182:185], v192 offset:18432
	ds_read_b128 v[204:207], v192 offset:19456
	ds_read_b128 v[208:211], v192 offset:20480
	ds_read_b128 v[212:215], v192 offset:21504
	ds_read_b128 v[216:219], v192 offset:22528
	ds_read_b128 v[242:245], v192 offset:23552
	global_load_lds_dwordx4 v[170:171], off
	v_lshl_add_u64 v[172:173], s[48:49], 0, v[150:151]
	s_mov_b32 m0, s13
	s_nop 0
	global_load_lds_dwordx4 v[172:173], off
	s_barrier
	s_waitcnt lgkmcnt(0)
	s_setprio 1
	s_waitcnt lgkmcnt(0)
	v_mfma_i32_16x16x64_i8 v[62:65], v[142:145], v[174:177], v[62:65]
	v_mfma_i32_16x16x64_i8 v[62:65], v[138:141], v[178:181], v[62:65]
	v_mfma_i32_16x16x64_i8 v[58:61], v[134:137], v[174:177], v[58:61]
	v_mfma_i32_16x16x64_i8 v[58:61], v[130:133], v[178:181], v[58:61]
	v_mfma_i32_16x16x64_i8 v[46:49], v[142:145], v[182:185], v[46:49]
	v_mfma_i32_16x16x64_i8 v[46:49], v[138:141], v[204:207], v[46:49]
	v_mfma_i32_16x16x64_i8 v[42:45], v[134:137], v[182:185], v[42:45]
	v_mfma_i32_16x16x64_i8 v[42:45], v[130:133], v[204:207], v[42:45]
	v_mfma_i32_16x16x64_i8 v[30:33], v[142:145], v[208:211], v[30:33]
	v_mfma_i32_16x16x64_i8 v[30:33], v[138:141], v[212:215], v[30:33]
	v_mfma_i32_16x16x64_i8 v[26:29], v[134:137], v[208:211], v[26:29]
	v_mfma_i32_16x16x64_i8 v[26:29], v[130:133], v[212:215], v[26:29]
	s_barrier
	s_setprio 2
	v_mfma_i32_16x16x64_i8 v[14:17], v[142:145], v[216:219], v[14:17]
	v_mfma_i32_16x16x64_i8 v[14:17], v[138:141], v[242:245], v[14:17]
	v_mfma_i32_16x16x64_i8 v[10:13], v[134:137], v[216:219], v[10:13]
	v_mfma_i32_16x16x64_i8 v[10:13], v[130:133], v[242:245], v[10:13]
	s_setprio 0
	s_add_u32 s50, s46, 0x80000
	s_addc_u32 s51, s47, 0
	s_add_i32 s59, s56, s8
	v_lshl_add_u64 v[130:131], s[50:51], 0, v[148:149]
	s_mov_b32 m0, s59
	s_nop 0
	global_load_lds_dwordx4 v[130:131], off
	v_lshl_add_u64 v[130:131], s[50:51], 0, v[152:153]
	s_add_i32 m0, s59, 0x2000
	s_nop 0
	global_load_lds_dwordx4 v[130:131], off
	s_waitcnt vmcnt(6)
	s_barrier
	s_setprio 1
	v_mfma_i32_16x16x64_i8 v[54:57], v[220:223], v[174:177], v[54:57]
	v_mfma_i32_16x16x64_i8 v[54:57], v[224:227], v[178:181], v[54:57]
	v_mfma_i32_16x16x64_i8 v[50:53], v[234:237], v[174:177], v[50:53]
	v_mfma_i32_16x16x64_i8 v[50:53], v[238:241], v[178:181], v[50:53]
	v_mfma_i32_16x16x64_i8 v[38:41], v[220:223], v[182:185], v[38:41]
	v_mfma_i32_16x16x64_i8 v[38:41], v[224:227], v[204:207], v[38:41]
	v_mfma_i32_16x16x64_i8 v[34:37], v[234:237], v[182:185], v[34:37]
	v_mfma_i32_16x16x64_i8 v[34:37], v[238:241], v[204:207], v[34:37]
	v_mfma_i32_16x16x64_i8 v[22:25], v[220:223], v[208:211], v[22:25]
	v_mfma_i32_16x16x64_i8 v[22:25], v[224:227], v[212:215], v[22:25]
	v_mfma_i32_16x16x64_i8 v[18:21], v[234:237], v[208:211], v[18:21]
	v_mfma_i32_16x16x64_i8 v[18:21], v[238:241], v[212:215], v[18:21]
	s_barrier
	s_setprio 2
	v_mfma_i32_16x16x64_i8 v[6:9], v[220:223], v[216:219], v[6:9]
	v_mfma_i32_16x16x64_i8 v[6:9], v[224:227], v[242:245], v[6:9]
	v_mfma_i32_16x16x64_i8 v[2:5], v[234:237], v[216:219], v[2:5]
	v_mfma_i32_16x16x64_i8 v[2:5], v[238:241], v[242:245], v[2:5]
	s_setprio 0
	s_add_i32 s50, 0, 0x18000
	v_add_u32_e32 v142, s50, v188
	ds_read_b128 v[130:133], v142
	ds_read_b128 v[134:137], v142 offset:1024
	ds_read_b128 v[138:141], v142 offset:2048
	ds_read_b128 v[142:145], v142 offset:3072
	s_add_u32 s48, s48, 0x80000
	s_addc_u32 s49, s49, 0
	s_mov_b32 m0, s29
	v_lshl_add_u64 v[186:187], s[48:49], 0, v[146:147]
	ds_read_b128 v[174:177], v192 offset:32768
	ds_read_b128 v[178:181], v192 offset:33792
	ds_read_b128 v[182:185], v192 offset:34816
	ds_read_b128 v[204:207], v192 offset:35840
	ds_read_b128 v[208:211], v192 offset:36864
	ds_read_b128 v[212:215], v192 offset:37888
	ds_read_b128 v[216:219], v192 offset:38912
	ds_read_b128 v[220:223], v192 offset:39936
	global_load_lds_dwordx4 v[186:187], off
	v_lshl_add_u64 v[186:187], s[48:49], 0, v[150:151]
	s_mov_b32 m0, s33
	s_nop 0
	global_load_lds_dwordx4 v[186:187], off
	s_waitcnt lgkmcnt(8)
	s_barrier
	s_waitcnt lgkmcnt(0)
	s_setprio 1
	s_waitcnt lgkmcnt(0)
	v_mfma_i32_16x16x64_i8 v[126:129], v[130:133], v[174:177], v[126:129]
	v_mfma_i32_16x16x64_i8 v[126:129], v[134:137], v[178:181], v[126:129]
	v_mfma_i32_16x16x64_i8 v[122:125], v[138:141], v[174:177], v[122:125]
	v_mfma_i32_16x16x64_i8 v[122:125], v[142:145], v[178:181], v[122:125]
	v_mfma_i32_16x16x64_i8 v[110:113], v[130:133], v[182:185], v[110:113]
	v_mfma_i32_16x16x64_i8 v[110:113], v[134:137], v[204:207], v[110:113]
	v_mfma_i32_16x16x64_i8 v[106:109], v[138:141], v[182:185], v[106:109]
	v_mfma_i32_16x16x64_i8 v[106:109], v[142:145], v[204:207], v[106:109]
	v_mfma_i32_16x16x64_i8 v[94:97], v[130:133], v[208:211], v[94:97]
	v_mfma_i32_16x16x64_i8 v[94:97], v[134:137], v[212:215], v[94:97]
	v_mfma_i32_16x16x64_i8 v[90:93], v[138:141], v[208:211], v[90:93]
	v_mfma_i32_16x16x64_i8 v[90:93], v[142:145], v[212:215], v[90:93]
	s_barrier
	s_setprio 2
	v_mfma_i32_16x16x64_i8 v[78:81], v[130:133], v[216:219], v[78:81]
	v_mfma_i32_16x16x64_i8 v[78:81], v[134:137], v[220:223], v[78:81]
	v_mfma_i32_16x16x64_i8 v[74:77], v[138:141], v[216:219], v[74:77]
	v_mfma_i32_16x16x64_i8 v[74:77], v[142:145], v[220:223], v[74:77]
	s_setprio 0
	s_add_i32 s48, 0, 0x1c000
	s_add_i32 s49, s50, s8
	v_add_u32_e32 v156, s48, v188
	v_lshl_add_u64 v[166:167], v[166:167], 0, s[22:23]
	s_mov_b32 m0, s49
	ds_read_b128 v[224:227], v156
	ds_read_b128 v[234:237], v156 offset:1024
	ds_read_b128 v[238:241], v156 offset:2048
	ds_read_b128 v[242:245], v156 offset:3072
	global_load_lds_dwordx4 v[166:167], off
	v_lshl_add_u64 v[166:167], v[168:169], 0, s[22:23]
	s_add_i32 m0, s49, 0x2000
	s_nop 0
	global_load_lds_dwordx4 v[166:167], off
	s_barrier
	s_waitcnt lgkmcnt(0)
	s_setprio 1
	s_waitcnt lgkmcnt(0)
	v_mfma_i32_16x16x64_i8 v[118:121], v[224:227], v[174:177], v[118:121]
	v_mfma_i32_16x16x64_i8 v[118:121], v[234:237], v[178:181], v[118:121]
	v_mfma_i32_16x16x64_i8 v[114:117], v[238:241], v[174:177], v[114:117]
	v_mfma_i32_16x16x64_i8 v[114:117], v[242:245], v[178:181], v[114:117]
	v_mfma_i32_16x16x64_i8 v[102:105], v[224:227], v[182:185], v[102:105]
	v_mfma_i32_16x16x64_i8 v[102:105], v[234:237], v[204:207], v[102:105]
	v_mfma_i32_16x16x64_i8 v[98:101], v[238:241], v[182:185], v[98:101]
	v_mfma_i32_16x16x64_i8 v[98:101], v[242:245], v[204:207], v[98:101]
	v_mfma_i32_16x16x64_i8 v[86:89], v[224:227], v[208:211], v[86:89]
	v_mfma_i32_16x16x64_i8 v[86:89], v[234:237], v[212:215], v[86:89]
	v_mfma_i32_16x16x64_i8 v[82:85], v[238:241], v[208:211], v[82:85]
	v_mfma_i32_16x16x64_i8 v[82:85], v[242:245], v[212:215], v[82:85]
	s_barrier
	s_setprio 2
	v_mfma_i32_16x16x64_i8 v[70:73], v[224:227], v[216:219], v[70:73]
	v_mfma_i32_16x16x64_i8 v[70:73], v[234:237], v[220:223], v[70:73]
	v_mfma_i32_16x16x64_i8 v[66:69], v[238:241], v[216:219], v[66:69]
	v_mfma_i32_16x16x64_i8 v[66:69], v[242:245], v[220:223], v[66:69]
	s_setprio 0
	s_mov_b32 m0, s53
	v_lshl_add_u64 v[170:171], v[170:171], 0, s[22:23]
	ds_read_b128 v[166:169], v192 offset:49152
	ds_read_b128 v[174:177], v192 offset:50176
	ds_read_b128 v[178:181], v192 offset:51200
	ds_read_b128 v[182:185], v192 offset:52224
	ds_read_b128 v[204:207], v192 offset:53248
	ds_read_b128 v[208:211], v192 offset:54272
	ds_read_b128 v[212:215], v192 offset:55296
	ds_read_b128 v[216:219], v192 offset:56320
	global_load_lds_dwordx4 v[170:171], off
	v_lshl_add_u64 v[170:171], v[172:173], 0, s[22:23]
	s_mov_b32 m0, s54
	s_nop 0
	global_load_lds_dwordx4 v[170:171], off
	s_barrier
	s_waitcnt lgkmcnt(0)
	s_setprio 1
	s_waitcnt lgkmcnt(0)
	v_mfma_i32_16x16x64_i8 v[62:65], v[130:133], v[166:169], v[62:65]
	v_mfma_i32_16x16x64_i8 v[62:65], v[134:137], v[174:177], v[62:65]
	v_mfma_i32_16x16x64_i8 v[58:61], v[138:141], v[166:169], v[58:61]
	v_mfma_i32_16x16x64_i8 v[58:61], v[142:145], v[174:177], v[58:61]
	v_mfma_i32_16x16x64_i8 v[46:49], v[130:133], v[178:181], v[46:49]
	v_mfma_i32_16x16x64_i8 v[46:49], v[134:137], v[182:185], v[46:49]
	v_mfma_i32_16x16x64_i8 v[42:45], v[138:141], v[178:181], v[42:45]
	v_mfma_i32_16x16x64_i8 v[42:45], v[142:145], v[182:185], v[42:45]
	v_mfma_i32_16x16x64_i8 v[30:33], v[130:133], v[204:207], v[30:33]
	v_mfma_i32_16x16x64_i8 v[30:33], v[134:137], v[208:211], v[30:33]
	v_mfma_i32_16x16x64_i8 v[26:29], v[138:141], v[204:207], v[26:29]
	v_mfma_i32_16x16x64_i8 v[26:29], v[142:145], v[208:211], v[26:29]
	s_barrier
	s_setprio 2
	v_mfma_i32_16x16x64_i8 v[14:17], v[130:133], v[212:215], v[14:17]
	v_mfma_i32_16x16x64_i8 v[14:17], v[134:137], v[216:219], v[14:17]
	v_mfma_i32_16x16x64_i8 v[10:13], v[138:141], v[212:215], v[10:13]
	v_mfma_i32_16x16x64_i8 v[10:13], v[142:145], v[216:219], v[10:13]
	s_setprio 0
	s_add_u32 s46, s46, 0x80080
	s_addc_u32 s47, s47, 0
	s_add_i32 s48, s48, s8
	v_lshl_add_u64 v[130:131], s[46:47], 0, v[148:149]
	s_mov_b32 m0, s48
	s_nop 0
	global_load_lds_dwordx4 v[130:131], off
	v_lshl_add_u64 v[130:131], s[46:47], 0, v[152:153]
	s_add_i32 m0, s48, 0x2000
	s_nop 0
	global_load_lds_dwordx4 v[130:131], off
	s_waitcnt vmcnt(6)
	s_barrier
	s_setprio 1
	v_mfma_i32_16x16x64_i8 v[54:57], v[224:227], v[166:169], v[54:57]
	v_mfma_i32_16x16x64_i8 v[54:57], v[234:237], v[174:177], v[54:57]
	v_mfma_i32_16x16x64_i8 v[50:53], v[238:241], v[166:169], v[50:53]
	v_mfma_i32_16x16x64_i8 v[50:53], v[242:245], v[174:177], v[50:53]
	v_mfma_i32_16x16x64_i8 v[38:41], v[224:227], v[178:181], v[38:41]
	v_mfma_i32_16x16x64_i8 v[38:41], v[234:237], v[182:185], v[38:41]
	v_mfma_i32_16x16x64_i8 v[34:37], v[238:241], v[178:181], v[34:37]
	v_mfma_i32_16x16x64_i8 v[34:37], v[242:245], v[182:185], v[34:37]
	v_mfma_i32_16x16x64_i8 v[22:25], v[224:227], v[204:207], v[22:25]
	v_mfma_i32_16x16x64_i8 v[22:25], v[234:237], v[208:211], v[22:25]
	v_mfma_i32_16x16x64_i8 v[18:21], v[238:241], v[204:207], v[18:21]
	v_mfma_i32_16x16x64_i8 v[18:21], v[242:245], v[208:211], v[18:21]
	s_barrier
	s_setprio 2
	v_mfma_i32_16x16x64_i8 v[6:9], v[224:227], v[212:215], v[6:9]
	v_mfma_i32_16x16x64_i8 v[6:9], v[234:237], v[216:219], v[6:9]
	v_mfma_i32_16x16x64_i8 v[2:5], v[238:241], v[212:215], v[2:5]
	v_mfma_i32_16x16x64_i8 v[2:5], v[242:245], v[216:219], v[2:5]
	s_setprio 0
	s_add_i32 s37, s37, 2
	s_add_u32 s44, s44, 0x100
	s_addc_u32 s45, s45, 0
	s_add_u32 s15, s15, 0x100
	s_addc_u32 s31, s31, 0
	s_cmp_gt_u32 s37, 29
	s_cbranch_scc0 .LBB0_308
	s_nop 15
	s_nop 15
	s_and_b64 vcc, exec, s[24:25]
	s_cbranch_vccz .LBB0_311
	s_barrier

.LBB0_412:
	ds_read_b128 v[130:133], v191
	ds_read_b128 v[134:137], v191 offset:1024
	ds_read_b128 v[138:141], v191 offset:2048
	ds_read_b128 v[142:145], v191 offset:3072
	ds_read_b128 v[146:149], v192
	ds_read_b128 v[150:153], v192 offset:1024
	ds_read_b128 v[174:177], v192 offset:2048
	s_waitcnt lgkmcnt(0)
	ds_read_b128 v[178:181], v192 offset:3072
	s_add_u32 s42, s40, 0xfff00080
	s_addc_u32 s43, s41, -1
	s_cmp_eq_u32 s29, 60
	s_cselect_b32 s45, s0, s43
	s_cselect_b32 s44, s1, s42
	s_cselect_b32 s43, s7, s27
	s_cselect_b32 s42, s14, s15
	v_lshl_add_u64 v[186:187], s[40:41], 0, v[170:171]
	s_add_i32 m0, s9, 0xc000
	ds_read_b128 v[182:185], v193
	ds_read_b128 v[204:207], v193 offset:1024
	ds_read_b128 v[208:211], v193 offset:2048
	ds_read_b128 v[212:215], v193 offset:3072
	ds_read_b128 v[216:219], v193 offset:4096
	ds_read_b128 v[220:223], v193 offset:5120
	ds_read_b128 v[224:227], v193 offset:6144
	ds_read_b128 v[234:237], v193 offset:7168
	global_load_lds_dwordx4 v[186:187], off
	v_lshl_add_u64 v[186:187], s[40:41], 0, v[172:173]
	s_add_i32 m0, s9, 0xe000
	s_nop 0
	global_load_lds_dwordx4 v[186:187], off
	s_waitcnt vmcnt(8)
	s_waitcnt lgkmcnt(0)
	s_barrier
	s_setprio 1
	s_waitcnt lgkmcnt(0)
	v_mfma_f32_16x16x32_bf16 v[126:129], v[130:133], v[182:185], v[126:129]
	v_mfma_f32_16x16x32_bf16 v[122:125], v[138:141], v[182:185], v[122:125]
	v_mfma_f32_16x16x32_bf16 v[118:121], v[130:133], v[208:211], v[118:121]
	v_mfma_f32_16x16x32_bf16 v[110:113], v[138:141], v[208:211], v[110:113]
	v_mfma_f32_16x16x32_bf16 v[102:105], v[130:133], v[216:219], v[102:105]
	v_mfma_f32_16x16x32_bf16 v[94:97], v[138:141], v[216:219], v[94:97]
	v_mfma_f32_16x16x32_bf16 v[86:89], v[130:133], v[224:227], v[86:89]
	v_mfma_f32_16x16x32_bf16 v[78:81], v[138:141], v[224:227], v[78:81]
	v_mfma_f32_16x16x32_bf16 v[126:129], v[134:137], v[204:207], v[126:129]
	v_mfma_f32_16x16x32_bf16 v[122:125], v[142:145], v[204:207], v[122:125]
	v_mfma_f32_16x16x32_bf16 v[118:121], v[134:137], v[212:215], v[118:121]
	v_mfma_f32_16x16x32_bf16 v[110:113], v[142:145], v[212:215], v[110:113]
	v_mfma_f32_16x16x32_bf16 v[102:105], v[134:137], v[220:223], v[102:105]
	v_mfma_f32_16x16x32_bf16 v[94:97], v[142:145], v[220:223], v[94:97]
	v_mfma_f32_16x16x32_bf16 v[86:89], v[134:137], v[234:237], v[86:89]
	v_mfma_f32_16x16x32_bf16 v[78:81], v[142:145], v[234:237], v[78:81]
	v_mfma_f32_16x16x32_bf16 v[114:117], v[146:149], v[182:185], v[114:117]
	v_mfma_f32_16x16x32_bf16 v[106:109], v[174:177], v[182:185], v[106:109]
	v_mfma_f32_16x16x32_bf16 v[98:101], v[146:149], v[208:211], v[98:101]
	v_mfma_f32_16x16x32_bf16 v[90:93], v[174:177], v[208:211], v[90:93]
	v_mfma_f32_16x16x32_bf16 v[82:85], v[146:149], v[216:219], v[82:85]
	v_mfma_f32_16x16x32_bf16 v[74:77], v[174:177], v[216:219], v[74:77]
	v_mfma_f32_16x16x32_bf16 v[70:73], v[146:149], v[224:227], v[70:73]
	v_mfma_f32_16x16x32_bf16 v[66:69], v[174:177], v[224:227], v[66:69]
	v_mfma_f32_16x16x32_bf16 v[114:117], v[150:153], v[204:207], v[114:117]
	v_mfma_f32_16x16x32_bf16 v[106:109], v[178:181], v[204:207], v[106:109]
	v_mfma_f32_16x16x32_bf16 v[98:101], v[150:153], v[212:215], v[98:101]
	v_mfma_f32_16x16x32_bf16 v[90:93], v[178:181], v[212:215], v[90:93]
	s_barrier
	s_setprio 2
	v_mfma_f32_16x16x32_bf16 v[82:85], v[150:153], v[220:223], v[82:85]
	v_mfma_f32_16x16x32_bf16 v[74:77], v[178:181], v[220:223], v[74:77]
	v_mfma_f32_16x16x32_bf16 v[70:73], v[150:153], v[234:237], v[70:73]
	v_mfma_f32_16x16x32_bf16 v[66:69], v[178:181], v[234:237], v[66:69]
	s_setprio 0
	s_add_i32 s46, s52, s8
	v_lshl_add_u64 v[186:187], s[42:43], 0, v[158:159]
	s_mov_b32 m0, s46
	ds_read_b128 v[182:185], v193 offset:16384
	ds_read_b128 v[204:207], v193 offset:17408
	ds_read_b128 v[208:211], v193 offset:18432
	ds_read_b128 v[212:215], v193 offset:19456
	ds_read_b128 v[216:219], v193 offset:20480
	ds_read_b128 v[220:223], v193 offset:21504
	ds_read_b128 v[224:227], v193 offset:22528
	ds_read_b128 v[234:237], v193 offset:23552
	global_load_lds_dwordx4 v[186:187], off
	s_add_i32 m0, s46, 0x2000
	s_add_u32 s46, s42, 0x100000
	v_lshl_add_u64 v[194:195], s[42:43], 0, v[162:163]
	s_addc_u32 s47, s43, 0
	s_add_i32 s56, s53, s8
	global_load_lds_dwordx4 v[194:195], off
	v_lshl_add_u64 v[200:201], s[46:47], 0, v[158:159]
	s_mov_b32 m0, s56
	v_lshl_add_u64 v[238:239], s[44:45], 0, v[160:161]
	global_load_lds_dwordx4 v[200:201], off
	v_lshl_add_u64 v[200:201], s[46:47], 0, v[162:163]
	s_add_i32 m0, s56, 0x2000
	s_nop 0
	global_load_lds_dwordx4 v[200:201], off
	v_lshl_add_u64 v[200:201], s[44:45], 0, v[156:157]
	s_mov_b32 m0, s9
	s_nop 0
	global_load_lds_dwordx4 v[200:201], off
	s_mov_b32 m0, s13
	s_nop 0
	global_load_lds_dwordx4 v[238:239], off
	s_waitcnt vmcnt(8)
	s_waitcnt lgkmcnt(0)
	s_barrier
	s_setprio 1
	s_waitcnt lgkmcnt(0)
	v_mfma_f32_16x16x32_bf16 v[62:65], v[130:133], v[182:185], v[62:65]
	v_mfma_f32_16x16x32_bf16 v[58:61], v[138:141], v[182:185], v[58:61]
	v_mfma_f32_16x16x32_bf16 v[54:57], v[130:133], v[208:211], v[54:57]
	v_mfma_f32_16x16x32_bf16 v[46:49], v[138:141], v[208:211], v[46:49]
	v_mfma_f32_16x16x32_bf16 v[38:41], v[130:133], v[216:219], v[38:41]
	v_mfma_f32_16x16x32_bf16 v[30:33], v[138:141], v[216:219], v[30:33]
	v_mfma_f32_16x16x32_bf16 v[22:25], v[130:133], v[224:227], v[22:25]
	v_mfma_f32_16x16x32_bf16 v[14:17], v[138:141], v[224:227], v[14:17]
	v_mfma_f32_16x16x32_bf16 v[62:65], v[134:137], v[204:207], v[62:65]
	v_mfma_f32_16x16x32_bf16 v[58:61], v[142:145], v[204:207], v[58:61]
	v_mfma_f32_16x16x32_bf16 v[54:57], v[134:137], v[212:215], v[54:57]
	v_mfma_f32_16x16x32_bf16 v[46:49], v[142:145], v[212:215], v[46:49]
	v_mfma_f32_16x16x32_bf16 v[38:41], v[134:137], v[220:223], v[38:41]
	v_mfma_f32_16x16x32_bf16 v[30:33], v[142:145], v[220:223], v[30:33]
	v_mfma_f32_16x16x32_bf16 v[22:25], v[134:137], v[234:237], v[22:25]
	v_mfma_f32_16x16x32_bf16 v[14:17], v[142:145], v[234:237], v[14:17]
	v_mfma_f32_16x16x32_bf16 v[50:53], v[146:149], v[182:185], v[50:53]
	v_mfma_f32_16x16x32_bf16 v[42:45], v[174:177], v[182:185], v[42:45]
	v_mfma_f32_16x16x32_bf16 v[34:37], v[146:149], v[208:211], v[34:37]
	v_mfma_f32_16x16x32_bf16 v[26:29], v[174:177], v[208:211], v[26:29]
	v_mfma_f32_16x16x32_bf16 v[18:21], v[146:149], v[216:219], v[18:21]
	v_mfma_f32_16x16x32_bf16 v[10:13], v[174:177], v[216:219], v[10:13]
	v_mfma_f32_16x16x32_bf16 v[6:9], v[146:149], v[224:227], v[6:9]
	v_mfma_f32_16x16x32_bf16 v[2:5], v[174:177], v[224:227], v[2:5]
	v_mfma_f32_16x16x32_bf16 v[50:53], v[150:153], v[204:207], v[50:53]
	v_mfma_f32_16x16x32_bf16 v[42:45], v[178:181], v[204:207], v[42:45]
	v_mfma_f32_16x16x32_bf16 v[34:37], v[150:153], v[212:215], v[34:37]
	v_mfma_f32_16x16x32_bf16 v[26:29], v[178:181], v[212:215], v[26:29]
	s_barrier
	s_setprio 2
	v_mfma_f32_16x16x32_bf16 v[18:21], v[150:153], v[220:223], v[18:21]
	v_mfma_f32_16x16x32_bf16 v[10:13], v[178:181], v[220:223], v[10:13]
	v_mfma_f32_16x16x32_bf16 v[6:9], v[150:153], v[234:237], v[6:9]
	v_mfma_f32_16x16x32_bf16 v[2:5], v[178:181], v[234:237], v[2:5]
	s_setprio 0
	s_add_i32 s46, 0, 0x18000
	s_add_i32 s47, 0, 0x1c000
	v_add_u32_e32 v142, s46, v188
	v_add_u32_e32 v164, s47, v188
	ds_read_b128 v[130:133], v142
	ds_read_b128 v[134:137], v142 offset:1024
	ds_read_b128 v[138:141], v142 offset:2048
	ds_read_b128 v[142:145], v142 offset:3072
	ds_read_b128 v[146:149], v164
	ds_read_b128 v[150:153], v164 offset:1024
	ds_read_b128 v[174:177], v164 offset:2048
	ds_read_b128 v[178:181], v164 offset:3072
	s_add_u32 s44, s44, 0x100000
	s_addc_u32 s45, s45, 0
	s_mov_b32 m0, s33
	v_lshl_add_u64 v[240:241], s[44:45], 0, v[156:157]
	ds_read_b128 v[182:185], v193 offset:32768
	ds_read_b128 v[204:207], v193 offset:33792
	ds_read_b128 v[208:211], v193 offset:34816
	ds_read_b128 v[212:215], v193 offset:35840
	ds_read_b128 v[216:219], v193 offset:36864
	ds_read_b128 v[220:223], v193 offset:37888
	ds_read_b128 v[224:227], v193 offset:38912
	ds_read_b128 v[234:237], v193 offset:39936
	global_load_lds_dwordx4 v[240:241], off
	v_lshl_add_u64 v[240:241], s[44:45], 0, v[160:161]
	s_mov_b32 m0, s39
	s_nop 0
	global_load_lds_dwordx4 v[240:241], off
	s_waitcnt vmcnt(8)
	s_waitcnt lgkmcnt(0)
	s_barrier
	s_setprio 1
	s_waitcnt lgkmcnt(0)
	v_mfma_f32_16x16x32_bf16 v[126:129], v[130:133], v[182:185], v[126:129]
	v_mfma_f32_16x16x32_bf16 v[122:125], v[138:141], v[182:185], v[122:125]
	v_mfma_f32_16x16x32_bf16 v[118:121], v[130:133], v[208:211], v[118:121]
	v_mfma_f32_16x16x32_bf16 v[110:113], v[138:141], v[208:211], v[110:113]
	v_mfma_f32_16x16x32_bf16 v[102:105], v[130:133], v[216:219], v[102:105]
	v_mfma_f32_16x16x32_bf16 v[94:97], v[138:141], v[216:219], v[94:97]
	v_mfma_f32_16x16x32_bf16 v[86:89], v[130:133], v[224:227], v[86:89]
	v_mfma_f32_16x16x32_bf16 v[78:81], v[138:141], v[224:227], v[78:81]
	v_mfma_f32_16x16x32_bf16 v[126:129], v[134:137], v[204:207], v[126:129]
	v_mfma_f32_16x16x32_bf16 v[122:125], v[142:145], v[204:207], v[122:125]
	v_mfma_f32_16x16x32_bf16 v[118:121], v[134:137], v[212:215], v[118:121]
	v_mfma_f32_16x16x32_bf16 v[110:113], v[142:145], v[212:215], v[110:113]
	v_mfma_f32_16x16x32_bf16 v[102:105], v[134:137], v[220:223], v[102:105]
	v_mfma_f32_16x16x32_bf16 v[94:97], v[142:145], v[220:223], v[94:97]
	v_mfma_f32_16x16x32_bf16 v[86:89], v[134:137], v[234:237], v[86:89]
	v_mfma_f32_16x16x32_bf16 v[78:81], v[142:145], v[234:237], v[78:81]
	v_mfma_f32_16x16x32_bf16 v[114:117], v[146:149], v[182:185], v[114:117]
	v_mfma_f32_16x16x32_bf16 v[106:109], v[174:177], v[182:185], v[106:109]
	v_mfma_f32_16x16x32_bf16 v[98:101], v[146:149], v[208:211], v[98:101]
	v_mfma_f32_16x16x32_bf16 v[90:93], v[174:177], v[208:211], v[90:93]
	v_mfma_f32_16x16x32_bf16 v[82:85], v[146:149], v[216:219], v[82:85]
	v_mfma_f32_16x16x32_bf16 v[74:77], v[174:177], v[216:219], v[74:77]
	v_mfma_f32_16x16x32_bf16 v[70:73], v[146:149], v[224:227], v[70:73]
	v_mfma_f32_16x16x32_bf16 v[66:69], v[174:177], v[224:227], v[66:69]
	v_mfma_f32_16x16x32_bf16 v[114:117], v[150:153], v[204:207], v[114:117]
	v_mfma_f32_16x16x32_bf16 v[106:109], v[178:181], v[204:207], v[106:109]
	v_mfma_f32_16x16x32_bf16 v[98:101], v[150:153], v[212:215], v[98:101]
	v_mfma_f32_16x16x32_bf16 v[90:93], v[178:181], v[212:215], v[90:93]
	s_barrier
	s_setprio 2
	v_mfma_f32_16x16x32_bf16 v[82:85], v[150:153], v[220:223], v[82:85]
	v_mfma_f32_16x16x32_bf16 v[74:77], v[178:181], v[220:223], v[74:77]
	v_mfma_f32_16x16x32_bf16 v[70:73], v[150:153], v[234:237], v[70:73]
	v_mfma_f32_16x16x32_bf16 v[66:69], v[178:181], v[234:237], v[66:69]
	s_setprio 0
	s_add_i32 s44, s46, s8
	v_lshl_add_u64 v[186:187], v[186:187], 0, s[20:21]
	s_mov_b32 m0, s44
	ds_read_b128 v[182:185], v193 offset:49152
	ds_read_b128 v[204:207], v193 offset:50176
	ds_read_b128 v[208:211], v193 offset:51200
	ds_read_b128 v[212:215], v193 offset:52224
	ds_read_b128 v[216:219], v193 offset:53248
	ds_read_b128 v[220:223], v193 offset:54272
	ds_read_b128 v[224:227], v193 offset:55296
	ds_read_b128 v[234:237], v193 offset:56320
	global_load_lds_dwordx4 v[186:187], off
	s_add_i32 m0, s44, 0x2000
	s_add_u32 s42, s42, 0x100080
	v_lshl_add_u64 v[186:187], v[194:195], 0, s[20:21]
	s_addc_u32 s43, s43, 0
	s_add_i32 s44, s47, s8
	global_load_lds_dwordx4 v[186:187], off
	v_lshl_add_u64 v[186:187], s[42:43], 0, v[158:159]
	s_mov_b32 m0, s44
	s_nop 0
	global_load_lds_dwordx4 v[186:187], off
	v_lshl_add_u64 v[186:187], s[42:43], 0, v[162:163]
	s_add_i32 m0, s44, 0x2000
	s_nop 0
	global_load_lds_dwordx4 v[186:187], off
	v_lshl_add_u64 v[186:187], v[200:201], 0, s[20:21]
	s_mov_b32 m0, s50
	s_nop 0
	global_load_lds_dwordx4 v[186:187], off
	v_lshl_add_u64 v[186:187], v[238:239], 0, s[20:21]
	s_mov_b32 m0, s51
	s_nop 0
	global_load_lds_dwordx4 v[186:187], off
	s_waitcnt vmcnt(8)
	s_waitcnt lgkmcnt(0)
	s_barrier
	s_setprio 1
	s_waitcnt lgkmcnt(0)
	v_mfma_f32_16x16x32_bf16 v[62:65], v[130:133], v[182:185], v[62:65]
	v_mfma_f32_16x16x32_bf16 v[58:61], v[138:141], v[182:185], v[58:61]
	v_mfma_f32_16x16x32_bf16 v[54:57], v[130:133], v[208:211], v[54:57]
	v_mfma_f32_16x16x32_bf16 v[46:49], v[138:141], v[208:211], v[46:49]
	v_mfma_f32_16x16x32_bf16 v[38:41], v[130:133], v[216:219], v[38:41]
	v_mfma_f32_16x16x32_bf16 v[30:33], v[138:141], v[216:219], v[30:33]
	v_mfma_f32_16x16x32_bf16 v[22:25], v[130:133], v[224:227], v[22:25]
	v_mfma_f32_16x16x32_bf16 v[14:17], v[138:141], v[224:227], v[14:17]
	v_mfma_f32_16x16x32_bf16 v[62:65], v[134:137], v[204:207], v[62:65]
	v_mfma_f32_16x16x32_bf16 v[58:61], v[142:145], v[204:207], v[58:61]
	v_mfma_f32_16x16x32_bf16 v[54:57], v[134:137], v[212:215], v[54:57]
	v_mfma_f32_16x16x32_bf16 v[46:49], v[142:145], v[212:215], v[46:49]
	v_mfma_f32_16x16x32_bf16 v[38:41], v[134:137], v[220:223], v[38:41]
	v_mfma_f32_16x16x32_bf16 v[30:33], v[142:145], v[220:223], v[30:33]
	v_mfma_f32_16x16x32_bf16 v[22:25], v[134:137], v[234:237], v[22:25]
	v_mfma_f32_16x16x32_bf16 v[14:17], v[142:145], v[234:237], v[14:17]
	v_mfma_f32_16x16x32_bf16 v[50:53], v[146:149], v[182:185], v[50:53]
	v_mfma_f32_16x16x32_bf16 v[42:45], v[174:177], v[182:185], v[42:45]
	v_mfma_f32_16x16x32_bf16 v[34:37], v[146:149], v[208:211], v[34:37]
	v_mfma_f32_16x16x32_bf16 v[26:29], v[174:177], v[208:211], v[26:29]
	v_mfma_f32_16x16x32_bf16 v[18:21], v[146:149], v[216:219], v[18:21]
	v_mfma_f32_16x16x32_bf16 v[10:13], v[174:177], v[216:219], v[10:13]
	v_mfma_f32_16x16x32_bf16 v[6:9], v[146:149], v[224:227], v[6:9]
	v_mfma_f32_16x16x32_bf16 v[2:5], v[174:177], v[224:227], v[2:5]
	v_mfma_f32_16x16x32_bf16 v[50:53], v[150:153], v[204:207], v[50:53]
	v_mfma_f32_16x16x32_bf16 v[42:45], v[178:181], v[204:207], v[42:45]
	v_mfma_f32_16x16x32_bf16 v[34:37], v[150:153], v[212:215], v[34:37]
	v_mfma_f32_16x16x32_bf16 v[26:29], v[178:181], v[212:215], v[26:29]
	s_barrier
	s_setprio 2
	v_mfma_f32_16x16x32_bf16 v[18:21], v[150:153], v[220:223], v[18:21]
	v_mfma_f32_16x16x32_bf16 v[10:13], v[178:181], v[220:223], v[10:13]
	v_mfma_f32_16x16x32_bf16 v[6:9], v[150:153], v[234:237], v[6:9]
	v_mfma_f32_16x16x32_bf16 v[2:5], v[178:181], v[234:237], v[2:5]
	s_setprio 0
	s_add_i32 s29, s29, 2
	s_add_u32 s40, s40, 0x100
	s_addc_u32 s41, s41, 0
	s_add_u32 s15, s15, 0x100
	s_addc_u32 s27, s27, 0
	s_cmp_gt_u32 s29, 61
	s_cbranch_scc0 .LBB0_412
	s_and_b64 vcc, exec, s[22:23]
	s_cbranch_vccz .LBB0_415
	s_barrier

.LBB0_514:
	ds_read_b128 v[156:159], v146
	ds_read_b128 v[160:163], v146 offset:1024
	ds_read_b128 v[164:167], v146 offset:2048
	ds_read_b128 v[168:171], v146 offset:3072
	ds_read_b128 v[172:175], v147
	s_waitcnt lgkmcnt(0)
	ds_read_b128 v[176:179], v147 offset:1024
	ds_read_b128 v[180:183], v147 offset:2048
	ds_read_b128 v[184:187], v147 offset:3072
	s_add_u32 s28, s26, 0xfff00080
	s_addc_u32 s29, s27, -1
	s_cmp_eq_u32 s50, 4
	s_cselect_b32 s31, s19, s29
	s_cselect_b32 s30, s18, s28
	s_cselect_b32 s29, s21, s49
	s_cselect_b32 s28, s20, s23
	s_mov_b32 m0, s36
	v_lshl_add_u64 v[142:143], s[26:27], 0, v[138:139]
	ds_read_b128 v[190:193], v148
	ds_read_b128 v[204:207], v148 offset:1024
	ds_read_b128 v[208:211], v148 offset:2048
	ds_read_b128 v[212:215], v148 offset:3072
	ds_read_b128 v[216:219], v148 offset:4096
	ds_read_b128 v[220:223], v148 offset:5120
	ds_read_b128 v[224:227], v148 offset:6144
	ds_read_b128 v[234:237], v148 offset:7168
	global_load_lds_dwordx4 v[142:143], off
	v_lshl_add_u64 v[142:143], s[26:27], 0, v[140:141]
	s_mov_b32 m0, s37
	s_nop 0
	global_load_lds_dwordx4 v[142:143], off
	s_waitcnt vmcnt(8)
	s_waitcnt lgkmcnt(0)
	s_barrier
	s_setprio 1
	s_waitcnt lgkmcnt(0)
	v_mfma_f32_16x16x32_bf16 v[126:129], v[156:159], v[190:193], v[126:129]
	v_mfma_f32_16x16x32_bf16 v[122:125], v[164:167], v[190:193], v[122:125]
	v_mfma_f32_16x16x32_bf16 v[118:121], v[156:159], v[208:211], v[118:121]
	v_mfma_f32_16x16x32_bf16 v[110:113], v[164:167], v[208:211], v[110:113]
	v_mfma_f32_16x16x32_bf16 v[102:105], v[156:159], v[216:219], v[102:105]
	v_mfma_f32_16x16x32_bf16 v[94:97], v[164:167], v[216:219], v[94:97]
	v_mfma_f32_16x16x32_bf16 v[82:85], v[156:159], v[224:227], v[82:85]
	v_mfma_f32_16x16x32_bf16 v[74:77], v[164:167], v[224:227], v[74:77]
	v_mfma_f32_16x16x32_bf16 v[126:129], v[160:163], v[204:207], v[126:129]
	v_mfma_f32_16x16x32_bf16 v[122:125], v[168:171], v[204:207], v[122:125]
	v_mfma_f32_16x16x32_bf16 v[118:121], v[160:163], v[212:215], v[118:121]
	v_mfma_f32_16x16x32_bf16 v[110:113], v[168:171], v[212:215], v[110:113]
	v_mfma_f32_16x16x32_bf16 v[102:105], v[160:163], v[220:223], v[102:105]
	v_mfma_f32_16x16x32_bf16 v[94:97], v[168:171], v[220:223], v[94:97]
	v_mfma_f32_16x16x32_bf16 v[82:85], v[160:163], v[234:237], v[82:85]
	v_mfma_f32_16x16x32_bf16 v[74:77], v[168:171], v[234:237], v[74:77]
	v_mfma_f32_16x16x32_bf16 v[114:117], v[172:175], v[190:193], v[114:117]
	v_mfma_f32_16x16x32_bf16 v[106:109], v[180:183], v[190:193], v[106:109]
	v_mfma_f32_16x16x32_bf16 v[98:101], v[172:175], v[208:211], v[98:101]
	v_mfma_f32_16x16x32_bf16 v[90:93], v[180:183], v[208:211], v[90:93]
	v_mfma_f32_16x16x32_bf16 v[86:89], v[172:175], v[216:219], v[86:89]
	v_mfma_f32_16x16x32_bf16 v[78:81], v[180:183], v[216:219], v[78:81]
	v_mfma_f32_16x16x32_bf16 v[70:73], v[172:175], v[224:227], v[70:73]
	v_mfma_f32_16x16x32_bf16 v[66:69], v[180:183], v[224:227], v[66:69]
	v_mfma_f32_16x16x32_bf16 v[114:117], v[176:179], v[204:207], v[114:117]
	v_mfma_f32_16x16x32_bf16 v[106:109], v[184:187], v[204:207], v[106:109]
	v_mfma_f32_16x16x32_bf16 v[98:101], v[176:179], v[212:215], v[98:101]
	v_mfma_f32_16x16x32_bf16 v[90:93], v[184:187], v[212:215], v[90:93]
	s_barrier
	s_setprio 2
	v_mfma_f32_16x16x32_bf16 v[86:89], v[176:179], v[220:223], v[86:89]
	v_mfma_f32_16x16x32_bf16 v[78:81], v[184:187], v[220:223], v[78:81]
	v_mfma_f32_16x16x32_bf16 v[70:73], v[176:179], v[234:237], v[70:73]
	v_mfma_f32_16x16x32_bf16 v[66:69], v[184:187], v[234:237], v[66:69]
	s_setprio 0
	s_mov_b32 m0, s38
	v_lshl_add_u64 v[142:143], s[28:29], 0, v[134:135]
	s_add_u32 s52, s28, 0x20000
	ds_read_b128 v[190:193], v148 offset:16384
	ds_read_b128 v[204:207], v148 offset:17408
	ds_read_b128 v[208:211], v148 offset:18432
	ds_read_b128 v[212:215], v148 offset:19456
	ds_read_b128 v[216:219], v148 offset:20480
	ds_read_b128 v[220:223], v148 offset:21504
	ds_read_b128 v[224:227], v148 offset:22528
	ds_read_b128 v[234:237], v148 offset:23552
	global_load_lds_dwordx4 v[142:143], off
	v_lshl_add_u64 v[152:153], s[28:29], 0, v[130:131]
	s_mov_b32 m0, s39
	s_addc_u32 s53, s29, 0
	global_load_lds_dwordx4 v[152:153], off
	v_lshl_add_u64 v[194:195], s[52:53], 0, v[134:135]
	s_mov_b32 m0, s40
	v_lshl_add_u64 v[200:201], s[30:31], 0, v[132:133]
	global_load_lds_dwordx4 v[194:195], off
	v_lshl_add_u64 v[194:195], s[52:53], 0, v[130:131]
	s_mov_b32 m0, s41
	s_nop 0
	global_load_lds_dwordx4 v[194:195], off
	v_lshl_add_u64 v[194:195], s[30:31], 0, v[136:137]
	s_mov_b32 m0, s9
	s_nop 0
	global_load_lds_dwordx4 v[194:195], off
	s_mov_b32 m0, s13
	s_nop 0
	global_load_lds_dwordx4 v[200:201], off
	s_waitcnt vmcnt(8)
	s_waitcnt lgkmcnt(0)
	s_barrier
	s_setprio 1
	s_waitcnt lgkmcnt(0)
	v_mfma_f32_16x16x32_bf16 v[62:65], v[156:159], v[190:193], v[62:65]
	v_mfma_f32_16x16x32_bf16 v[58:61], v[164:167], v[190:193], v[58:61]
	v_mfma_f32_16x16x32_bf16 v[54:57], v[156:159], v[208:211], v[54:57]
	v_mfma_f32_16x16x32_bf16 v[46:49], v[164:167], v[208:211], v[46:49]
	v_mfma_f32_16x16x32_bf16 v[38:41], v[156:159], v[216:219], v[38:41]
	v_mfma_f32_16x16x32_bf16 v[30:33], v[164:167], v[216:219], v[30:33]
	v_mfma_f32_16x16x32_bf16 v[22:25], v[156:159], v[224:227], v[22:25]
	v_mfma_f32_16x16x32_bf16 v[14:17], v[164:167], v[224:227], v[14:17]
	v_mfma_f32_16x16x32_bf16 v[62:65], v[160:163], v[204:207], v[62:65]
	v_mfma_f32_16x16x32_bf16 v[58:61], v[168:171], v[204:207], v[58:61]
	v_mfma_f32_16x16x32_bf16 v[54:57], v[160:163], v[212:215], v[54:57]
	v_mfma_f32_16x16x32_bf16 v[46:49], v[168:171], v[212:215], v[46:49]
	v_mfma_f32_16x16x32_bf16 v[38:41], v[160:163], v[220:223], v[38:41]
	v_mfma_f32_16x16x32_bf16 v[30:33], v[168:171], v[220:223], v[30:33]
	v_mfma_f32_16x16x32_bf16 v[22:25], v[160:163], v[234:237], v[22:25]
	v_mfma_f32_16x16x32_bf16 v[14:17], v[168:171], v[234:237], v[14:17]
	v_mfma_f32_16x16x32_bf16 v[50:53], v[172:175], v[190:193], v[50:53]
	v_mfma_f32_16x16x32_bf16 v[42:45], v[180:183], v[190:193], v[42:45]
	v_mfma_f32_16x16x32_bf16 v[34:37], v[172:175], v[208:211], v[34:37]
	v_mfma_f32_16x16x32_bf16 v[26:29], v[180:183], v[208:211], v[26:29]
	v_mfma_f32_16x16x32_bf16 v[18:21], v[172:175], v[216:219], v[18:21]
	v_mfma_f32_16x16x32_bf16 v[10:13], v[180:183], v[216:219], v[10:13]
	v_mfma_f32_16x16x32_bf16 v[6:9], v[172:175], v[224:227], v[6:9]
	v_mfma_f32_16x16x32_bf16 v[2:5], v[180:183], v[224:227], v[2:5]
	v_mfma_f32_16x16x32_bf16 v[50:53], v[176:179], v[204:207], v[50:53]
	v_mfma_f32_16x16x32_bf16 v[42:45], v[184:187], v[204:207], v[42:45]
	v_mfma_f32_16x16x32_bf16 v[34:37], v[176:179], v[212:215], v[34:37]
	v_mfma_f32_16x16x32_bf16 v[26:29], v[184:187], v[212:215], v[26:29]
	s_barrier
	s_setprio 2
	v_mfma_f32_16x16x32_bf16 v[18:21], v[176:179], v[220:223], v[18:21]
	v_mfma_f32_16x16x32_bf16 v[10:13], v[184:187], v[220:223], v[10:13]
	v_mfma_f32_16x16x32_bf16 v[6:9], v[176:179], v[234:237], v[6:9]
	v_mfma_f32_16x16x32_bf16 v[2:5], v[184:187], v[234:237], v[2:5]
	s_setprio 0
	ds_read_b128 v[156:159], v149
	ds_read_b128 v[160:163], v149 offset:1024
	ds_read_b128 v[164:167], v149 offset:2048
	ds_read_b128 v[168:171], v149 offset:3072
	ds_read_b128 v[172:175], v150
	ds_read_b128 v[176:179], v150 offset:1024
	ds_read_b128 v[180:183], v150 offset:2048
	ds_read_b128 v[184:187], v150 offset:3072
	s_add_u32 s30, s30, 0x100000
	s_addc_u32 s31, s31, 0
	s_mov_b32 m0, s14
	v_lshl_add_u64 v[238:239], s[30:31], 0, v[136:137]
	ds_read_b128 v[190:193], v148 offset:32768
	ds_read_b128 v[204:207], v148 offset:33792
	ds_read_b128 v[208:211], v148 offset:34816
	ds_read_b128 v[212:215], v148 offset:35840
	ds_read_b128 v[216:219], v148 offset:36864
	ds_read_b128 v[220:223], v148 offset:37888
	ds_read_b128 v[224:227], v148 offset:38912
	ds_read_b128 v[234:237], v148 offset:39936
	global_load_lds_dwordx4 v[238:239], off
	v_lshl_add_u64 v[238:239], s[30:31], 0, v[132:133]
	s_mov_b32 m0, s15
	s_nop 0
	global_load_lds_dwordx4 v[238:239], off
	s_waitcnt vmcnt(8)
	s_waitcnt lgkmcnt(0)
	s_barrier
	s_setprio 1
	s_waitcnt lgkmcnt(0)
	v_mfma_f32_16x16x32_bf16 v[126:129], v[156:159], v[190:193], v[126:129]
	v_mfma_f32_16x16x32_bf16 v[122:125], v[164:167], v[190:193], v[122:125]
	v_mfma_f32_16x16x32_bf16 v[118:121], v[156:159], v[208:211], v[118:121]
	v_mfma_f32_16x16x32_bf16 v[110:113], v[164:167], v[208:211], v[110:113]
	v_mfma_f32_16x16x32_bf16 v[102:105], v[156:159], v[216:219], v[102:105]
	v_mfma_f32_16x16x32_bf16 v[94:97], v[164:167], v[216:219], v[94:97]
	v_mfma_f32_16x16x32_bf16 v[82:85], v[156:159], v[224:227], v[82:85]
	v_mfma_f32_16x16x32_bf16 v[74:77], v[164:167], v[224:227], v[74:77]
	v_mfma_f32_16x16x32_bf16 v[126:129], v[160:163], v[204:207], v[126:129]
	v_mfma_f32_16x16x32_bf16 v[122:125], v[168:171], v[204:207], v[122:125]
	v_mfma_f32_16x16x32_bf16 v[118:121], v[160:163], v[212:215], v[118:121]
	v_mfma_f32_16x16x32_bf16 v[110:113], v[168:171], v[212:215], v[110:113]
	v_mfma_f32_16x16x32_bf16 v[102:105], v[160:163], v[220:223], v[102:105]
	v_mfma_f32_16x16x32_bf16 v[94:97], v[168:171], v[220:223], v[94:97]
	v_mfma_f32_16x16x32_bf16 v[82:85], v[160:163], v[234:237], v[82:85]
	v_mfma_f32_16x16x32_bf16 v[74:77], v[168:171], v[234:237], v[74:77]
	v_mfma_f32_16x16x32_bf16 v[114:117], v[172:175], v[190:193], v[114:117]
	v_mfma_f32_16x16x32_bf16 v[106:109], v[180:183], v[190:193], v[106:109]
	v_mfma_f32_16x16x32_bf16 v[98:101], v[172:175], v[208:211], v[98:101]
	v_mfma_f32_16x16x32_bf16 v[90:93], v[180:183], v[208:211], v[90:93]
	v_mfma_f32_16x16x32_bf16 v[86:89], v[172:175], v[216:219], v[86:89]
	v_mfma_f32_16x16x32_bf16 v[78:81], v[180:183], v[216:219], v[78:81]
	v_mfma_f32_16x16x32_bf16 v[70:73], v[172:175], v[224:227], v[70:73]
	v_mfma_f32_16x16x32_bf16 v[66:69], v[180:183], v[224:227], v[66:69]
	v_mfma_f32_16x16x32_bf16 v[114:117], v[176:179], v[204:207], v[114:117]
	v_mfma_f32_16x16x32_bf16 v[106:109], v[184:187], v[204:207], v[106:109]
	v_mfma_f32_16x16x32_bf16 v[98:101], v[176:179], v[212:215], v[98:101]
	v_mfma_f32_16x16x32_bf16 v[90:93], v[184:187], v[212:215], v[90:93]
	s_barrier
	s_setprio 2
	v_mfma_f32_16x16x32_bf16 v[86:89], v[176:179], v[220:223], v[86:89]
	v_mfma_f32_16x16x32_bf16 v[78:81], v[184:187], v[220:223], v[78:81]
	v_mfma_f32_16x16x32_bf16 v[70:73], v[176:179], v[234:237], v[70:73]
	v_mfma_f32_16x16x32_bf16 v[66:69], v[184:187], v[234:237], v[66:69]
	s_setprio 0
	s_mov_b32 m0, s42
	v_lshl_add_u64 v[142:143], v[142:143], 0, s[4:5]
	s_add_u32 s28, s28, 0x20080
	ds_read_b128 v[190:193], v148 offset:49152
	ds_read_b128 v[204:207], v148 offset:50176
	ds_read_b128 v[208:211], v148 offset:51200
	ds_read_b128 v[212:215], v148 offset:52224
	ds_read_b128 v[216:219], v148 offset:53248
	ds_read_b128 v[220:223], v148 offset:54272
	ds_read_b128 v[224:227], v148 offset:55296
	ds_read_b128 v[234:237], v148 offset:56320
	global_load_lds_dwordx4 v[142:143], off
	v_lshl_add_u64 v[142:143], v[152:153], 0, s[4:5]
	s_mov_b32 m0, s43
	s_addc_u32 s29, s29, 0
	global_load_lds_dwordx4 v[142:143], off
	v_lshl_add_u64 v[142:143], s[28:29], 0, v[134:135]
	s_mov_b32 m0, s44
	s_nop 0
	global_load_lds_dwordx4 v[142:143], off
	v_lshl_add_u64 v[142:143], s[28:29], 0, v[130:131]
	s_mov_b32 m0, s45
	s_nop 0
	global_load_lds_dwordx4 v[142:143], off
	v_lshl_add_u64 v[142:143], v[194:195], 0, s[4:5]
	s_mov_b32 m0, s34
	s_nop 0
	global_load_lds_dwordx4 v[142:143], off
	v_lshl_add_u64 v[142:143], v[200:201], 0, s[4:5]
	s_mov_b32 m0, s35
	s_nop 0
	global_load_lds_dwordx4 v[142:143], off
	s_waitcnt vmcnt(8)
	s_waitcnt lgkmcnt(0)
	s_barrier
	s_setprio 1
	s_waitcnt lgkmcnt(0)
	v_mfma_f32_16x16x32_bf16 v[62:65], v[156:159], v[190:193], v[62:65]
	v_mfma_f32_16x16x32_bf16 v[58:61], v[164:167], v[190:193], v[58:61]
	v_mfma_f32_16x16x32_bf16 v[54:57], v[156:159], v[208:211], v[54:57]
	v_mfma_f32_16x16x32_bf16 v[46:49], v[164:167], v[208:211], v[46:49]
	v_mfma_f32_16x16x32_bf16 v[38:41], v[156:159], v[216:219], v[38:41]
	v_mfma_f32_16x16x32_bf16 v[30:33], v[164:167], v[216:219], v[30:33]
	v_mfma_f32_16x16x32_bf16 v[22:25], v[156:159], v[224:227], v[22:25]
	v_mfma_f32_16x16x32_bf16 v[14:17], v[164:167], v[224:227], v[14:17]
	v_mfma_f32_16x16x32_bf16 v[62:65], v[160:163], v[204:207], v[62:65]
	v_mfma_f32_16x16x32_bf16 v[58:61], v[168:171], v[204:207], v[58:61]
	v_mfma_f32_16x16x32_bf16 v[54:57], v[160:163], v[212:215], v[54:57]
	v_mfma_f32_16x16x32_bf16 v[46:49], v[168:171], v[212:215], v[46:49]
	v_mfma_f32_16x16x32_bf16 v[38:41], v[160:163], v[220:223], v[38:41]
	v_mfma_f32_16x16x32_bf16 v[30:33], v[168:171], v[220:223], v[30:33]
	v_mfma_f32_16x16x32_bf16 v[22:25], v[160:163], v[234:237], v[22:25]
	v_mfma_f32_16x16x32_bf16 v[14:17], v[168:171], v[234:237], v[14:17]
	v_mfma_f32_16x16x32_bf16 v[50:53], v[172:175], v[190:193], v[50:53]
	v_mfma_f32_16x16x32_bf16 v[42:45], v[180:183], v[190:193], v[42:45]
	v_mfma_f32_16x16x32_bf16 v[34:37], v[172:175], v[208:211], v[34:37]
	v_mfma_f32_16x16x32_bf16 v[26:29], v[180:183], v[208:211], v[26:29]
	v_mfma_f32_16x16x32_bf16 v[18:21], v[172:175], v[216:219], v[18:21]
	v_mfma_f32_16x16x32_bf16 v[10:13], v[180:183], v[216:219], v[10:13]
	v_mfma_f32_16x16x32_bf16 v[6:9], v[172:175], v[224:227], v[6:9]
	v_mfma_f32_16x16x32_bf16 v[2:5], v[180:183], v[224:227], v[2:5]
	v_mfma_f32_16x16x32_bf16 v[50:53], v[176:179], v[204:207], v[50:53]
	v_mfma_f32_16x16x32_bf16 v[42:45], v[184:187], v[204:207], v[42:45]
	v_mfma_f32_16x16x32_bf16 v[34:37], v[176:179], v[212:215], v[34:37]
	v_mfma_f32_16x16x32_bf16 v[26:29], v[184:187], v[212:215], v[26:29]
	s_barrier
	s_setprio 2
	v_mfma_f32_16x16x32_bf16 v[18:21], v[176:179], v[220:223], v[18:21]
	v_mfma_f32_16x16x32_bf16 v[10:13], v[184:187], v[220:223], v[10:13]
	v_mfma_f32_16x16x32_bf16 v[6:9], v[176:179], v[234:237], v[6:9]
	v_mfma_f32_16x16x32_bf16 v[2:5], v[184:187], v[234:237], v[2:5]
	s_setprio 0
	s_add_i32 s50, s50, 2
	s_add_u32 s26, s26, 0x100
	s_addc_u32 s27, s27, 0
	s_add_u32 s23, s23, 0x100
	s_addc_u32 s49, s49, 0
	s_cmp_gt_u32 s50, 5
	s_cbranch_scc0 .LBB0_514
	s_and_b64 vcc, exec, s[6:7]
	s_cbranch_vccz .LBB0_517
	s_barrier

.LBB0_734:
	ds_read_b128 v[158:161], v227
	ds_read_b128 v[154:157], v227 offset:1024
	ds_read_b128 v[150:153], v227 offset:2048
	ds_read_b128 v[146:149], v227 offset:3072
	ds_read_b128 v[62:65], v233
	ds_read_b128 v[58:61], v233 offset:1024
	ds_read_b128 v[54:57], v233 offset:2048
	ds_read_b128 v[50:53], v233 offset:3072
	s_add_u32 s14, s30, s34
	s_addc_u32 s15, s31, s35
	s_add_u32 s14, s14, 0x100
	s_addc_u32 s15, s15, 0
	s_add_u32 s25, s77, s34
	s_addc_u32 s29, s78, s35
	s_cmpk_eq_i32 s34, 0xf00
	s_cselect_b32 s41, s31, s15
	s_cselect_b32 s40, s30, s14
	s_cselect_b32 s39, s1, s29
	s_cselect_b32 s38, s0, s25
	s_add_i32 s66, s23, 0xc000
	v_lshl_add_u64 v[240:241], v[162:163], 0, s[34:35]
	s_mov_b32 m0, s66
	s_add_i32 s67, s23, 0xe000
	ds_read_b128 v[166:169], v226
	ds_read_b128 v[170:173], v226 offset:1024
	ds_read_b128 v[174:177], v226 offset:2048
	ds_read_b128 v[178:181], v226 offset:3072
	ds_read_b128 v[182:185], v226 offset:4096
	ds_read_b128 v[186:189], v226 offset:5120
	ds_read_b128 v[190:193], v226 offset:6144
	ds_read_b128 v[236:239], v226 offset:7168
	global_load_lds_dwordx4 v[240:241], off
	v_lshl_add_u64 v[240:241], v[164:165], 0, s[34:35]
	s_mov_b32 m0, s67
	s_nop 0
	global_load_lds_dwordx4 v[240:241], off
	s_waitcnt vmcnt(8)
	s_waitcnt lgkmcnt(0)
	s_barrier
	s_setprio 1
	s_waitcnt lgkmcnt(0)
	v_mfma_i32_16x16x64_i8 v[142:145], v[158:161], v[166:169], v[142:145]
	v_mfma_i32_16x16x64_i8 v[142:145], v[154:157], v[170:173], v[142:145]
	v_mfma_i32_16x16x64_i8 v[138:141], v[150:153], v[166:169], v[138:141]
	v_mfma_i32_16x16x64_i8 v[138:141], v[146:149], v[170:173], v[138:141]
	v_mfma_i32_16x16x64_i8 v[126:129], v[158:161], v[174:177], v[126:129]
	v_mfma_i32_16x16x64_i8 v[126:129], v[154:157], v[178:181], v[126:129]
	v_mfma_i32_16x16x64_i8 v[122:125], v[150:153], v[174:177], v[122:125]
	v_mfma_i32_16x16x64_i8 v[122:125], v[146:149], v[178:181], v[122:125]
	v_mfma_i32_16x16x64_i8 v[110:113], v[158:161], v[182:185], v[110:113]
	v_mfma_i32_16x16x64_i8 v[110:113], v[154:157], v[186:189], v[110:113]
	v_mfma_i32_16x16x64_i8 v[106:109], v[150:153], v[182:185], v[106:109]
	v_mfma_i32_16x16x64_i8 v[106:109], v[146:149], v[186:189], v[106:109]
	v_mfma_i32_16x16x64_i8 v[94:97], v[158:161], v[190:193], v[94:97]
	v_mfma_i32_16x16x64_i8 v[94:97], v[154:157], v[236:239], v[94:97]
	v_mfma_i32_16x16x64_i8 v[90:93], v[150:153], v[190:193], v[90:93]
	v_mfma_i32_16x16x64_i8 v[90:93], v[146:149], v[236:239], v[90:93]
	v_mfma_i32_16x16x64_i8 v[134:137], v[62:65], v[166:169], v[134:137]
	v_mfma_i32_16x16x64_i8 v[134:137], v[58:61], v[170:173], v[134:137]
	v_mfma_i32_16x16x64_i8 v[130:133], v[54:57], v[166:169], v[130:133]
	v_mfma_i32_16x16x64_i8 v[130:133], v[50:53], v[170:173], v[130:133]
	v_mfma_i32_16x16x64_i8 v[118:121], v[62:65], v[174:177], v[118:121]
	v_mfma_i32_16x16x64_i8 v[118:121], v[58:61], v[178:181], v[118:121]
	v_mfma_i32_16x16x64_i8 v[114:117], v[54:57], v[174:177], v[114:117]
	v_mfma_i32_16x16x64_i8 v[114:117], v[50:53], v[178:181], v[114:117]
	v_mfma_i32_16x16x64_i8 v[102:105], v[62:65], v[182:185], v[102:105]
	v_mfma_i32_16x16x64_i8 v[102:105], v[58:61], v[186:189], v[102:105]
	v_mfma_i32_16x16x64_i8 v[98:101], v[54:57], v[182:185], v[98:101]
	v_mfma_i32_16x16x64_i8 v[98:101], v[50:53], v[186:189], v[98:101]
	s_barrier
	s_setprio 2
	v_mfma_i32_16x16x64_i8 v[86:89], v[62:65], v[190:193], v[86:89]
	v_mfma_i32_16x16x64_i8 v[86:89], v[58:61], v[236:239], v[86:89]
	v_mfma_i32_16x16x64_i8 v[82:85], v[54:57], v[190:193], v[82:85]
	v_mfma_i32_16x16x64_i8 v[82:85], v[50:53], v[236:239], v[82:85]
	s_setprio 0
	s_add_i32 s68, s60, s21
	s_add_i32 s69, s68, 0x2000
	v_lshl_add_u64 v[166:167], s[38:39], 0, v[202:203]
	s_mov_b32 m0, s68
	s_add_u32 s14, s38, 0x80000
	ds_read_b128 v[174:177], v226 offset:16384
	ds_read_b128 v[178:181], v226 offset:17408
	ds_read_b128 v[182:185], v226 offset:18432
	ds_read_b128 v[186:189], v226 offset:19456
	ds_read_b128 v[190:193], v226 offset:20480
	ds_read_b128 v[236:239], v226 offset:21504
	ds_read_b128 v[240:243], v226 offset:22528
	ds_read_b128 v[244:247], v226 offset:23552
	global_load_lds_dwordx4 v[166:167], off
	v_lshl_add_u64 v[168:169], s[38:39], 0, v[206:207]
	s_mov_b32 m0, s69
	s_addc_u32 s15, s39, 0
	s_add_i32 s70, s61, s21
	global_load_lds_dwordx4 v[168:169], off
	v_lshl_add_u64 v[170:171], s[14:15], 0, v[202:203]
	s_mov_b32 m0, s70
	s_add_i32 s71, s70, 0x2000
	global_load_lds_dwordx4 v[170:171], off
	v_lshl_add_u64 v[170:171], s[14:15], 0, v[206:207]
	s_mov_b32 m0, s71
	v_lshl_add_u64 v[172:173], s[40:41], 0, v[204:205]
	global_load_lds_dwordx4 v[170:171], off
	v_lshl_add_u64 v[170:171], s[40:41], 0, v[194:195]
	s_mov_b32 m0, s23
	s_nop 0
	global_load_lds_dwordx4 v[170:171], off
	s_mov_b32 m0, s42
	s_nop 0
	global_load_lds_dwordx4 v[172:173], off
	s_waitcnt vmcnt(8)
	s_waitcnt lgkmcnt(0)
	s_barrier
	s_setprio 1
	s_waitcnt lgkmcnt(0)
	v_mfma_i32_16x16x64_i8 v[78:81], v[158:161], v[174:177], v[78:81]
	v_mfma_i32_16x16x64_i8 v[78:81], v[154:157], v[178:181], v[78:81]
	v_mfma_i32_16x16x64_i8 v[74:77], v[150:153], v[174:177], v[74:77]
	v_mfma_i32_16x16x64_i8 v[74:77], v[146:149], v[178:181], v[74:77]
	v_mfma_i32_16x16x64_i8 v[46:49], v[158:161], v[182:185], v[46:49]
	v_mfma_i32_16x16x64_i8 v[46:49], v[154:157], v[186:189], v[46:49]
	v_mfma_i32_16x16x64_i8 v[42:45], v[150:153], v[182:185], v[42:45]
	v_mfma_i32_16x16x64_i8 v[42:45], v[146:149], v[186:189], v[42:45]
	v_mfma_i32_16x16x64_i8 v[30:33], v[158:161], v[190:193], v[30:33]
	v_mfma_i32_16x16x64_i8 v[30:33], v[154:157], v[236:239], v[30:33]
	v_mfma_i32_16x16x64_i8 v[26:29], v[150:153], v[190:193], v[26:29]
	v_mfma_i32_16x16x64_i8 v[26:29], v[146:149], v[236:239], v[26:29]
	v_mfma_i32_16x16x64_i8 v[14:17], v[158:161], v[240:243], v[14:17]
	v_mfma_i32_16x16x64_i8 v[14:17], v[154:157], v[244:247], v[14:17]
	v_mfma_i32_16x16x64_i8 v[10:13], v[150:153], v[240:243], v[10:13]
	v_mfma_i32_16x16x64_i8 v[10:13], v[146:149], v[244:247], v[10:13]
	v_mfma_i32_16x16x64_i8 v[70:73], v[62:65], v[174:177], v[70:73]
	v_mfma_i32_16x16x64_i8 v[70:73], v[58:61], v[178:181], v[70:73]
	v_mfma_i32_16x16x64_i8 v[66:69], v[54:57], v[174:177], v[66:69]
	v_mfma_i32_16x16x64_i8 v[66:69], v[50:53], v[178:181], v[66:69]
	v_mfma_i32_16x16x64_i8 v[38:41], v[62:65], v[182:185], v[38:41]
	v_mfma_i32_16x16x64_i8 v[38:41], v[58:61], v[186:189], v[38:41]
	v_mfma_i32_16x16x64_i8 v[34:37], v[54:57], v[182:185], v[34:37]
	v_mfma_i32_16x16x64_i8 v[34:37], v[50:53], v[186:189], v[34:37]
	v_mfma_i32_16x16x64_i8 v[22:25], v[62:65], v[190:193], v[22:25]
	v_mfma_i32_16x16x64_i8 v[22:25], v[58:61], v[236:239], v[22:25]
	v_mfma_i32_16x16x64_i8 v[18:21], v[54:57], v[190:193], v[18:21]
	v_mfma_i32_16x16x64_i8 v[18:21], v[50:53], v[236:239], v[18:21]
	s_barrier
	s_setprio 2
	v_mfma_i32_16x16x64_i8 v[6:9], v[62:65], v[240:243], v[6:9]
	v_mfma_i32_16x16x64_i8 v[6:9], v[58:61], v[244:247], v[6:9]
	v_mfma_i32_16x16x64_i8 v[2:5], v[54:57], v[240:243], v[2:5]
	v_mfma_i32_16x16x64_i8 v[2:5], v[50:53], v[244:247], v[2:5]
	s_setprio 0
	s_add_i32 s72, 0, 0x18000
	v_add_u32_e32 v235, s72, v225
	s_add_i32 s74, 0, 0x1c000
	v_add_u32_e32 v236, s74, v225
	ds_read_b128 v[50:53], v235
	ds_read_b128 v[54:57], v235 offset:1024
	ds_read_b128 v[58:61], v235 offset:2048
	ds_read_b128 v[62:65], v235 offset:3072
	ds_read_b128 v[146:149], v236
	ds_read_b128 v[150:153], v236 offset:1024
	ds_read_b128 v[154:157], v236 offset:2048
	ds_read_b128 v[158:161], v236 offset:3072
	s_add_u32 s14, s40, 0x80000
	s_addc_u32 s15, s41, 0
	s_mov_b32 m0, s43
	v_lshl_add_u64 v[250:251], s[14:15], 0, v[194:195]
	ds_read_b128 v[174:177], v226 offset:32768
	ds_read_b128 v[178:181], v226 offset:33792
	ds_read_b128 v[182:185], v226 offset:34816
	ds_read_b128 v[186:189], v226 offset:35840
	ds_read_b128 v[190:193], v226 offset:36864
	ds_read_b128 v[238:241], v226 offset:37888
	ds_read_b128 v[242:245], v226 offset:38912
	ds_read_b128 v[246:249], v226 offset:39936
	global_load_lds_dwordx4 v[250:251], off
	v_lshl_add_u64 v[250:251], s[14:15], 0, v[204:205]
	s_mov_b32 m0, s44
	s_nop 0
	global_load_lds_dwordx4 v[250:251], off
	s_waitcnt vmcnt(8)
	s_waitcnt lgkmcnt(0)
	s_barrier
	s_setprio 1
	s_waitcnt lgkmcnt(0)
	v_mfma_i32_16x16x64_i8 v[142:145], v[50:53], v[174:177], v[142:145]
	v_mfma_i32_16x16x64_i8 v[142:145], v[54:57], v[178:181], v[142:145]
	v_mfma_i32_16x16x64_i8 v[138:141], v[58:61], v[174:177], v[138:141]
	v_mfma_i32_16x16x64_i8 v[138:141], v[62:65], v[178:181], v[138:141]
	v_mfma_i32_16x16x64_i8 v[126:129], v[50:53], v[182:185], v[126:129]
	v_mfma_i32_16x16x64_i8 v[126:129], v[54:57], v[186:189], v[126:129]
	v_mfma_i32_16x16x64_i8 v[122:125], v[58:61], v[182:185], v[122:125]
	v_mfma_i32_16x16x64_i8 v[122:125], v[62:65], v[186:189], v[122:125]
	v_mfma_i32_16x16x64_i8 v[110:113], v[50:53], v[190:193], v[110:113]
	v_mfma_i32_16x16x64_i8 v[110:113], v[54:57], v[238:241], v[110:113]
	v_mfma_i32_16x16x64_i8 v[106:109], v[58:61], v[190:193], v[106:109]
	v_mfma_i32_16x16x64_i8 v[106:109], v[62:65], v[238:241], v[106:109]
	v_mfma_i32_16x16x64_i8 v[94:97], v[50:53], v[242:245], v[94:97]
	v_mfma_i32_16x16x64_i8 v[94:97], v[54:57], v[246:249], v[94:97]
	v_mfma_i32_16x16x64_i8 v[90:93], v[58:61], v[242:245], v[90:93]
	v_mfma_i32_16x16x64_i8 v[90:93], v[62:65], v[246:249], v[90:93]
	v_mfma_i32_16x16x64_i8 v[134:137], v[146:149], v[174:177], v[134:137]
	v_mfma_i32_16x16x64_i8 v[134:137], v[150:153], v[178:181], v[134:137]
	v_mfma_i32_16x16x64_i8 v[130:133], v[154:157], v[174:177], v[130:133]
	v_mfma_i32_16x16x64_i8 v[130:133], v[158:161], v[178:181], v[130:133]
	v_mfma_i32_16x16x64_i8 v[118:121], v[146:149], v[182:185], v[118:121]
	v_mfma_i32_16x16x64_i8 v[118:121], v[150:153], v[186:189], v[118:121]
	v_mfma_i32_16x16x64_i8 v[114:117], v[154:157], v[182:185], v[114:117]
	v_mfma_i32_16x16x64_i8 v[114:117], v[158:161], v[186:189], v[114:117]
	v_mfma_i32_16x16x64_i8 v[102:105], v[146:149], v[190:193], v[102:105]
	v_mfma_i32_16x16x64_i8 v[102:105], v[150:153], v[238:241], v[102:105]
	v_mfma_i32_16x16x64_i8 v[98:101], v[154:157], v[190:193], v[98:101]
	v_mfma_i32_16x16x64_i8 v[98:101], v[158:161], v[238:241], v[98:101]
	s_barrier
	s_setprio 2
	v_mfma_i32_16x16x64_i8 v[86:89], v[146:149], v[242:245], v[86:89]
	v_mfma_i32_16x16x64_i8 v[86:89], v[150:153], v[246:249], v[86:89]
	v_mfma_i32_16x16x64_i8 v[82:85], v[154:157], v[242:245], v[82:85]
	v_mfma_i32_16x16x64_i8 v[82:85], v[158:161], v[246:249], v[82:85]
	s_setprio 0
	s_add_i32 s72, s72, s21
	s_add_i32 s73, s72, 0x2000
	v_lshl_add_u64 v[166:167], v[166:167], 0, s[6:7]
	s_mov_b32 m0, s72
	s_add_u32 s14, s38, 0x80080
	ds_read_b128 v[174:177], v226 offset:49152
	ds_read_b128 v[178:181], v226 offset:50176
	ds_read_b128 v[182:185], v226 offset:51200
	ds_read_b128 v[186:189], v226 offset:52224
	ds_read_b128 v[190:193], v226 offset:53248
	ds_read_b128 v[238:241], v226 offset:54272
	ds_read_b128 v[242:245], v226 offset:55296
	ds_read_b128 v[246:249], v226 offset:56320
	global_load_lds_dwordx4 v[166:167], off
	v_lshl_add_u64 v[166:167], v[168:169], 0, s[6:7]
	s_mov_b32 m0, s73
	s_addc_u32 s15, s39, 0
	s_add_i32 s74, s74, s21
	global_load_lds_dwordx4 v[166:167], off
	v_lshl_add_u64 v[166:167], s[14:15], 0, v[202:203]
	s_mov_b32 m0, s74
	s_add_i32 s75, s74, 0x2000
	global_load_lds_dwordx4 v[166:167], off
	v_lshl_add_u64 v[166:167], s[14:15], 0, v[206:207]
	s_mov_b32 m0, s75
	s_nop 0
	global_load_lds_dwordx4 v[166:167], off
	v_lshl_add_u64 v[166:167], v[170:171], 0, s[6:7]
	s_mov_b32 m0, s51
	s_nop 0
	global_load_lds_dwordx4 v[166:167], off
	v_lshl_add_u64 v[166:167], v[172:173], 0, s[6:7]
	s_mov_b32 m0, s53
	s_nop 0
	global_load_lds_dwordx4 v[166:167], off
	s_waitcnt vmcnt(8)
	s_waitcnt lgkmcnt(0)
	s_barrier
	s_setprio 1
	s_waitcnt lgkmcnt(0)
	v_mfma_i32_16x16x64_i8 v[78:81], v[50:53], v[174:177], v[78:81]
	v_mfma_i32_16x16x64_i8 v[78:81], v[54:57], v[178:181], v[78:81]
	v_mfma_i32_16x16x64_i8 v[74:77], v[58:61], v[174:177], v[74:77]
	v_mfma_i32_16x16x64_i8 v[74:77], v[62:65], v[178:181], v[74:77]
	v_mfma_i32_16x16x64_i8 v[46:49], v[50:53], v[182:185], v[46:49]
	v_mfma_i32_16x16x64_i8 v[46:49], v[54:57], v[186:189], v[46:49]
	v_mfma_i32_16x16x64_i8 v[42:45], v[58:61], v[182:185], v[42:45]
	v_mfma_i32_16x16x64_i8 v[42:45], v[62:65], v[186:189], v[42:45]
	v_mfma_i32_16x16x64_i8 v[30:33], v[50:53], v[190:193], v[30:33]
	v_mfma_i32_16x16x64_i8 v[30:33], v[54:57], v[238:241], v[30:33]
	v_mfma_i32_16x16x64_i8 v[26:29], v[58:61], v[190:193], v[26:29]
	v_mfma_i32_16x16x64_i8 v[26:29], v[62:65], v[238:241], v[26:29]
	v_mfma_i32_16x16x64_i8 v[14:17], v[50:53], v[242:245], v[14:17]
	v_mfma_i32_16x16x64_i8 v[14:17], v[54:57], v[246:249], v[14:17]
	v_mfma_i32_16x16x64_i8 v[10:13], v[58:61], v[242:245], v[10:13]
	v_mfma_i32_16x16x64_i8 v[10:13], v[62:65], v[246:249], v[10:13]
	v_mfma_i32_16x16x64_i8 v[70:73], v[146:149], v[174:177], v[70:73]
	v_mfma_i32_16x16x64_i8 v[70:73], v[150:153], v[178:181], v[70:73]
	v_mfma_i32_16x16x64_i8 v[66:69], v[154:157], v[174:177], v[66:69]
	v_mfma_i32_16x16x64_i8 v[66:69], v[158:161], v[178:181], v[66:69]
	v_mfma_i32_16x16x64_i8 v[38:41], v[146:149], v[182:185], v[38:41]
	v_mfma_i32_16x16x64_i8 v[38:41], v[150:153], v[186:189], v[38:41]
	v_mfma_i32_16x16x64_i8 v[34:37], v[154:157], v[182:185], v[34:37]
	v_mfma_i32_16x16x64_i8 v[34:37], v[158:161], v[186:189], v[34:37]
	v_mfma_i32_16x16x64_i8 v[22:25], v[146:149], v[190:193], v[22:25]
	v_mfma_i32_16x16x64_i8 v[22:25], v[150:153], v[238:241], v[22:25]
	v_mfma_i32_16x16x64_i8 v[18:21], v[154:157], v[190:193], v[18:21]
	v_mfma_i32_16x16x64_i8 v[18:21], v[158:161], v[238:241], v[18:21]
	s_barrier
	s_setprio 2
	v_mfma_i32_16x16x64_i8 v[6:9], v[146:149], v[242:245], v[6:9]
	v_mfma_i32_16x16x64_i8 v[6:9], v[150:153], v[246:249], v[6:9]
	v_mfma_i32_16x16x64_i8 v[2:5], v[154:157], v[242:245], v[2:5]
	v_mfma_i32_16x16x64_i8 v[2:5], v[158:161], v[246:249], v[2:5]
	s_setprio 0
	s_add_i32 s3, s3, 2
	s_add_u32 s34, s34, 0x100
	s_addc_u32 s35, s35, 0
	s_cmp_gt_u32 s3, 29
	s_cbranch_scc0 .LBB0_734
	s_nop 15
	s_nop 15
	s_and_b64 vcc, exec, s[8:9]
	s_cbranch_vccz .LBB0_737
	s_barrier

.LBB0_740:
	ds_read_b128 v[158:161], v227
	ds_read_b128 v[154:157], v227 offset:1024
	ds_read_b128 v[150:153], v227 offset:2048
	ds_read_b128 v[146:149], v227 offset:3072
	ds_read_b128 v[62:65], v233
	ds_read_b128 v[58:61], v233 offset:1024
	ds_read_b128 v[54:57], v233 offset:2048
	ds_read_b128 v[50:53], v233 offset:3072
	s_add_u32 s36, s38, 0xfff80080
	s_addc_u32 s37, s39, -1
	s_cmp_eq_u32 s33, 28
	s_cselect_b32 s41, s1, s37
	s_cselect_b32 s40, s0, s36
	s_cselect_b32 s37, s15, s29
	s_cselect_b32 s36, s14, s25
	s_mov_b32 m0, s66
	v_lshl_add_u64 v[238:239], s[38:39], 0, v[208:209]
	ds_read_b128 v[162:165], v226
	ds_read_b128 v[166:169], v226 offset:1024
	ds_read_b128 v[170:173], v226 offset:2048
	ds_read_b128 v[174:177], v226 offset:3072
	ds_read_b128 v[178:181], v226 offset:4096
	ds_read_b128 v[182:185], v226 offset:5120
	ds_read_b128 v[186:189], v226 offset:6144
	ds_read_b128 v[190:193], v226 offset:7168
	global_load_lds_dwordx4 v[238:239], off
	v_lshl_add_u64 v[238:239], s[38:39], 0, v[212:213]
	s_mov_b32 m0, s67
	s_nop 0
	global_load_lds_dwordx4 v[238:239], off
	s_waitcnt vmcnt(8)
	s_waitcnt lgkmcnt(0)
	s_barrier
	s_setprio 1
	s_waitcnt lgkmcnt(0)
	v_mfma_i32_16x16x64_i8 v[142:145], v[158:161], v[162:165], v[142:145]
	v_mfma_i32_16x16x64_i8 v[142:145], v[154:157], v[166:169], v[142:145]
	v_mfma_i32_16x16x64_i8 v[138:141], v[150:153], v[162:165], v[138:141]
	v_mfma_i32_16x16x64_i8 v[138:141], v[146:149], v[166:169], v[138:141]
	v_mfma_i32_16x16x64_i8 v[126:129], v[158:161], v[170:173], v[126:129]
	v_mfma_i32_16x16x64_i8 v[126:129], v[154:157], v[174:177], v[126:129]
	v_mfma_i32_16x16x64_i8 v[122:125], v[150:153], v[170:173], v[122:125]
	v_mfma_i32_16x16x64_i8 v[122:125], v[146:149], v[174:177], v[122:125]
	v_mfma_i32_16x16x64_i8 v[110:113], v[158:161], v[178:181], v[110:113]
	v_mfma_i32_16x16x64_i8 v[110:113], v[154:157], v[182:185], v[110:113]
	v_mfma_i32_16x16x64_i8 v[106:109], v[150:153], v[178:181], v[106:109]
	v_mfma_i32_16x16x64_i8 v[106:109], v[146:149], v[182:185], v[106:109]
	v_mfma_i32_16x16x64_i8 v[94:97], v[158:161], v[186:189], v[94:97]
	v_mfma_i32_16x16x64_i8 v[94:97], v[154:157], v[190:193], v[94:97]
	v_mfma_i32_16x16x64_i8 v[90:93], v[150:153], v[186:189], v[90:93]
	v_mfma_i32_16x16x64_i8 v[90:93], v[146:149], v[190:193], v[90:93]
	v_mfma_i32_16x16x64_i8 v[134:137], v[62:65], v[162:165], v[134:137]
	v_mfma_i32_16x16x64_i8 v[134:137], v[58:61], v[166:169], v[134:137]
	v_mfma_i32_16x16x64_i8 v[130:133], v[54:57], v[162:165], v[130:133]
	v_mfma_i32_16x16x64_i8 v[130:133], v[50:53], v[166:169], v[130:133]
	v_mfma_i32_16x16x64_i8 v[118:121], v[62:65], v[170:173], v[118:121]
	v_mfma_i32_16x16x64_i8 v[118:121], v[58:61], v[174:177], v[118:121]
	v_mfma_i32_16x16x64_i8 v[114:117], v[54:57], v[170:173], v[114:117]
	v_mfma_i32_16x16x64_i8 v[114:117], v[50:53], v[174:177], v[114:117]
	v_mfma_i32_16x16x64_i8 v[102:105], v[62:65], v[178:181], v[102:105]
	v_mfma_i32_16x16x64_i8 v[102:105], v[58:61], v[182:185], v[102:105]
	v_mfma_i32_16x16x64_i8 v[98:101], v[54:57], v[178:181], v[98:101]
	v_mfma_i32_16x16x64_i8 v[98:101], v[50:53], v[182:185], v[98:101]
	s_barrier
	s_setprio 2
	v_mfma_i32_16x16x64_i8 v[86:89], v[62:65], v[186:189], v[86:89]
	v_mfma_i32_16x16x64_i8 v[86:89], v[58:61], v[190:193], v[86:89]
	v_mfma_i32_16x16x64_i8 v[82:85], v[54:57], v[186:189], v[82:85]
	v_mfma_i32_16x16x64_i8 v[82:85], v[50:53], v[190:193], v[82:85]
	s_setprio 0
	s_mov_b32 m0, s68
	v_lshl_add_u64 v[162:163], s[36:37], 0, v[202:203]
	s_add_u32 s80, s36, 0x80000
	ds_read_b128 v[170:173], v226 offset:16384
	ds_read_b128 v[174:177], v226 offset:17408
	ds_read_b128 v[178:181], v226 offset:18432
	ds_read_b128 v[182:185], v226 offset:19456
	ds_read_b128 v[186:189], v226 offset:20480
	ds_read_b128 v[190:193], v226 offset:21504
	ds_read_b128 v[238:241], v226 offset:22528
	ds_read_b128 v[242:245], v226 offset:23552
	global_load_lds_dwordx4 v[162:163], off
	v_lshl_add_u64 v[164:165], s[36:37], 0, v[206:207]
	s_mov_b32 m0, s69
	s_addc_u32 s81, s37, 0
	global_load_lds_dwordx4 v[164:165], off
	v_lshl_add_u64 v[166:167], s[80:81], 0, v[202:203]
	s_mov_b32 m0, s70
	v_lshl_add_u64 v[168:169], s[40:41], 0, v[204:205]
	global_load_lds_dwordx4 v[166:167], off
	v_lshl_add_u64 v[166:167], s[80:81], 0, v[206:207]
	s_mov_b32 m0, s71
	s_nop 0
	global_load_lds_dwordx4 v[166:167], off
	v_lshl_add_u64 v[166:167], s[40:41], 0, v[194:195]
	s_mov_b32 m0, s23
	s_nop 0
	global_load_lds_dwordx4 v[166:167], off
	s_mov_b32 m0, s42
	s_nop 0
	global_load_lds_dwordx4 v[168:169], off
	s_waitcnt vmcnt(8)
	s_waitcnt lgkmcnt(0)
	s_barrier
	s_setprio 1
	s_waitcnt lgkmcnt(0)
	v_mfma_i32_16x16x64_i8 v[78:81], v[158:161], v[170:173], v[78:81]
	v_mfma_i32_16x16x64_i8 v[78:81], v[154:157], v[174:177], v[78:81]
	v_mfma_i32_16x16x64_i8 v[74:77], v[150:153], v[170:173], v[74:77]
	v_mfma_i32_16x16x64_i8 v[74:77], v[146:149], v[174:177], v[74:77]
	v_mfma_i32_16x16x64_i8 v[46:49], v[158:161], v[178:181], v[46:49]
	v_mfma_i32_16x16x64_i8 v[46:49], v[154:157], v[182:185], v[46:49]
	v_mfma_i32_16x16x64_i8 v[42:45], v[150:153], v[178:181], v[42:45]
	v_mfma_i32_16x16x64_i8 v[42:45], v[146:149], v[182:185], v[42:45]
	v_mfma_i32_16x16x64_i8 v[30:33], v[158:161], v[186:189], v[30:33]
	v_mfma_i32_16x16x64_i8 v[30:33], v[154:157], v[190:193], v[30:33]
	v_mfma_i32_16x16x64_i8 v[26:29], v[150:153], v[186:189], v[26:29]
	v_mfma_i32_16x16x64_i8 v[26:29], v[146:149], v[190:193], v[26:29]
	v_mfma_i32_16x16x64_i8 v[14:17], v[158:161], v[238:241], v[14:17]
	v_mfma_i32_16x16x64_i8 v[14:17], v[154:157], v[242:245], v[14:17]
	v_mfma_i32_16x16x64_i8 v[10:13], v[150:153], v[238:241], v[10:13]
	v_mfma_i32_16x16x64_i8 v[10:13], v[146:149], v[242:245], v[10:13]
	v_mfma_i32_16x16x64_i8 v[70:73], v[62:65], v[170:173], v[70:73]
	v_mfma_i32_16x16x64_i8 v[70:73], v[58:61], v[174:177], v[70:73]
	v_mfma_i32_16x16x64_i8 v[66:69], v[54:57], v[170:173], v[66:69]
	v_mfma_i32_16x16x64_i8 v[66:69], v[50:53], v[174:177], v[66:69]
	v_mfma_i32_16x16x64_i8 v[38:41], v[62:65], v[178:181], v[38:41]
	v_mfma_i32_16x16x64_i8 v[38:41], v[58:61], v[182:185], v[38:41]
	v_mfma_i32_16x16x64_i8 v[34:37], v[54:57], v[178:181], v[34:37]
	v_mfma_i32_16x16x64_i8 v[34:37], v[50:53], v[182:185], v[34:37]
	v_mfma_i32_16x16x64_i8 v[22:25], v[62:65], v[186:189], v[22:25]
	v_mfma_i32_16x16x64_i8 v[22:25], v[58:61], v[190:193], v[22:25]
	v_mfma_i32_16x16x64_i8 v[18:21], v[54:57], v[186:189], v[18:21]
	v_mfma_i32_16x16x64_i8 v[18:21], v[50:53], v[190:193], v[18:21]
	s_barrier
	s_setprio 2
	v_mfma_i32_16x16x64_i8 v[6:9], v[62:65], v[238:241], v[6:9]
	v_mfma_i32_16x16x64_i8 v[6:9], v[58:61], v[242:245], v[6:9]
	v_mfma_i32_16x16x64_i8 v[2:5], v[54:57], v[238:241], v[2:5]
	v_mfma_i32_16x16x64_i8 v[2:5], v[50:53], v[242:245], v[2:5]
	s_setprio 0
	ds_read_b128 v[50:53], v235
	ds_read_b128 v[54:57], v235 offset:1024
	ds_read_b128 v[58:61], v235 offset:2048
	ds_read_b128 v[62:65], v235 offset:3072
	ds_read_b128 v[146:149], v236
	ds_read_b128 v[150:153], v236 offset:1024
	ds_read_b128 v[154:157], v236 offset:2048
	ds_read_b128 v[158:161], v236 offset:3072
	s_add_u32 s40, s40, 0x80000
	s_addc_u32 s41, s41, 0
	s_mov_b32 m0, s43
	v_lshl_add_u64 v[246:247], s[40:41], 0, v[194:195]
	ds_read_b128 v[170:173], v226 offset:32768
	ds_read_b128 v[174:177], v226 offset:33792
	ds_read_b128 v[178:181], v226 offset:34816
	ds_read_b128 v[182:185], v226 offset:35840
	ds_read_b128 v[186:189], v226 offset:36864
	ds_read_b128 v[190:193], v226 offset:37888
	ds_read_b128 v[238:241], v226 offset:38912
	ds_read_b128 v[242:245], v226 offset:39936
	global_load_lds_dwordx4 v[246:247], off
	v_lshl_add_u64 v[246:247], s[40:41], 0, v[204:205]
	s_mov_b32 m0, s44
	s_nop 0
	global_load_lds_dwordx4 v[246:247], off
	s_waitcnt vmcnt(8)
	s_waitcnt lgkmcnt(0)
	s_barrier
	s_setprio 1
	s_waitcnt lgkmcnt(0)
	v_mfma_i32_16x16x64_i8 v[142:145], v[50:53], v[170:173], v[142:145]
	v_mfma_i32_16x16x64_i8 v[142:145], v[54:57], v[174:177], v[142:145]
	v_mfma_i32_16x16x64_i8 v[138:141], v[58:61], v[170:173], v[138:141]
	v_mfma_i32_16x16x64_i8 v[138:141], v[62:65], v[174:177], v[138:141]
	v_mfma_i32_16x16x64_i8 v[126:129], v[50:53], v[178:181], v[126:129]
	v_mfma_i32_16x16x64_i8 v[126:129], v[54:57], v[182:185], v[126:129]
	v_mfma_i32_16x16x64_i8 v[122:125], v[58:61], v[178:181], v[122:125]
	v_mfma_i32_16x16x64_i8 v[122:125], v[62:65], v[182:185], v[122:125]
	v_mfma_i32_16x16x64_i8 v[110:113], v[50:53], v[186:189], v[110:113]
	v_mfma_i32_16x16x64_i8 v[110:113], v[54:57], v[190:193], v[110:113]
	v_mfma_i32_16x16x64_i8 v[106:109], v[58:61], v[186:189], v[106:109]
	v_mfma_i32_16x16x64_i8 v[106:109], v[62:65], v[190:193], v[106:109]
	v_mfma_i32_16x16x64_i8 v[94:97], v[50:53], v[238:241], v[94:97]
	v_mfma_i32_16x16x64_i8 v[94:97], v[54:57], v[242:245], v[94:97]
	v_mfma_i32_16x16x64_i8 v[90:93], v[58:61], v[238:241], v[90:93]
	v_mfma_i32_16x16x64_i8 v[90:93], v[62:65], v[242:245], v[90:93]
	v_mfma_i32_16x16x64_i8 v[134:137], v[146:149], v[170:173], v[134:137]
	v_mfma_i32_16x16x64_i8 v[134:137], v[150:153], v[174:177], v[134:137]
	v_mfma_i32_16x16x64_i8 v[130:133], v[154:157], v[170:173], v[130:133]
	v_mfma_i32_16x16x64_i8 v[130:133], v[158:161], v[174:177], v[130:133]
	v_mfma_i32_16x16x64_i8 v[118:121], v[146:149], v[178:181], v[118:121]
	v_mfma_i32_16x16x64_i8 v[118:121], v[150:153], v[182:185], v[118:121]
	v_mfma_i32_16x16x64_i8 v[114:117], v[154:157], v[178:181], v[114:117]
	v_mfma_i32_16x16x64_i8 v[114:117], v[158:161], v[182:185], v[114:117]
	v_mfma_i32_16x16x64_i8 v[102:105], v[146:149], v[186:189], v[102:105]
	v_mfma_i32_16x16x64_i8 v[102:105], v[150:153], v[190:193], v[102:105]
	v_mfma_i32_16x16x64_i8 v[98:101], v[154:157], v[186:189], v[98:101]
	v_mfma_i32_16x16x64_i8 v[98:101], v[158:161], v[190:193], v[98:101]
	s_barrier
	s_setprio 2
	v_mfma_i32_16x16x64_i8 v[86:89], v[146:149], v[238:241], v[86:89]
	v_mfma_i32_16x16x64_i8 v[86:89], v[150:153], v[242:245], v[86:89]
	v_mfma_i32_16x16x64_i8 v[82:85], v[154:157], v[238:241], v[82:85]
	v_mfma_i32_16x16x64_i8 v[82:85], v[158:161], v[242:245], v[82:85]
	s_setprio 0
	s_mov_b32 m0, s72
	v_lshl_add_u64 v[162:163], v[162:163], 0, s[6:7]
	s_add_u32 s36, s36, 0x80080
	ds_read_b128 v[170:173], v226 offset:49152
	ds_read_b128 v[174:177], v226 offset:50176
	ds_read_b128 v[178:181], v226 offset:51200
	ds_read_b128 v[182:185], v226 offset:52224
	ds_read_b128 v[186:189], v226 offset:53248
	ds_read_b128 v[190:193], v226 offset:54272
	ds_read_b128 v[238:241], v226 offset:55296
	ds_read_b128 v[242:245], v226 offset:56320
	global_load_lds_dwordx4 v[162:163], off
	v_lshl_add_u64 v[162:163], v[164:165], 0, s[6:7]
	s_mov_b32 m0, s73
	s_addc_u32 s37, s37, 0
	global_load_lds_dwordx4 v[162:163], off
	v_lshl_add_u64 v[162:163], s[36:37], 0, v[202:203]
	s_mov_b32 m0, s74
	s_nop 0
	global_load_lds_dwordx4 v[162:163], off
	v_lshl_add_u64 v[162:163], s[36:37], 0, v[206:207]
	s_mov_b32 m0, s75
	s_nop 0
	global_load_lds_dwordx4 v[162:163], off
	v_lshl_add_u64 v[162:163], v[166:167], 0, s[6:7]
	s_mov_b32 m0, s51
	s_nop 0
	global_load_lds_dwordx4 v[162:163], off
	v_lshl_add_u64 v[162:163], v[168:169], 0, s[6:7]
	s_mov_b32 m0, s53
	s_nop 0
	global_load_lds_dwordx4 v[162:163], off
	s_waitcnt vmcnt(8)
	s_waitcnt lgkmcnt(0)
	s_barrier
	s_setprio 1
	s_waitcnt lgkmcnt(0)
	v_mfma_i32_16x16x64_i8 v[78:81], v[50:53], v[170:173], v[78:81]
	v_mfma_i32_16x16x64_i8 v[78:81], v[54:57], v[174:177], v[78:81]
	v_mfma_i32_16x16x64_i8 v[74:77], v[58:61], v[170:173], v[74:77]
	v_mfma_i32_16x16x64_i8 v[74:77], v[62:65], v[174:177], v[74:77]
	v_mfma_i32_16x16x64_i8 v[46:49], v[50:53], v[178:181], v[46:49]
	v_mfma_i32_16x16x64_i8 v[46:49], v[54:57], v[182:185], v[46:49]
	v_mfma_i32_16x16x64_i8 v[42:45], v[58:61], v[178:181], v[42:45]
	v_mfma_i32_16x16x64_i8 v[42:45], v[62:65], v[182:185], v[42:45]
	v_mfma_i32_16x16x64_i8 v[30:33], v[50:53], v[186:189], v[30:33]
	v_mfma_i32_16x16x64_i8 v[30:33], v[54:57], v[190:193], v[30:33]
	v_mfma_i32_16x16x64_i8 v[26:29], v[58:61], v[186:189], v[26:29]
	v_mfma_i32_16x16x64_i8 v[26:29], v[62:65], v[190:193], v[26:29]
	v_mfma_i32_16x16x64_i8 v[14:17], v[50:53], v[238:241], v[14:17]
	v_mfma_i32_16x16x64_i8 v[14:17], v[54:57], v[242:245], v[14:17]
	v_mfma_i32_16x16x64_i8 v[10:13], v[58:61], v[238:241], v[10:13]
	v_mfma_i32_16x16x64_i8 v[10:13], v[62:65], v[242:245], v[10:13]
	v_mfma_i32_16x16x64_i8 v[70:73], v[146:149], v[170:173], v[70:73]
	v_mfma_i32_16x16x64_i8 v[70:73], v[150:153], v[174:177], v[70:73]
	v_mfma_i32_16x16x64_i8 v[66:69], v[154:157], v[170:173], v[66:69]
	v_mfma_i32_16x16x64_i8 v[66:69], v[158:161], v[174:177], v[66:69]
	v_mfma_i32_16x16x64_i8 v[38:41], v[146:149], v[178:181], v[38:41]
	v_mfma_i32_16x16x64_i8 v[38:41], v[150:153], v[182:185], v[38:41]
	v_mfma_i32_16x16x64_i8 v[34:37], v[154:157], v[178:181], v[34:37]
	v_mfma_i32_16x16x64_i8 v[34:37], v[158:161], v[182:185], v[34:37]
	v_mfma_i32_16x16x64_i8 v[22:25], v[146:149], v[186:189], v[22:25]
	v_mfma_i32_16x16x64_i8 v[22:25], v[150:153], v[190:193], v[22:25]
	v_mfma_i32_16x16x64_i8 v[18:21], v[154:157], v[186:189], v[18:21]
	v_mfma_i32_16x16x64_i8 v[18:21], v[158:161], v[190:193], v[18:21]
	s_barrier
	s_setprio 2
	v_mfma_i32_16x16x64_i8 v[6:9], v[146:149], v[238:241], v[6:9]
	v_mfma_i32_16x16x64_i8 v[6:9], v[150:153], v[242:245], v[6:9]
	v_mfma_i32_16x16x64_i8 v[2:5], v[154:157], v[238:241], v[2:5]
	v_mfma_i32_16x16x64_i8 v[2:5], v[158:161], v[242:245], v[2:5]
	s_setprio 0
	s_add_i32 s33, s33, 2
	s_add_u32 s38, s38, 0x100
	s_addc_u32 s39, s39, 0
	s_add_u32 s25, s25, 0x100
	s_addc_u32 s29, s29, 0
	s_cmp_gt_u32 s33, 29
	s_cbranch_scc0 .LBB0_740
	s_nop 15
	s_nop 15
	s_and_b64 vcc, exec, s[8:9]
	s_cbranch_vccz .LBB0_743
	s_barrier

.LBB0_746:
	ds_read_b128 v[158:161], v227
	ds_read_b128 v[154:157], v227 offset:1024
	ds_read_b128 v[150:153], v227 offset:2048
	ds_read_b128 v[146:149], v227 offset:3072
	ds_read_b128 v[142:145], v233
	ds_read_b128 v[138:141], v233 offset:1024
	ds_read_b128 v[134:137], v233 offset:2048
	ds_read_b128 v[130:133], v233 offset:3072
	s_add_u32 s38, s29, s36
	s_addc_u32 s39, s33, s37
	s_add_u32 s38, s38, 0x3d000100
	s_addc_u32 s39, s39, 0
	s_add_u32 s81, s25, s36
	s_addc_u32 s82, s79, s37
	s_cmpk_eq_i32 s36, 0x700
	s_cselect_b32 s41, s1, s39
	s_cselect_b32 s40, s0, s38
	s_cselect_b32 s39, s15, s82
	s_cselect_b32 s38, s14, s81
	s_mov_b32 m0, s66
	v_lshl_add_u64 v[242:243], v[162:163], 0, s[36:37]
	ds_read_b128 v[166:169], v226
	ds_read_b128 v[170:173], v226 offset:1024
	ds_read_b128 v[174:177], v226 offset:2048
	ds_read_b128 v[178:181], v226 offset:3072
	ds_read_b128 v[182:185], v226 offset:4096
	ds_read_b128 v[186:189], v226 offset:5120
	ds_read_b128 v[190:193], v226 offset:6144
	ds_read_b128 v[238:241], v226 offset:7168
	global_load_lds_dwordx4 v[242:243], off
	v_lshl_add_u64 v[242:243], v[164:165], 0, s[36:37]
	s_mov_b32 m0, s67
	s_nop 0
	global_load_lds_dwordx4 v[242:243], off
	s_waitcnt vmcnt(8)
	s_waitcnt lgkmcnt(0)
	s_barrier
	s_setprio 1
	s_waitcnt lgkmcnt(0)
	v_mfma_i32_16x16x64_i8 v[30:33], v[158:161], v[166:169], v[30:33]
	v_mfma_i32_16x16x64_i8 v[30:33], v[154:157], v[170:173], v[30:33]
	v_mfma_i32_16x16x64_i8 v[26:29], v[150:153], v[166:169], v[26:29]
	v_mfma_i32_16x16x64_i8 v[26:29], v[146:149], v[170:173], v[26:29]
	v_mfma_i32_16x16x64_i8 v[46:49], v[158:161], v[174:177], v[46:49]
	v_mfma_i32_16x16x64_i8 v[46:49], v[154:157], v[178:181], v[46:49]
	v_mfma_i32_16x16x64_i8 v[42:45], v[150:153], v[174:177], v[42:45]
	v_mfma_i32_16x16x64_i8 v[42:45], v[146:149], v[178:181], v[42:45]
	v_mfma_i32_16x16x64_i8 v[74:77], v[158:161], v[182:185], v[74:77]
	v_mfma_i32_16x16x64_i8 v[74:77], v[154:157], v[186:189], v[74:77]
	v_mfma_i32_16x16x64_i8 v[70:73], v[150:153], v[182:185], v[70:73]
	v_mfma_i32_16x16x64_i8 v[70:73], v[146:149], v[186:189], v[70:73]
	v_mfma_i32_16x16x64_i8 v[94:97], v[158:161], v[190:193], v[94:97]
	v_mfma_i32_16x16x64_i8 v[94:97], v[154:157], v[238:241], v[94:97]
	v_mfma_i32_16x16x64_i8 v[90:93], v[150:153], v[190:193], v[90:93]
	v_mfma_i32_16x16x64_i8 v[90:93], v[146:149], v[238:241], v[90:93]
	v_mfma_i32_16x16x64_i8 v[38:41], v[142:145], v[166:169], v[38:41]
	v_mfma_i32_16x16x64_i8 v[38:41], v[138:141], v[170:173], v[38:41]
	v_mfma_i32_16x16x64_i8 v[34:37], v[134:137], v[166:169], v[34:37]
	v_mfma_i32_16x16x64_i8 v[34:37], v[130:133], v[170:173], v[34:37]
	v_mfma_i32_16x16x64_i8 v[58:61], v[142:145], v[174:177], v[58:61]
	v_mfma_i32_16x16x64_i8 v[58:61], v[138:141], v[178:181], v[58:61]
	v_mfma_i32_16x16x64_i8 v[54:57], v[134:137], v[174:177], v[54:57]
	v_mfma_i32_16x16x64_i8 v[54:57], v[130:133], v[178:181], v[54:57]
	v_mfma_i32_16x16x64_i8 v[86:89], v[142:145], v[182:185], v[86:89]
	v_mfma_i32_16x16x64_i8 v[86:89], v[138:141], v[186:189], v[86:89]
	v_mfma_i32_16x16x64_i8 v[82:85], v[134:137], v[182:185], v[82:85]
	v_mfma_i32_16x16x64_i8 v[82:85], v[130:133], v[186:189], v[82:85]
	s_barrier
	s_setprio 2
	v_mfma_i32_16x16x64_i8 v[102:105], v[142:145], v[190:193], v[102:105]
	v_mfma_i32_16x16x64_i8 v[102:105], v[138:141], v[238:241], v[102:105]
	v_mfma_i32_16x16x64_i8 v[98:101], v[134:137], v[190:193], v[98:101]
	v_mfma_i32_16x16x64_i8 v[98:101], v[130:133], v[238:241], v[98:101]
	s_setprio 0
	s_mov_b32 m0, s68
	v_lshl_add_u64 v[166:167], s[38:39], 0, v[202:203]
	s_add_u32 s82, s38, 0x80000
	ds_read_b128 v[174:177], v226 offset:16384
	ds_read_b128 v[178:181], v226 offset:17408
	ds_read_b128 v[182:185], v226 offset:18432
	ds_read_b128 v[186:189], v226 offset:19456
	ds_read_b128 v[190:193], v226 offset:20480
	ds_read_b128 v[238:241], v226 offset:21504
	ds_read_b128 v[242:245], v226 offset:22528
	ds_read_b128 v[246:249], v226 offset:23552
	global_load_lds_dwordx4 v[166:167], off
	v_lshl_add_u64 v[168:169], s[38:39], 0, v[206:207]
	s_mov_b32 m0, s69
	s_addc_u32 s83, s39, 0
	global_load_lds_dwordx4 v[168:169], off
	v_lshl_add_u64 v[170:171], s[82:83], 0, v[202:203]
	s_mov_b32 m0, s70
	v_lshl_add_u64 v[172:173], s[40:41], 0, v[204:205]
	global_load_lds_dwordx4 v[170:171], off
	v_lshl_add_u64 v[170:171], s[82:83], 0, v[206:207]
	s_mov_b32 m0, s71
	s_nop 0
	global_load_lds_dwordx4 v[170:171], off
	v_lshl_add_u64 v[170:171], s[40:41], 0, v[194:195]
	s_mov_b32 m0, s23
	s_nop 0
	global_load_lds_dwordx4 v[170:171], off
	s_mov_b32 m0, s42
	s_nop 0
	global_load_lds_dwordx4 v[172:173], off
	s_waitcnt vmcnt(8)
	s_waitcnt lgkmcnt(0)
	s_barrier
	s_setprio 1
	s_waitcnt lgkmcnt(0)
	v_mfma_i32_16x16x64_i8 v[110:113], v[158:161], v[174:177], v[110:113]
	v_mfma_i32_16x16x64_i8 v[110:113], v[154:157], v[178:181], v[110:113]
	v_mfma_i32_16x16x64_i8 v[106:109], v[150:153], v[174:177], v[106:109]
	v_mfma_i32_16x16x64_i8 v[106:109], v[146:149], v[178:181], v[106:109]
	v_mfma_i32_16x16x64_i8 v[126:129], v[158:161], v[182:185], v[126:129]
	v_mfma_i32_16x16x64_i8 v[126:129], v[154:157], v[186:189], v[126:129]
	v_mfma_i32_16x16x64_i8 v[118:121], v[150:153], v[182:185], v[118:121]
	v_mfma_i32_16x16x64_i8 v[118:121], v[146:149], v[186:189], v[118:121]
	v_mfma_i32_16x16x64_i8 v[62:65], v[158:161], v[190:193], v[62:65]
	v_mfma_i32_16x16x64_i8 v[62:65], v[154:157], v[238:241], v[62:65]
	v_mfma_i32_16x16x64_i8 v[50:53], v[150:153], v[190:193], v[50:53]
	v_mfma_i32_16x16x64_i8 v[50:53], v[146:149], v[238:241], v[50:53]
	v_mfma_i32_16x16x64_i8 v[14:17], v[158:161], v[242:245], v[14:17]
	v_mfma_i32_16x16x64_i8 v[14:17], v[154:157], v[246:249], v[14:17]
	v_mfma_i32_16x16x64_i8 v[10:13], v[150:153], v[242:245], v[10:13]
	v_mfma_i32_16x16x64_i8 v[10:13], v[146:149], v[246:249], v[10:13]
	v_mfma_i32_16x16x64_i8 v[122:125], v[142:145], v[174:177], v[122:125]
	v_mfma_i32_16x16x64_i8 v[122:125], v[138:141], v[178:181], v[122:125]
	v_mfma_i32_16x16x64_i8 v[114:117], v[134:137], v[174:177], v[114:117]
	v_mfma_i32_16x16x64_i8 v[114:117], v[130:133], v[178:181], v[114:117]
	v_mfma_i32_16x16x64_i8 v[78:81], v[142:145], v[182:185], v[78:81]
	v_mfma_i32_16x16x64_i8 v[78:81], v[138:141], v[186:189], v[78:81]
	v_mfma_i32_16x16x64_i8 v[66:69], v[134:137], v[182:185], v[66:69]
	v_mfma_i32_16x16x64_i8 v[66:69], v[130:133], v[186:189], v[66:69]
	v_mfma_i32_16x16x64_i8 v[22:25], v[142:145], v[190:193], v[22:25]
	v_mfma_i32_16x16x64_i8 v[22:25], v[138:141], v[238:241], v[22:25]
	v_mfma_i32_16x16x64_i8 v[18:21], v[134:137], v[190:193], v[18:21]
	v_mfma_i32_16x16x64_i8 v[18:21], v[130:133], v[238:241], v[18:21]
	s_barrier
	s_setprio 2
	v_mfma_i32_16x16x64_i8 v[6:9], v[142:145], v[242:245], v[6:9]
	v_mfma_i32_16x16x64_i8 v[6:9], v[138:141], v[246:249], v[6:9]
	v_mfma_i32_16x16x64_i8 v[2:5], v[134:137], v[242:245], v[2:5]
	v_mfma_i32_16x16x64_i8 v[2:5], v[130:133], v[246:249], v[2:5]
	s_setprio 0
	ds_read_b128 v[130:133], v235
	ds_read_b128 v[134:137], v235 offset:1024
	ds_read_b128 v[138:141], v235 offset:2048
	ds_read_b128 v[142:145], v235 offset:3072
	ds_read_b128 v[146:149], v236
	ds_read_b128 v[150:153], v236 offset:1024
	ds_read_b128 v[154:157], v236 offset:2048
	ds_read_b128 v[158:161], v236 offset:3072
	s_add_u32 s40, s40, 0x80000
	s_addc_u32 s41, s41, 0
	s_mov_b32 m0, s43
	v_lshl_add_u64 v[250:251], s[40:41], 0, v[194:195]
	ds_read_b128 v[174:177], v226 offset:32768
	ds_read_b128 v[178:181], v226 offset:33792
	ds_read_b128 v[182:185], v226 offset:34816
	ds_read_b128 v[186:189], v226 offset:35840
	ds_read_b128 v[190:193], v226 offset:36864
	ds_read_b128 v[238:241], v226 offset:37888
	ds_read_b128 v[242:245], v226 offset:38912
	ds_read_b128 v[246:249], v226 offset:39936
	global_load_lds_dwordx4 v[250:251], off
	v_lshl_add_u64 v[250:251], s[40:41], 0, v[204:205]
	s_mov_b32 m0, s44
	s_nop 0
	global_load_lds_dwordx4 v[250:251], off
	s_waitcnt vmcnt(8)
	s_waitcnt lgkmcnt(0)
	s_barrier
	s_setprio 1
	s_waitcnt lgkmcnt(0)
	v_mfma_i32_16x16x64_i8 v[30:33], v[130:133], v[174:177], v[30:33]
	v_mfma_i32_16x16x64_i8 v[30:33], v[134:137], v[178:181], v[30:33]
	v_mfma_i32_16x16x64_i8 v[26:29], v[138:141], v[174:177], v[26:29]
	v_mfma_i32_16x16x64_i8 v[26:29], v[142:145], v[178:181], v[26:29]
	v_mfma_i32_16x16x64_i8 v[46:49], v[130:133], v[182:185], v[46:49]
	v_mfma_i32_16x16x64_i8 v[46:49], v[134:137], v[186:189], v[46:49]
	v_mfma_i32_16x16x64_i8 v[42:45], v[138:141], v[182:185], v[42:45]
	v_mfma_i32_16x16x64_i8 v[42:45], v[142:145], v[186:189], v[42:45]
	v_mfma_i32_16x16x64_i8 v[74:77], v[130:133], v[190:193], v[74:77]
	v_mfma_i32_16x16x64_i8 v[74:77], v[134:137], v[238:241], v[74:77]
	v_mfma_i32_16x16x64_i8 v[70:73], v[138:141], v[190:193], v[70:73]
	v_mfma_i32_16x16x64_i8 v[70:73], v[142:145], v[238:241], v[70:73]
	v_mfma_i32_16x16x64_i8 v[94:97], v[130:133], v[242:245], v[94:97]
	v_mfma_i32_16x16x64_i8 v[94:97], v[134:137], v[246:249], v[94:97]
	v_mfma_i32_16x16x64_i8 v[90:93], v[138:141], v[242:245], v[90:93]
	v_mfma_i32_16x16x64_i8 v[90:93], v[142:145], v[246:249], v[90:93]
	v_mfma_i32_16x16x64_i8 v[38:41], v[146:149], v[174:177], v[38:41]
	v_mfma_i32_16x16x64_i8 v[38:41], v[150:153], v[178:181], v[38:41]
	v_mfma_i32_16x16x64_i8 v[34:37], v[154:157], v[174:177], v[34:37]
	v_mfma_i32_16x16x64_i8 v[34:37], v[158:161], v[178:181], v[34:37]
	v_mfma_i32_16x16x64_i8 v[58:61], v[146:149], v[182:185], v[58:61]
	v_mfma_i32_16x16x64_i8 v[58:61], v[150:153], v[186:189], v[58:61]
	v_mfma_i32_16x16x64_i8 v[54:57], v[154:157], v[182:185], v[54:57]
	v_mfma_i32_16x16x64_i8 v[54:57], v[158:161], v[186:189], v[54:57]
	v_mfma_i32_16x16x64_i8 v[86:89], v[146:149], v[190:193], v[86:89]
	v_mfma_i32_16x16x64_i8 v[86:89], v[150:153], v[238:241], v[86:89]
	v_mfma_i32_16x16x64_i8 v[82:85], v[154:157], v[190:193], v[82:85]
	v_mfma_i32_16x16x64_i8 v[82:85], v[158:161], v[238:241], v[82:85]
	s_barrier
	s_setprio 2
	v_mfma_i32_16x16x64_i8 v[102:105], v[146:149], v[242:245], v[102:105]
	v_mfma_i32_16x16x64_i8 v[102:105], v[150:153], v[246:249], v[102:105]
	v_mfma_i32_16x16x64_i8 v[98:101], v[154:157], v[242:245], v[98:101]
	v_mfma_i32_16x16x64_i8 v[98:101], v[158:161], v[246:249], v[98:101]
	s_setprio 0
	s_mov_b32 m0, s72
	v_lshl_add_u64 v[166:167], v[166:167], 0, s[6:7]
	s_add_u32 s38, s38, 0x80080
	ds_read_b128 v[174:177], v226 offset:49152
	ds_read_b128 v[178:181], v226 offset:50176
	ds_read_b128 v[182:185], v226 offset:51200
	ds_read_b128 v[186:189], v226 offset:52224
	ds_read_b128 v[190:193], v226 offset:53248
	ds_read_b128 v[238:241], v226 offset:54272
	ds_read_b128 v[242:245], v226 offset:55296
	ds_read_b128 v[246:249], v226 offset:56320
	global_load_lds_dwordx4 v[166:167], off
	v_lshl_add_u64 v[166:167], v[168:169], 0, s[6:7]
	s_mov_b32 m0, s73
	s_addc_u32 s39, s39, 0
	global_load_lds_dwordx4 v[166:167], off
	v_lshl_add_u64 v[166:167], s[38:39], 0, v[202:203]
	s_mov_b32 m0, s74
	s_nop 0
	global_load_lds_dwordx4 v[166:167], off
	v_lshl_add_u64 v[166:167], s[38:39], 0, v[206:207]
	s_mov_b32 m0, s75
	s_nop 0
	global_load_lds_dwordx4 v[166:167], off
	v_lshl_add_u64 v[166:167], v[170:171], 0, s[6:7]
	s_mov_b32 m0, s51
	s_nop 0
	global_load_lds_dwordx4 v[166:167], off
	v_lshl_add_u64 v[166:167], v[172:173], 0, s[6:7]
	s_mov_b32 m0, s53
	s_nop 0
	global_load_lds_dwordx4 v[166:167], off
	s_waitcnt vmcnt(8)
	s_waitcnt lgkmcnt(0)
	s_barrier
	s_setprio 1
	s_waitcnt lgkmcnt(0)
	v_mfma_i32_16x16x64_i8 v[110:113], v[130:133], v[174:177], v[110:113]
	v_mfma_i32_16x16x64_i8 v[110:113], v[134:137], v[178:181], v[110:113]
	v_mfma_i32_16x16x64_i8 v[106:109], v[138:141], v[174:177], v[106:109]
	v_mfma_i32_16x16x64_i8 v[106:109], v[142:145], v[178:181], v[106:109]
	v_mfma_i32_16x16x64_i8 v[126:129], v[130:133], v[182:185], v[126:129]
	v_mfma_i32_16x16x64_i8 v[126:129], v[134:137], v[186:189], v[126:129]
	v_mfma_i32_16x16x64_i8 v[118:121], v[138:141], v[182:185], v[118:121]
	v_mfma_i32_16x16x64_i8 v[118:121], v[142:145], v[186:189], v[118:121]
	v_mfma_i32_16x16x64_i8 v[62:65], v[130:133], v[190:193], v[62:65]
	v_mfma_i32_16x16x64_i8 v[62:65], v[134:137], v[238:241], v[62:65]
	v_mfma_i32_16x16x64_i8 v[50:53], v[138:141], v[190:193], v[50:53]
	v_mfma_i32_16x16x64_i8 v[50:53], v[142:145], v[238:241], v[50:53]
	v_mfma_i32_16x16x64_i8 v[14:17], v[130:133], v[242:245], v[14:17]
	v_mfma_i32_16x16x64_i8 v[14:17], v[134:137], v[246:249], v[14:17]
	v_mfma_i32_16x16x64_i8 v[10:13], v[138:141], v[242:245], v[10:13]
	v_mfma_i32_16x16x64_i8 v[10:13], v[142:145], v[246:249], v[10:13]
	v_mfma_i32_16x16x64_i8 v[122:125], v[146:149], v[174:177], v[122:125]
	v_mfma_i32_16x16x64_i8 v[122:125], v[150:153], v[178:181], v[122:125]
	v_mfma_i32_16x16x64_i8 v[114:117], v[154:157], v[174:177], v[114:117]
	v_mfma_i32_16x16x64_i8 v[114:117], v[158:161], v[178:181], v[114:117]
	v_mfma_i32_16x16x64_i8 v[78:81], v[146:149], v[182:185], v[78:81]
	v_mfma_i32_16x16x64_i8 v[78:81], v[150:153], v[186:189], v[78:81]
	v_mfma_i32_16x16x64_i8 v[66:69], v[154:157], v[182:185], v[66:69]
	v_mfma_i32_16x16x64_i8 v[66:69], v[158:161], v[186:189], v[66:69]
	v_mfma_i32_16x16x64_i8 v[22:25], v[146:149], v[190:193], v[22:25]
	v_mfma_i32_16x16x64_i8 v[22:25], v[150:153], v[238:241], v[22:25]
	v_mfma_i32_16x16x64_i8 v[18:21], v[154:157], v[190:193], v[18:21]
	v_mfma_i32_16x16x64_i8 v[18:21], v[158:161], v[238:241], v[18:21]
	s_barrier
	s_setprio 2
	v_mfma_i32_16x16x64_i8 v[6:9], v[146:149], v[242:245], v[6:9]
	v_mfma_i32_16x16x64_i8 v[6:9], v[150:153], v[246:249], v[6:9]
	v_mfma_i32_16x16x64_i8 v[2:5], v[154:157], v[242:245], v[2:5]
	v_mfma_i32_16x16x64_i8 v[2:5], v[158:161], v[246:249], v[2:5]
	s_setprio 0
	s_add_i32 s80, s80, 2
	s_add_u32 s36, s36, 0x100
	s_addc_u32 s37, s37, 0
	s_cmp_gt_u32 s80, 13
	s_cbranch_scc0 .LBB0_746
	s_nop 15
	s_nop 15
	s_and_b64 vcc, exec, s[8:9]
	s_cbranch_vccz .LBB0_749
	s_barrier

.LBB0_752:
	ds_read_b128 v[134:137], v227
	ds_read_b128 v[138:141], v227 offset:1024
	ds_read_b128 v[142:145], v227 offset:2048
	ds_read_b128 v[146:149], v227 offset:3072
	ds_read_b128 v[150:153], v233
	ds_read_b128 v[154:157], v233 offset:1024
	ds_read_b128 v[158:161], v233 offset:2048
	ds_read_b128 v[162:165], v233 offset:3072
	s_add_u32 s30, s29, s2
	s_addc_u32 s31, s33, s3
	s_add_u32 s30, s30, 0x200100
	s_addc_u32 s31, s31, 0
	s_add_u32 s77, s25, s2
	s_addc_u32 s78, s40, s3
	s_cmpk_eq_i32 s2, 0xf00
	s_cselect_b32 s35, s0, s31
	s_cselect_b32 s34, s1, s30
	s_cselect_b32 s31, s14, s78
	s_cselect_b32 s30, s15, s77
	s_mov_b32 m0, s66
	v_lshl_add_u64 v[242:243], v[130:131], 0, s[2:3]
	ds_read_b128 v[166:169], v226
	ds_read_b128 v[170:173], v226 offset:1024
	ds_read_b128 v[174:177], v226 offset:2048
	ds_read_b128 v[178:181], v226 offset:3072
	ds_read_b128 v[182:185], v226 offset:4096
	ds_read_b128 v[186:189], v226 offset:5120
	ds_read_b128 v[190:193], v226 offset:6144
	ds_read_b128 v[238:241], v226 offset:7168
	global_load_lds_dwordx4 v[242:243], off
	v_lshl_add_u64 v[242:243], v[132:133], 0, s[2:3]
	s_mov_b32 m0, s67
	s_nop 0
	global_load_lds_dwordx4 v[242:243], off
	s_waitcnt vmcnt(8)
	s_waitcnt lgkmcnt(0)
	s_barrier
	s_setprio 1
	s_waitcnt lgkmcnt(0)
	v_mfma_f32_16x16x32_bf16 v[26:29], v[134:137], v[166:169], v[26:29]
	v_mfma_f32_16x16x32_bf16 v[30:33], v[142:145], v[166:169], v[30:33]
	v_mfma_f32_16x16x32_bf16 v[42:45], v[134:137], v[174:177], v[42:45]
	v_mfma_f32_16x16x32_bf16 v[46:49], v[142:145], v[174:177], v[46:49]
	v_mfma_f32_16x16x32_bf16 v[70:73], v[134:137], v[182:185], v[70:73]
	v_mfma_f32_16x16x32_bf16 v[74:77], v[142:145], v[182:185], v[74:77]
	v_mfma_f32_16x16x32_bf16 v[90:93], v[134:137], v[190:193], v[90:93]
	v_mfma_f32_16x16x32_bf16 v[94:97], v[142:145], v[190:193], v[94:97]
	v_mfma_f32_16x16x32_bf16 v[26:29], v[138:141], v[170:173], v[26:29]
	v_mfma_f32_16x16x32_bf16 v[30:33], v[146:149], v[170:173], v[30:33]
	v_mfma_f32_16x16x32_bf16 v[42:45], v[138:141], v[178:181], v[42:45]
	v_mfma_f32_16x16x32_bf16 v[46:49], v[146:149], v[178:181], v[46:49]
	v_mfma_f32_16x16x32_bf16 v[70:73], v[138:141], v[186:189], v[70:73]
	v_mfma_f32_16x16x32_bf16 v[74:77], v[146:149], v[186:189], v[74:77]
	v_mfma_f32_16x16x32_bf16 v[90:93], v[138:141], v[238:241], v[90:93]
	v_mfma_f32_16x16x32_bf16 v[94:97], v[146:149], v[238:241], v[94:97]
	v_mfma_f32_16x16x32_bf16 v[34:37], v[150:153], v[166:169], v[34:37]
	v_mfma_f32_16x16x32_bf16 v[38:41], v[158:161], v[166:169], v[38:41]
	v_mfma_f32_16x16x32_bf16 v[54:57], v[150:153], v[174:177], v[54:57]
	v_mfma_f32_16x16x32_bf16 v[58:61], v[158:161], v[174:177], v[58:61]
	v_mfma_f32_16x16x32_bf16 v[82:85], v[150:153], v[182:185], v[82:85]
	v_mfma_f32_16x16x32_bf16 v[86:89], v[158:161], v[182:185], v[86:89]
	v_mfma_f32_16x16x32_bf16 v[98:101], v[150:153], v[190:193], v[98:101]
	v_mfma_f32_16x16x32_bf16 v[102:105], v[158:161], v[190:193], v[102:105]
	v_mfma_f32_16x16x32_bf16 v[34:37], v[154:157], v[170:173], v[34:37]
	v_mfma_f32_16x16x32_bf16 v[38:41], v[162:165], v[170:173], v[38:41]
	v_mfma_f32_16x16x32_bf16 v[54:57], v[154:157], v[178:181], v[54:57]
	v_mfma_f32_16x16x32_bf16 v[58:61], v[162:165], v[178:181], v[58:61]
	s_barrier
	s_setprio 2
	v_mfma_f32_16x16x32_bf16 v[82:85], v[154:157], v[186:189], v[82:85]
	v_mfma_f32_16x16x32_bf16 v[86:89], v[162:165], v[186:189], v[86:89]
	v_mfma_f32_16x16x32_bf16 v[98:101], v[154:157], v[238:241], v[98:101]
	v_mfma_f32_16x16x32_bf16 v[102:105], v[162:165], v[238:241], v[102:105]
	s_setprio 0
	s_mov_b32 m0, s68
	v_lshl_add_u64 v[242:243], s[30:31], 0, v[202:203]
	s_add_u32 s78, s30, 0x80000
	ds_read_b128 v[166:169], v226 offset:16384
	ds_read_b128 v[170:173], v226 offset:17408
	ds_read_b128 v[174:177], v226 offset:18432
	ds_read_b128 v[178:181], v226 offset:19456
	ds_read_b128 v[182:185], v226 offset:20480
	ds_read_b128 v[186:189], v226 offset:21504
	ds_read_b128 v[190:193], v226 offset:22528
	ds_read_b128 v[238:241], v226 offset:23552
	global_load_lds_dwordx4 v[242:243], off
	v_lshl_add_u64 v[244:245], s[30:31], 0, v[206:207]
	s_mov_b32 m0, s69
	s_addc_u32 s79, s31, 0
	global_load_lds_dwordx4 v[244:245], off
	v_lshl_add_u64 v[246:247], s[78:79], 0, v[202:203]
	s_mov_b32 m0, s70
	v_lshl_add_u64 v[248:249], s[34:35], 0, v[204:205]
	global_load_lds_dwordx4 v[246:247], off
	v_lshl_add_u64 v[246:247], s[78:79], 0, v[206:207]
	s_mov_b32 m0, s71
	s_nop 0
	global_load_lds_dwordx4 v[246:247], off
	v_lshl_add_u64 v[246:247], s[34:35], 0, v[194:195]
	s_mov_b32 m0, s23
	s_nop 0
	global_load_lds_dwordx4 v[246:247], off
	s_mov_b32 m0, s42
	s_nop 0
	global_load_lds_dwordx4 v[248:249], off
	s_waitcnt vmcnt(8)
	s_waitcnt lgkmcnt(0)
	s_barrier
	s_setprio 1
	s_waitcnt lgkmcnt(0)
	v_mfma_f32_16x16x32_bf16 v[106:109], v[134:137], v[166:169], v[106:109]
	v_mfma_f32_16x16x32_bf16 v[110:113], v[142:145], v[166:169], v[110:113]
	v_mfma_f32_16x16x32_bf16 v[118:121], v[134:137], v[174:177], v[118:121]
	v_mfma_f32_16x16x32_bf16 v[126:129], v[142:145], v[174:177], v[126:129]
	v_mfma_f32_16x16x32_bf16 v[50:53], v[134:137], v[182:185], v[50:53]
	v_mfma_f32_16x16x32_bf16 v[62:65], v[142:145], v[182:185], v[62:65]
	v_mfma_f32_16x16x32_bf16 v[10:13], v[134:137], v[190:193], v[10:13]
	v_mfma_f32_16x16x32_bf16 v[14:17], v[142:145], v[190:193], v[14:17]
	v_mfma_f32_16x16x32_bf16 v[106:109], v[138:141], v[170:173], v[106:109]
	v_mfma_f32_16x16x32_bf16 v[110:113], v[146:149], v[170:173], v[110:113]
	v_mfma_f32_16x16x32_bf16 v[118:121], v[138:141], v[178:181], v[118:121]
	v_mfma_f32_16x16x32_bf16 v[126:129], v[146:149], v[178:181], v[126:129]
	v_mfma_f32_16x16x32_bf16 v[50:53], v[138:141], v[186:189], v[50:53]
	v_mfma_f32_16x16x32_bf16 v[62:65], v[146:149], v[186:189], v[62:65]
	v_mfma_f32_16x16x32_bf16 v[10:13], v[138:141], v[238:241], v[10:13]
	v_mfma_f32_16x16x32_bf16 v[14:17], v[146:149], v[238:241], v[14:17]
	v_mfma_f32_16x16x32_bf16 v[114:117], v[150:153], v[166:169], v[114:117]
	v_mfma_f32_16x16x32_bf16 v[122:125], v[158:161], v[166:169], v[122:125]
	v_mfma_f32_16x16x32_bf16 v[66:69], v[150:153], v[174:177], v[66:69]
	v_mfma_f32_16x16x32_bf16 v[78:81], v[158:161], v[174:177], v[78:81]
	v_mfma_f32_16x16x32_bf16 v[18:21], v[150:153], v[182:185], v[18:21]
	v_mfma_f32_16x16x32_bf16 v[22:25], v[158:161], v[182:185], v[22:25]
	v_mfma_f32_16x16x32_bf16 v[2:5], v[150:153], v[190:193], v[2:5]
	v_mfma_f32_16x16x32_bf16 v[6:9], v[158:161], v[190:193], v[6:9]
	v_mfma_f32_16x16x32_bf16 v[114:117], v[154:157], v[170:173], v[114:117]
	v_mfma_f32_16x16x32_bf16 v[122:125], v[162:165], v[170:173], v[122:125]
	v_mfma_f32_16x16x32_bf16 v[66:69], v[154:157], v[178:181], v[66:69]
	v_mfma_f32_16x16x32_bf16 v[78:81], v[162:165], v[178:181], v[78:81]
	s_barrier
	s_setprio 2
	v_mfma_f32_16x16x32_bf16 v[18:21], v[154:157], v[186:189], v[18:21]
	v_mfma_f32_16x16x32_bf16 v[22:25], v[162:165], v[186:189], v[22:25]
	v_mfma_f32_16x16x32_bf16 v[2:5], v[154:157], v[238:241], v[2:5]
	v_mfma_f32_16x16x32_bf16 v[6:9], v[162:165], v[238:241], v[6:9]
	s_setprio 0
	ds_read_b128 v[134:137], v235
	ds_read_b128 v[138:141], v235 offset:1024
	ds_read_b128 v[142:145], v235 offset:2048
	ds_read_b128 v[146:149], v235 offset:3072
	ds_read_b128 v[150:153], v236
	ds_read_b128 v[154:157], v236 offset:1024
	ds_read_b128 v[158:161], v236 offset:2048
	ds_read_b128 v[162:165], v236 offset:3072
	s_add_u32 s34, s34, 0x80000
	s_addc_u32 s35, s35, 0
	s_mov_b32 m0, s43
	v_lshl_add_u64 v[250:251], s[34:35], 0, v[194:195]
	ds_read_b128 v[166:169], v226 offset:32768
	ds_read_b128 v[170:173], v226 offset:33792
	ds_read_b128 v[174:177], v226 offset:34816
	ds_read_b128 v[178:181], v226 offset:35840
	ds_read_b128 v[182:185], v226 offset:36864
	ds_read_b128 v[186:189], v226 offset:37888
	ds_read_b128 v[190:193], v226 offset:38912
	ds_read_b128 v[238:241], v226 offset:39936
	global_load_lds_dwordx4 v[250:251], off
	v_lshl_add_u64 v[250:251], s[34:35], 0, v[204:205]
	s_mov_b32 m0, s44
	s_nop 0
	global_load_lds_dwordx4 v[250:251], off
	s_waitcnt vmcnt(8)
	s_waitcnt lgkmcnt(0)
	s_barrier
	s_setprio 1
	s_waitcnt lgkmcnt(0)
	v_mfma_f32_16x16x32_bf16 v[26:29], v[134:137], v[166:169], v[26:29]
	v_mfma_f32_16x16x32_bf16 v[30:33], v[142:145], v[166:169], v[30:33]
	v_mfma_f32_16x16x32_bf16 v[42:45], v[134:137], v[174:177], v[42:45]
	v_mfma_f32_16x16x32_bf16 v[46:49], v[142:145], v[174:177], v[46:49]
	v_mfma_f32_16x16x32_bf16 v[70:73], v[134:137], v[182:185], v[70:73]
	v_mfma_f32_16x16x32_bf16 v[74:77], v[142:145], v[182:185], v[74:77]
	v_mfma_f32_16x16x32_bf16 v[90:93], v[134:137], v[190:193], v[90:93]
	v_mfma_f32_16x16x32_bf16 v[94:97], v[142:145], v[190:193], v[94:97]
	v_mfma_f32_16x16x32_bf16 v[26:29], v[138:141], v[170:173], v[26:29]
	v_mfma_f32_16x16x32_bf16 v[30:33], v[146:149], v[170:173], v[30:33]
	v_mfma_f32_16x16x32_bf16 v[42:45], v[138:141], v[178:181], v[42:45]
	v_mfma_f32_16x16x32_bf16 v[46:49], v[146:149], v[178:181], v[46:49]
	v_mfma_f32_16x16x32_bf16 v[70:73], v[138:141], v[186:189], v[70:73]
	v_mfma_f32_16x16x32_bf16 v[74:77], v[146:149], v[186:189], v[74:77]
	v_mfma_f32_16x16x32_bf16 v[90:93], v[138:141], v[238:241], v[90:93]
	v_mfma_f32_16x16x32_bf16 v[94:97], v[146:149], v[238:241], v[94:97]
	v_mfma_f32_16x16x32_bf16 v[34:37], v[150:153], v[166:169], v[34:37]
	v_mfma_f32_16x16x32_bf16 v[38:41], v[158:161], v[166:169], v[38:41]
	v_mfma_f32_16x16x32_bf16 v[54:57], v[150:153], v[174:177], v[54:57]
	v_mfma_f32_16x16x32_bf16 v[58:61], v[158:161], v[174:177], v[58:61]
	v_mfma_f32_16x16x32_bf16 v[82:85], v[150:153], v[182:185], v[82:85]
	v_mfma_f32_16x16x32_bf16 v[86:89], v[158:161], v[182:185], v[86:89]
	v_mfma_f32_16x16x32_bf16 v[98:101], v[150:153], v[190:193], v[98:101]
	v_mfma_f32_16x16x32_bf16 v[102:105], v[158:161], v[190:193], v[102:105]
	v_mfma_f32_16x16x32_bf16 v[34:37], v[154:157], v[170:173], v[34:37]
	v_mfma_f32_16x16x32_bf16 v[38:41], v[162:165], v[170:173], v[38:41]
	v_mfma_f32_16x16x32_bf16 v[54:57], v[154:157], v[178:181], v[54:57]
	v_mfma_f32_16x16x32_bf16 v[58:61], v[162:165], v[178:181], v[58:61]
	s_barrier
	s_setprio 2
	v_mfma_f32_16x16x32_bf16 v[82:85], v[154:157], v[186:189], v[82:85]
	v_mfma_f32_16x16x32_bf16 v[86:89], v[162:165], v[186:189], v[86:89]
	v_mfma_f32_16x16x32_bf16 v[98:101], v[154:157], v[238:241], v[98:101]
	v_mfma_f32_16x16x32_bf16 v[102:105], v[162:165], v[238:241], v[102:105]
	s_setprio 0
	s_mov_b32 m0, s72
	v_lshl_add_u64 v[242:243], v[242:243], 0, s[6:7]
	s_add_u32 s30, s30, 0x80080
	ds_read_b128 v[166:169], v226 offset:49152
	ds_read_b128 v[170:173], v226 offset:50176
	ds_read_b128 v[174:177], v226 offset:51200
	ds_read_b128 v[178:181], v226 offset:52224
	ds_read_b128 v[182:185], v226 offset:53248
	ds_read_b128 v[186:189], v226 offset:54272
	ds_read_b128 v[190:193], v226 offset:55296
	ds_read_b128 v[238:241], v226 offset:56320
	global_load_lds_dwordx4 v[242:243], off
	v_lshl_add_u64 v[242:243], v[244:245], 0, s[6:7]
	s_mov_b32 m0, s73
	s_addc_u32 s31, s31, 0
	global_load_lds_dwordx4 v[242:243], off
	v_lshl_add_u64 v[242:243], s[30:31], 0, v[202:203]
	s_mov_b32 m0, s74
	s_nop 0
	global_load_lds_dwordx4 v[242:243], off
	v_lshl_add_u64 v[242:243], s[30:31], 0, v[206:207]
	s_mov_b32 m0, s75
	s_nop 0
	global_load_lds_dwordx4 v[242:243], off
	v_lshl_add_u64 v[242:243], v[246:247], 0, s[6:7]
	s_mov_b32 m0, s51
	s_nop 0
	global_load_lds_dwordx4 v[242:243], off
	v_lshl_add_u64 v[242:243], v[248:249], 0, s[6:7]
	s_mov_b32 m0, s53
	s_nop 0
	global_load_lds_dwordx4 v[242:243], off
	s_waitcnt vmcnt(8)
	s_waitcnt lgkmcnt(0)
	s_barrier
	s_setprio 1
	s_waitcnt lgkmcnt(0)
	v_mfma_f32_16x16x32_bf16 v[106:109], v[134:137], v[166:169], v[106:109]
	v_mfma_f32_16x16x32_bf16 v[110:113], v[142:145], v[166:169], v[110:113]
	v_mfma_f32_16x16x32_bf16 v[118:121], v[134:137], v[174:177], v[118:121]
	v_mfma_f32_16x16x32_bf16 v[126:129], v[142:145], v[174:177], v[126:129]
	v_mfma_f32_16x16x32_bf16 v[50:53], v[134:137], v[182:185], v[50:53]
	v_mfma_f32_16x16x32_bf16 v[62:65], v[142:145], v[182:185], v[62:65]
	v_mfma_f32_16x16x32_bf16 v[10:13], v[134:137], v[190:193], v[10:13]
	v_mfma_f32_16x16x32_bf16 v[14:17], v[142:145], v[190:193], v[14:17]
	v_mfma_f32_16x16x32_bf16 v[106:109], v[138:141], v[170:173], v[106:109]
	v_mfma_f32_16x16x32_bf16 v[110:113], v[146:149], v[170:173], v[110:113]
	v_mfma_f32_16x16x32_bf16 v[118:121], v[138:141], v[178:181], v[118:121]
	v_mfma_f32_16x16x32_bf16 v[126:129], v[146:149], v[178:181], v[126:129]
	v_mfma_f32_16x16x32_bf16 v[50:53], v[138:141], v[186:189], v[50:53]
	v_mfma_f32_16x16x32_bf16 v[62:65], v[146:149], v[186:189], v[62:65]
	v_mfma_f32_16x16x32_bf16 v[10:13], v[138:141], v[238:241], v[10:13]
	v_mfma_f32_16x16x32_bf16 v[14:17], v[146:149], v[238:241], v[14:17]
	v_mfma_f32_16x16x32_bf16 v[114:117], v[150:153], v[166:169], v[114:117]
	v_mfma_f32_16x16x32_bf16 v[122:125], v[158:161], v[166:169], v[122:125]
	v_mfma_f32_16x16x32_bf16 v[66:69], v[150:153], v[174:177], v[66:69]
	v_mfma_f32_16x16x32_bf16 v[78:81], v[158:161], v[174:177], v[78:81]
	v_mfma_f32_16x16x32_bf16 v[18:21], v[150:153], v[182:185], v[18:21]
	v_mfma_f32_16x16x32_bf16 v[22:25], v[158:161], v[182:185], v[22:25]
	v_mfma_f32_16x16x32_bf16 v[2:5], v[150:153], v[190:193], v[2:5]
	v_mfma_f32_16x16x32_bf16 v[6:9], v[158:161], v[190:193], v[6:9]
	v_mfma_f32_16x16x32_bf16 v[114:117], v[154:157], v[170:173], v[114:117]
	v_mfma_f32_16x16x32_bf16 v[122:125], v[162:165], v[170:173], v[122:125]
	v_mfma_f32_16x16x32_bf16 v[66:69], v[154:157], v[178:181], v[66:69]
	v_mfma_f32_16x16x32_bf16 v[78:81], v[162:165], v[178:181], v[78:81]
	s_barrier
	s_setprio 2
	v_mfma_f32_16x16x32_bf16 v[18:21], v[154:157], v[186:189], v[18:21]
	v_mfma_f32_16x16x32_bf16 v[22:25], v[162:165], v[186:189], v[22:25]
	v_mfma_f32_16x16x32_bf16 v[2:5], v[154:157], v[238:241], v[2:5]
	v_mfma_f32_16x16x32_bf16 v[6:9], v[162:165], v[238:241], v[6:9]
	s_setprio 0
	s_add_i32 s41, s41, 2
	s_add_u32 s2, s2, 0x100
	s_addc_u32 s3, s3, 0
	s_cmp_gt_u32 s41, 29
	s_cbranch_scc0 .LBB0_752
	s_and_b64 vcc, exec, s[8:9]
	s_cbranch_vccz .LBB0_755
	s_barrier

.LBB0_817:
	ds_read_b128 v[130:133], v223
	ds_read_b128 v[134:137], v223 offset:1024
	ds_read_b128 v[138:141], v223 offset:2048
	ds_read_b128 v[142:145], v223 offset:3072
	ds_read_b128 v[146:149], v224
	ds_read_b128 v[150:153], v224 offset:1024
	ds_read_b128 v[154:157], v224 offset:2048
	ds_read_b128 v[158:161], v224 offset:3072
	s_add_u32 s6, s4, 0xfff00080
	s_addc_u32 s7, s5, -1
	s_cmp_eq_u32 s14, 60
	s_cselect_b32 s9, s19, s7
	s_cselect_b32 s8, s18, s6
	s_cselect_b32 s7, s79, s1
	s_cselect_b32 s6, s78, s0
	v_lshl_add_u64 v[194:195], s[4:5], 0, v[170:171]
	s_add_i32 m0, s35, 0xc000
	ds_read_b128 v[174:177], v225
	ds_read_b128 v[178:181], v225 offset:1024
	ds_read_b128 v[182:185], v225 offset:2048
	ds_read_b128 v[186:189], v225 offset:3072
	ds_read_b128 v[190:193], v225 offset:4096
	ds_read_b128 v[202:205], v225 offset:5120
	ds_read_b128 v[206:209], v225 offset:6144
	ds_read_b128 v[210:213], v225 offset:7168
	global_load_lds_dwordx4 v[194:195], off
	v_lshl_add_u64 v[194:195], s[4:5], 0, v[172:173]
	s_add_i32 m0, s35, 0xe000
	s_nop 0
	global_load_lds_dwordx4 v[194:195], off
	s_waitcnt vmcnt(8)
	s_waitcnt lgkmcnt(0)
	s_barrier
	s_setprio 1
	s_waitcnt lgkmcnt(0)
	v_mfma_f32_16x16x32_bf16 v[14:17], v[130:133], v[174:177], v[14:17]
	v_mfma_f32_16x16x32_bf16 v[10:13], v[138:141], v[174:177], v[10:13]
	v_mfma_f32_16x16x32_bf16 v[34:37], v[130:133], v[182:185], v[34:37]
	v_mfma_f32_16x16x32_bf16 v[26:29], v[138:141], v[182:185], v[26:29]
	v_mfma_f32_16x16x32_bf16 v[46:49], v[130:133], v[190:193], v[46:49]
	v_mfma_f32_16x16x32_bf16 v[42:45], v[138:141], v[190:193], v[42:45]
	v_mfma_f32_16x16x32_bf16 v[62:65], v[130:133], v[206:209], v[62:65]
	v_mfma_f32_16x16x32_bf16 v[58:61], v[138:141], v[206:209], v[58:61]
	v_mfma_f32_16x16x32_bf16 v[14:17], v[134:137], v[178:181], v[14:17]
	v_mfma_f32_16x16x32_bf16 v[10:13], v[142:145], v[178:181], v[10:13]
	v_mfma_f32_16x16x32_bf16 v[34:37], v[134:137], v[186:189], v[34:37]
	v_mfma_f32_16x16x32_bf16 v[26:29], v[142:145], v[186:189], v[26:29]
	v_mfma_f32_16x16x32_bf16 v[46:49], v[134:137], v[202:205], v[46:49]
	v_mfma_f32_16x16x32_bf16 v[42:45], v[142:145], v[202:205], v[42:45]
	v_mfma_f32_16x16x32_bf16 v[62:65], v[134:137], v[210:213], v[62:65]
	v_mfma_f32_16x16x32_bf16 v[58:61], v[142:145], v[210:213], v[58:61]
	v_mfma_f32_16x16x32_bf16 v[6:9], v[146:149], v[174:177], v[6:9]
	v_mfma_f32_16x16x32_bf16 v[2:5], v[154:157], v[174:177], v[2:5]
	v_mfma_f32_16x16x32_bf16 v[22:25], v[146:149], v[182:185], v[22:25]
	v_mfma_f32_16x16x32_bf16 v[18:21], v[154:157], v[182:185], v[18:21]
	v_mfma_f32_16x16x32_bf16 v[38:41], v[146:149], v[190:193], v[38:41]
	v_mfma_f32_16x16x32_bf16 v[30:33], v[154:157], v[190:193], v[30:33]
	v_mfma_f32_16x16x32_bf16 v[54:57], v[146:149], v[206:209], v[54:57]
	v_mfma_f32_16x16x32_bf16 v[50:53], v[154:157], v[206:209], v[50:53]
	v_mfma_f32_16x16x32_bf16 v[6:9], v[150:153], v[178:181], v[6:9]
	v_mfma_f32_16x16x32_bf16 v[2:5], v[158:161], v[178:181], v[2:5]
	v_mfma_f32_16x16x32_bf16 v[22:25], v[150:153], v[186:189], v[22:25]
	v_mfma_f32_16x16x32_bf16 v[18:21], v[158:161], v[186:189], v[18:21]
	s_barrier
	s_setprio 2
	v_mfma_f32_16x16x32_bf16 v[38:41], v[150:153], v[202:205], v[38:41]
	v_mfma_f32_16x16x32_bf16 v[30:33], v[158:161], v[202:205], v[30:33]
	v_mfma_f32_16x16x32_bf16 v[54:57], v[150:153], v[210:213], v[54:57]
	v_mfma_f32_16x16x32_bf16 v[50:53], v[158:161], v[210:213], v[50:53]
	s_setprio 0
	s_add_i32 s15, s17, s33
	v_lshl_add_u64 v[194:195], s[6:7], 0, v[164:165]
	s_mov_b32 m0, s15
	ds_read_b128 v[174:177], v225 offset:16384
	ds_read_b128 v[178:181], v225 offset:17408
	ds_read_b128 v[182:185], v225 offset:18432
	ds_read_b128 v[186:189], v225 offset:19456
	ds_read_b128 v[190:193], v225 offset:20480
	ds_read_b128 v[202:205], v225 offset:21504
	ds_read_b128 v[206:209], v225 offset:22528
	ds_read_b128 v[210:213], v225 offset:23552
	global_load_lds_dwordx4 v[194:195], off
	s_add_i32 m0, s15, 0x2000
	s_add_u32 s44, s6, 0x100000
	v_lshl_add_u64 v[214:215], s[6:7], 0, v[168:169]
	s_addc_u32 s45, s7, 0
	s_add_i32 s15, s55, s33
	global_load_lds_dwordx4 v[214:215], off
	v_lshl_add_u64 v[216:217], s[44:45], 0, v[164:165]
	s_mov_b32 m0, s15
	v_lshl_add_u64 v[218:219], s[8:9], 0, v[166:167]
	global_load_lds_dwordx4 v[216:217], off
	v_lshl_add_u64 v[216:217], s[44:45], 0, v[168:169]
	s_add_i32 m0, s15, 0x2000
	s_nop 0
	global_load_lds_dwordx4 v[216:217], off
	v_lshl_add_u64 v[216:217], s[8:9], 0, v[162:163]
	s_mov_b32 m0, s35
	s_nop 0
	global_load_lds_dwordx4 v[216:217], off
	s_mov_b32 m0, s80
	s_nop 0
	global_load_lds_dwordx4 v[218:219], off
	s_waitcnt vmcnt(8)
	s_waitcnt lgkmcnt(0)
	s_barrier
	s_setprio 1
	s_waitcnt lgkmcnt(0)
	v_mfma_f32_16x16x32_bf16 v[78:81], v[130:133], v[174:177], v[78:81]
	v_mfma_f32_16x16x32_bf16 v[74:77], v[138:141], v[174:177], v[74:77]
	v_mfma_f32_16x16x32_bf16 v[94:97], v[130:133], v[182:185], v[94:97]
	v_mfma_f32_16x16x32_bf16 v[90:93], v[138:141], v[182:185], v[90:93]
	v_mfma_f32_16x16x32_bf16 v[110:113], v[130:133], v[190:193], v[110:113]
	v_mfma_f32_16x16x32_bf16 v[106:109], v[138:141], v[190:193], v[106:109]
	v_mfma_f32_16x16x32_bf16 v[118:121], v[130:133], v[206:209], v[118:121]
	v_mfma_f32_16x16x32_bf16 v[114:117], v[138:141], v[206:209], v[114:117]
	v_mfma_f32_16x16x32_bf16 v[78:81], v[134:137], v[178:181], v[78:81]
	v_mfma_f32_16x16x32_bf16 v[74:77], v[142:145], v[178:181], v[74:77]
	v_mfma_f32_16x16x32_bf16 v[94:97], v[134:137], v[186:189], v[94:97]
	v_mfma_f32_16x16x32_bf16 v[90:93], v[142:145], v[186:189], v[90:93]
	v_mfma_f32_16x16x32_bf16 v[110:113], v[134:137], v[202:205], v[110:113]
	v_mfma_f32_16x16x32_bf16 v[106:109], v[142:145], v[202:205], v[106:109]
	v_mfma_f32_16x16x32_bf16 v[118:121], v[134:137], v[210:213], v[118:121]
	v_mfma_f32_16x16x32_bf16 v[114:117], v[142:145], v[210:213], v[114:117]
	v_mfma_f32_16x16x32_bf16 v[70:73], v[146:149], v[174:177], v[70:73]
	v_mfma_f32_16x16x32_bf16 v[66:69], v[154:157], v[174:177], v[66:69]
	v_mfma_f32_16x16x32_bf16 v[86:89], v[146:149], v[182:185], v[86:89]
	v_mfma_f32_16x16x32_bf16 v[82:85], v[154:157], v[182:185], v[82:85]
	v_mfma_f32_16x16x32_bf16 v[102:105], v[146:149], v[190:193], v[102:105]
	v_mfma_f32_16x16x32_bf16 v[98:101], v[154:157], v[190:193], v[98:101]
	v_mfma_f32_16x16x32_bf16 v[122:125], v[146:149], v[206:209], v[122:125]
	v_mfma_f32_16x16x32_bf16 v[126:129], v[154:157], v[206:209], v[126:129]
	v_mfma_f32_16x16x32_bf16 v[70:73], v[150:153], v[178:181], v[70:73]
	v_mfma_f32_16x16x32_bf16 v[66:69], v[158:161], v[178:181], v[66:69]
	v_mfma_f32_16x16x32_bf16 v[86:89], v[150:153], v[186:189], v[86:89]
	v_mfma_f32_16x16x32_bf16 v[82:85], v[158:161], v[186:189], v[82:85]
	s_barrier
	s_setprio 2
	v_mfma_f32_16x16x32_bf16 v[102:105], v[150:153], v[202:205], v[102:105]
	v_mfma_f32_16x16x32_bf16 v[98:101], v[158:161], v[202:205], v[98:101]
	v_mfma_f32_16x16x32_bf16 v[122:125], v[150:153], v[210:213], v[122:125]
	v_mfma_f32_16x16x32_bf16 v[126:129], v[158:161], v[210:213], v[126:129]
	s_setprio 0
	s_add_i32 s56, 0, 0x18000
	s_add_i32 s57, 0, 0x1c000
	v_add_u32_e32 v142, s56, v222
	v_add_u32_e32 v158, s57, v222
	ds_read_b128 v[130:133], v142
	ds_read_b128 v[134:137], v142 offset:1024
	ds_read_b128 v[138:141], v142 offset:2048
	ds_read_b128 v[142:145], v142 offset:3072
	ds_read_b128 v[146:149], v158
	ds_read_b128 v[150:153], v158 offset:1024
	ds_read_b128 v[154:157], v158 offset:2048
	ds_read_b128 v[158:161], v158 offset:3072
	s_add_u32 s8, s8, 0x100000
	s_addc_u32 s9, s9, 0
	s_mov_b32 m0, s59
	v_lshl_add_u64 v[238:239], s[8:9], 0, v[162:163]
	ds_read_b128 v[174:177], v225 offset:32768
	ds_read_b128 v[178:181], v225 offset:33792
	ds_read_b128 v[182:185], v225 offset:34816
	ds_read_b128 v[186:189], v225 offset:35840
	ds_read_b128 v[190:193], v225 offset:36864
	ds_read_b128 v[202:205], v225 offset:37888
	ds_read_b128 v[206:209], v225 offset:38912
	ds_read_b128 v[210:213], v225 offset:39936
	global_load_lds_dwordx4 v[238:239], off
	v_lshl_add_u64 v[238:239], s[8:9], 0, v[166:167]
	s_mov_b32 m0, s60
	s_nop 0
	global_load_lds_dwordx4 v[238:239], off
	s_waitcnt vmcnt(8)
	s_waitcnt lgkmcnt(0)
	s_barrier
	s_setprio 1
	s_waitcnt lgkmcnt(0)
	v_mfma_f32_16x16x32_bf16 v[14:17], v[130:133], v[174:177], v[14:17]
	v_mfma_f32_16x16x32_bf16 v[10:13], v[138:141], v[174:177], v[10:13]
	v_mfma_f32_16x16x32_bf16 v[34:37], v[130:133], v[182:185], v[34:37]
	v_mfma_f32_16x16x32_bf16 v[26:29], v[138:141], v[182:185], v[26:29]
	v_mfma_f32_16x16x32_bf16 v[46:49], v[130:133], v[190:193], v[46:49]
	v_mfma_f32_16x16x32_bf16 v[42:45], v[138:141], v[190:193], v[42:45]
	v_mfma_f32_16x16x32_bf16 v[62:65], v[130:133], v[206:209], v[62:65]
	v_mfma_f32_16x16x32_bf16 v[58:61], v[138:141], v[206:209], v[58:61]
	v_mfma_f32_16x16x32_bf16 v[14:17], v[134:137], v[178:181], v[14:17]
	v_mfma_f32_16x16x32_bf16 v[10:13], v[142:145], v[178:181], v[10:13]
	v_mfma_f32_16x16x32_bf16 v[34:37], v[134:137], v[186:189], v[34:37]
	v_mfma_f32_16x16x32_bf16 v[26:29], v[142:145], v[186:189], v[26:29]
	v_mfma_f32_16x16x32_bf16 v[46:49], v[134:137], v[202:205], v[46:49]
	v_mfma_f32_16x16x32_bf16 v[42:45], v[142:145], v[202:205], v[42:45]
	v_mfma_f32_16x16x32_bf16 v[62:65], v[134:137], v[210:213], v[62:65]
	v_mfma_f32_16x16x32_bf16 v[58:61], v[142:145], v[210:213], v[58:61]
	v_mfma_f32_16x16x32_bf16 v[6:9], v[146:149], v[174:177], v[6:9]
	v_mfma_f32_16x16x32_bf16 v[2:5], v[154:157], v[174:177], v[2:5]
	v_mfma_f32_16x16x32_bf16 v[22:25], v[146:149], v[182:185], v[22:25]
	v_mfma_f32_16x16x32_bf16 v[18:21], v[154:157], v[182:185], v[18:21]
	v_mfma_f32_16x16x32_bf16 v[38:41], v[146:149], v[190:193], v[38:41]
	v_mfma_f32_16x16x32_bf16 v[30:33], v[154:157], v[190:193], v[30:33]
	v_mfma_f32_16x16x32_bf16 v[54:57], v[146:149], v[206:209], v[54:57]
	v_mfma_f32_16x16x32_bf16 v[50:53], v[154:157], v[206:209], v[50:53]
	v_mfma_f32_16x16x32_bf16 v[6:9], v[150:153], v[178:181], v[6:9]
	v_mfma_f32_16x16x32_bf16 v[2:5], v[158:161], v[178:181], v[2:5]
	v_mfma_f32_16x16x32_bf16 v[22:25], v[150:153], v[186:189], v[22:25]
	v_mfma_f32_16x16x32_bf16 v[18:21], v[158:161], v[186:189], v[18:21]
	s_barrier
	s_setprio 2
	v_mfma_f32_16x16x32_bf16 v[38:41], v[150:153], v[202:205], v[38:41]
	v_mfma_f32_16x16x32_bf16 v[30:33], v[158:161], v[202:205], v[30:33]
	v_mfma_f32_16x16x32_bf16 v[54:57], v[150:153], v[210:213], v[54:57]
	v_mfma_f32_16x16x32_bf16 v[50:53], v[158:161], v[210:213], v[50:53]
	s_setprio 0
	s_add_i32 s8, s56, s33
	v_lshl_add_u64 v[194:195], v[194:195], 0, s[26:27]
	s_mov_b32 m0, s8
	ds_read_b128 v[174:177], v225 offset:49152
	ds_read_b128 v[178:181], v225 offset:50176
	ds_read_b128 v[182:185], v225 offset:51200
	ds_read_b128 v[186:189], v225 offset:52224
	ds_read_b128 v[190:193], v225 offset:53248
	ds_read_b128 v[202:205], v225 offset:54272
	ds_read_b128 v[206:209], v225 offset:55296
	ds_read_b128 v[210:213], v225 offset:56320
	global_load_lds_dwordx4 v[194:195], off
	s_add_i32 m0, s8, 0x2000
	s_add_u32 s6, s6, 0x100080
	v_lshl_add_u64 v[194:195], v[214:215], 0, s[26:27]
	s_addc_u32 s7, s7, 0
	s_add_i32 s8, s57, s33
	global_load_lds_dwordx4 v[194:195], off
	v_lshl_add_u64 v[194:195], s[6:7], 0, v[164:165]
	s_mov_b32 m0, s8
	s_nop 0
	global_load_lds_dwordx4 v[194:195], off
	v_lshl_add_u64 v[194:195], s[6:7], 0, v[168:169]
	s_add_i32 m0, s8, 0x2000
	s_nop 0
	global_load_lds_dwordx4 v[194:195], off
	v_lshl_add_u64 v[194:195], v[216:217], 0, s[26:27]
	s_mov_b32 m0, s65
	s_nop 0
	global_load_lds_dwordx4 v[194:195], off
	v_lshl_add_u64 v[194:195], v[218:219], 0, s[26:27]
	s_mov_b32 m0, s66
	s_nop 0
	global_load_lds_dwordx4 v[194:195], off
	s_waitcnt vmcnt(8)
	s_waitcnt lgkmcnt(0)
	s_barrier
	s_setprio 1
	s_waitcnt lgkmcnt(0)
	v_mfma_f32_16x16x32_bf16 v[78:81], v[130:133], v[174:177], v[78:81]
	v_mfma_f32_16x16x32_bf16 v[74:77], v[138:141], v[174:177], v[74:77]
	v_mfma_f32_16x16x32_bf16 v[94:97], v[130:133], v[182:185], v[94:97]
	v_mfma_f32_16x16x32_bf16 v[90:93], v[138:141], v[182:185], v[90:93]
	v_mfma_f32_16x16x32_bf16 v[110:113], v[130:133], v[190:193], v[110:113]
	v_mfma_f32_16x16x32_bf16 v[106:109], v[138:141], v[190:193], v[106:109]
	v_mfma_f32_16x16x32_bf16 v[118:121], v[130:133], v[206:209], v[118:121]
	v_mfma_f32_16x16x32_bf16 v[114:117], v[138:141], v[206:209], v[114:117]
	v_mfma_f32_16x16x32_bf16 v[78:81], v[134:137], v[178:181], v[78:81]
	v_mfma_f32_16x16x32_bf16 v[74:77], v[142:145], v[178:181], v[74:77]
	v_mfma_f32_16x16x32_bf16 v[94:97], v[134:137], v[186:189], v[94:97]
	v_mfma_f32_16x16x32_bf16 v[90:93], v[142:145], v[186:189], v[90:93]
	v_mfma_f32_16x16x32_bf16 v[110:113], v[134:137], v[202:205], v[110:113]
	v_mfma_f32_16x16x32_bf16 v[106:109], v[142:145], v[202:205], v[106:109]
	v_mfma_f32_16x16x32_bf16 v[118:121], v[134:137], v[210:213], v[118:121]
	v_mfma_f32_16x16x32_bf16 v[114:117], v[142:145], v[210:213], v[114:117]
	v_mfma_f32_16x16x32_bf16 v[70:73], v[146:149], v[174:177], v[70:73]
	v_mfma_f32_16x16x32_bf16 v[66:69], v[154:157], v[174:177], v[66:69]
	v_mfma_f32_16x16x32_bf16 v[86:89], v[146:149], v[182:185], v[86:89]
	v_mfma_f32_16x16x32_bf16 v[82:85], v[154:157], v[182:185], v[82:85]
	v_mfma_f32_16x16x32_bf16 v[102:105], v[146:149], v[190:193], v[102:105]
	v_mfma_f32_16x16x32_bf16 v[98:101], v[154:157], v[190:193], v[98:101]
	v_mfma_f32_16x16x32_bf16 v[122:125], v[146:149], v[206:209], v[122:125]
	v_mfma_f32_16x16x32_bf16 v[126:129], v[154:157], v[206:209], v[126:129]
	v_mfma_f32_16x16x32_bf16 v[70:73], v[150:153], v[178:181], v[70:73]
	v_mfma_f32_16x16x32_bf16 v[66:69], v[158:161], v[178:181], v[66:69]
	v_mfma_f32_16x16x32_bf16 v[86:89], v[150:153], v[186:189], v[86:89]
	v_mfma_f32_16x16x32_bf16 v[82:85], v[158:161], v[186:189], v[82:85]
	s_barrier
	s_setprio 2
	v_mfma_f32_16x16x32_bf16 v[102:105], v[150:153], v[202:205], v[102:105]
	v_mfma_f32_16x16x32_bf16 v[98:101], v[158:161], v[202:205], v[98:101]
	v_mfma_f32_16x16x32_bf16 v[122:125], v[150:153], v[210:213], v[122:125]
	v_mfma_f32_16x16x32_bf16 v[126:129], v[158:161], v[210:213], v[126:129]
	s_setprio 0
	s_add_i32 s14, s14, 2
	s_add_u32 s4, s4, 0x100
	s_addc_u32 s5, s5, 0
	s_add_u32 s0, s0, 0x100
	s_addc_u32 s1, s1, 0
	s_cmp_gt_u32 s14, 61
	s_cbranch_scc0 .LBB0_817
	s_and_b64 vcc, exec, s[28:29]
	s_cbranch_vccz .LBB0_820
	s_barrier

.LBB0_961:
	ds_read_b128 v[158:161], v185
	ds_read_b128 v[154:157], v185 offset:1024
	ds_read_b128 v[150:153], v185 offset:2048
	ds_read_b128 v[146:149], v185 offset:3072
	ds_read_b128 v[142:145], v186
	ds_read_b128 v[138:141], v186 offset:1024
	ds_read_b128 v[134:137], v186 offset:2048
	ds_read_b128 v[130:133], v186 offset:3072
	s_add_u32 s30, s28, 0xfff80080
	s_addc_u32 s31, s29, -1
	s_cmp_eq_u32 s45, 28
	s_cselect_b32 s35, s1, s31
	s_cselect_b32 s34, s15, s30
	s_cselect_b32 s31, s19, s44
	s_cselect_b32 s30, s42, s43
	v_lshl_add_u64 v[220:221], s[28:29], 0, v[170:171]
	s_add_i32 m0, s27, 0xc000
	ds_read_b128 v[174:177], v187
	ds_read_b128 v[178:181], v187 offset:1024
	ds_read_b128 v[188:191], v187 offset:2048
	ds_read_b128 v[192:195], v187 offset:3072
	ds_read_b128 v[202:205], v187 offset:4096
	ds_read_b128 v[206:209], v187 offset:5120
	ds_read_b128 v[210:213], v187 offset:6144
	ds_read_b128 v[214:217], v187 offset:7168
	global_load_lds_dwordx4 v[220:221], off
	v_lshl_add_u64 v[220:221], s[28:29], 0, v[172:173]
	s_add_i32 m0, s27, 0xe000
	s_nop 0
	global_load_lds_dwordx4 v[220:221], off
	s_waitcnt vmcnt(8)
	s_waitcnt lgkmcnt(0)
	s_barrier
	s_setprio 1
	s_waitcnt lgkmcnt(0)
	v_mfma_i32_16x16x64_i8 v[126:129], v[158:161], v[174:177], v[126:129]
	v_mfma_i32_16x16x64_i8 v[126:129], v[154:157], v[178:181], v[126:129]
	v_mfma_i32_16x16x64_i8 v[122:125], v[150:153], v[174:177], v[122:125]
	v_mfma_i32_16x16x64_i8 v[122:125], v[146:149], v[178:181], v[122:125]
	v_mfma_i32_16x16x64_i8 v[110:113], v[158:161], v[188:191], v[110:113]
	v_mfma_i32_16x16x64_i8 v[110:113], v[154:157], v[192:195], v[110:113]
	v_mfma_i32_16x16x64_i8 v[106:109], v[150:153], v[188:191], v[106:109]
	v_mfma_i32_16x16x64_i8 v[106:109], v[146:149], v[192:195], v[106:109]
	v_mfma_i32_16x16x64_i8 v[94:97], v[158:161], v[202:205], v[94:97]
	v_mfma_i32_16x16x64_i8 v[94:97], v[154:157], v[206:209], v[94:97]
	v_mfma_i32_16x16x64_i8 v[90:93], v[150:153], v[202:205], v[90:93]
	v_mfma_i32_16x16x64_i8 v[90:93], v[146:149], v[206:209], v[90:93]
	v_mfma_i32_16x16x64_i8 v[78:81], v[158:161], v[210:213], v[78:81]
	v_mfma_i32_16x16x64_i8 v[78:81], v[154:157], v[214:217], v[78:81]
	v_mfma_i32_16x16x64_i8 v[74:77], v[150:153], v[210:213], v[74:77]
	v_mfma_i32_16x16x64_i8 v[74:77], v[146:149], v[214:217], v[74:77]
	v_mfma_i32_16x16x64_i8 v[118:121], v[142:145], v[174:177], v[118:121]
	v_mfma_i32_16x16x64_i8 v[118:121], v[138:141], v[178:181], v[118:121]
	v_mfma_i32_16x16x64_i8 v[114:117], v[134:137], v[174:177], v[114:117]
	v_mfma_i32_16x16x64_i8 v[114:117], v[130:133], v[178:181], v[114:117]
	v_mfma_i32_16x16x64_i8 v[102:105], v[142:145], v[188:191], v[102:105]
	v_mfma_i32_16x16x64_i8 v[102:105], v[138:141], v[192:195], v[102:105]
	v_mfma_i32_16x16x64_i8 v[98:101], v[134:137], v[188:191], v[98:101]
	v_mfma_i32_16x16x64_i8 v[98:101], v[130:133], v[192:195], v[98:101]
	v_mfma_i32_16x16x64_i8 v[86:89], v[142:145], v[202:205], v[86:89]
	v_mfma_i32_16x16x64_i8 v[86:89], v[138:141], v[206:209], v[86:89]
	v_mfma_i32_16x16x64_i8 v[82:85], v[134:137], v[202:205], v[82:85]
	v_mfma_i32_16x16x64_i8 v[82:85], v[130:133], v[206:209], v[82:85]
	s_barrier
	s_setprio 2
	v_mfma_i32_16x16x64_i8 v[70:73], v[142:145], v[210:213], v[70:73]
	v_mfma_i32_16x16x64_i8 v[70:73], v[138:141], v[214:217], v[70:73]
	v_mfma_i32_16x16x64_i8 v[66:69], v[134:137], v[210:213], v[66:69]
	v_mfma_i32_16x16x64_i8 v[66:69], v[130:133], v[214:217], v[66:69]
	s_setprio 0
	s_add_i32 s46, s17, s9
	v_lshl_add_u64 v[174:175], s[30:31], 0, v[166:167]
	s_mov_b32 m0, s46
	ds_read_b128 v[188:191], v187 offset:16384
	ds_read_b128 v[192:195], v187 offset:17408
	ds_read_b128 v[202:205], v187 offset:18432
	ds_read_b128 v[206:209], v187 offset:19456
	ds_read_b128 v[210:213], v187 offset:20480
	ds_read_b128 v[214:217], v187 offset:21504
	ds_read_b128 v[220:223], v187 offset:22528
	ds_read_b128 v[224:227], v187 offset:23552
	global_load_lds_dwordx4 v[174:175], off
	s_add_i32 m0, s46, 0x2000
	s_add_u32 s46, s30, 0x80000
	v_lshl_add_u64 v[176:177], s[30:31], 0, v[162:163]
	s_addc_u32 s47, s31, 0
	s_add_i32 s48, s55, s9
	global_load_lds_dwordx4 v[176:177], off
	v_lshl_add_u64 v[178:179], s[46:47], 0, v[166:167]
	s_mov_b32 m0, s48
	v_lshl_add_u64 v[180:181], s[34:35], 0, v[164:165]
	global_load_lds_dwordx4 v[178:179], off
	v_lshl_add_u64 v[178:179], s[46:47], 0, v[162:163]
	s_add_i32 m0, s48, 0x2000
	s_nop 0
	global_load_lds_dwordx4 v[178:179], off
	v_lshl_add_u64 v[178:179], s[34:35], 0, v[168:169]
	s_mov_b32 m0, s27
	s_nop 0
	global_load_lds_dwordx4 v[178:179], off
	s_mov_b32 m0, s33
	s_nop 0
	global_load_lds_dwordx4 v[180:181], off
	s_waitcnt vmcnt(8)
	s_waitcnt lgkmcnt(0)
	s_barrier
	s_setprio 1
	s_waitcnt lgkmcnt(0)
	v_mfma_i32_16x16x64_i8 v[62:65], v[158:161], v[188:191], v[62:65]
	v_mfma_i32_16x16x64_i8 v[62:65], v[154:157], v[192:195], v[62:65]
	v_mfma_i32_16x16x64_i8 v[58:61], v[150:153], v[188:191], v[58:61]
	v_mfma_i32_16x16x64_i8 v[58:61], v[146:149], v[192:195], v[58:61]
	v_mfma_i32_16x16x64_i8 v[46:49], v[158:161], v[202:205], v[46:49]
	v_mfma_i32_16x16x64_i8 v[46:49], v[154:157], v[206:209], v[46:49]
	v_mfma_i32_16x16x64_i8 v[42:45], v[150:153], v[202:205], v[42:45]
	v_mfma_i32_16x16x64_i8 v[42:45], v[146:149], v[206:209], v[42:45]
	v_mfma_i32_16x16x64_i8 v[30:33], v[158:161], v[210:213], v[30:33]
	v_mfma_i32_16x16x64_i8 v[30:33], v[154:157], v[214:217], v[30:33]
	v_mfma_i32_16x16x64_i8 v[26:29], v[150:153], v[210:213], v[26:29]
	v_mfma_i32_16x16x64_i8 v[26:29], v[146:149], v[214:217], v[26:29]
	v_mfma_i32_16x16x64_i8 v[14:17], v[158:161], v[220:223], v[14:17]
	v_mfma_i32_16x16x64_i8 v[14:17], v[154:157], v[224:227], v[14:17]
	v_mfma_i32_16x16x64_i8 v[10:13], v[150:153], v[220:223], v[10:13]
	v_mfma_i32_16x16x64_i8 v[10:13], v[146:149], v[224:227], v[10:13]
	v_mfma_i32_16x16x64_i8 v[54:57], v[142:145], v[188:191], v[54:57]
	v_mfma_i32_16x16x64_i8 v[54:57], v[138:141], v[192:195], v[54:57]
	v_mfma_i32_16x16x64_i8 v[50:53], v[134:137], v[188:191], v[50:53]
	v_mfma_i32_16x16x64_i8 v[50:53], v[130:133], v[192:195], v[50:53]
	v_mfma_i32_16x16x64_i8 v[38:41], v[142:145], v[202:205], v[38:41]
	v_mfma_i32_16x16x64_i8 v[38:41], v[138:141], v[206:209], v[38:41]
	v_mfma_i32_16x16x64_i8 v[34:37], v[134:137], v[202:205], v[34:37]
	v_mfma_i32_16x16x64_i8 v[34:37], v[130:133], v[206:209], v[34:37]
	v_mfma_i32_16x16x64_i8 v[22:25], v[142:145], v[210:213], v[22:25]
	v_mfma_i32_16x16x64_i8 v[22:25], v[138:141], v[214:217], v[22:25]
	v_mfma_i32_16x16x64_i8 v[18:21], v[134:137], v[210:213], v[18:21]
	v_mfma_i32_16x16x64_i8 v[18:21], v[130:133], v[214:217], v[18:21]
	s_barrier
	s_setprio 2
	v_mfma_i32_16x16x64_i8 v[6:9], v[142:145], v[220:223], v[6:9]
	v_mfma_i32_16x16x64_i8 v[6:9], v[138:141], v[224:227], v[6:9]
	v_mfma_i32_16x16x64_i8 v[2:5], v[134:137], v[220:223], v[2:5]
	v_mfma_i32_16x16x64_i8 v[2:5], v[130:133], v[224:227], v[2:5]
	s_setprio 0
	v_add_u32_e32 v142, s56, v183
	v_add_u32_e32 v158, s57, v183
	ds_read_b128 v[130:133], v142
	ds_read_b128 v[134:137], v142 offset:1024
	ds_read_b128 v[138:141], v142 offset:2048
	ds_read_b128 v[142:145], v142 offset:3072
	ds_read_b128 v[146:149], v158
	ds_read_b128 v[150:153], v158 offset:1024
	ds_read_b128 v[154:157], v158 offset:2048
	ds_read_b128 v[158:161], v158 offset:3072
	s_add_u32 s34, s34, 0x80000
	s_addc_u32 s35, s35, 0
	s_mov_b32 m0, s36
	v_lshl_add_u64 v[232:233], s[34:35], 0, v[168:169]
	ds_read_b128 v[188:191], v187 offset:32768
	ds_read_b128 v[192:195], v187 offset:33792
	ds_read_b128 v[202:205], v187 offset:34816
	ds_read_b128 v[206:209], v187 offset:35840
	ds_read_b128 v[210:213], v187 offset:36864
	ds_read_b128 v[214:217], v187 offset:37888
	ds_read_b128 v[220:223], v187 offset:38912
	ds_read_b128 v[224:227], v187 offset:39936
	global_load_lds_dwordx4 v[232:233], off
	v_lshl_add_u64 v[232:233], s[34:35], 0, v[164:165]
	s_mov_b32 m0, s37
	s_nop 0
	global_load_lds_dwordx4 v[232:233], off
	s_waitcnt vmcnt(8)
	s_waitcnt lgkmcnt(0)
	s_barrier
	s_setprio 1
	s_waitcnt lgkmcnt(0)
	v_mfma_i32_16x16x64_i8 v[126:129], v[130:133], v[188:191], v[126:129]
	v_mfma_i32_16x16x64_i8 v[126:129], v[134:137], v[192:195], v[126:129]
	v_mfma_i32_16x16x64_i8 v[122:125], v[138:141], v[188:191], v[122:125]
	v_mfma_i32_16x16x64_i8 v[122:125], v[142:145], v[192:195], v[122:125]
	v_mfma_i32_16x16x64_i8 v[110:113], v[130:133], v[202:205], v[110:113]
	v_mfma_i32_16x16x64_i8 v[110:113], v[134:137], v[206:209], v[110:113]
	v_mfma_i32_16x16x64_i8 v[106:109], v[138:141], v[202:205], v[106:109]
	v_mfma_i32_16x16x64_i8 v[106:109], v[142:145], v[206:209], v[106:109]
	v_mfma_i32_16x16x64_i8 v[94:97], v[130:133], v[210:213], v[94:97]
	v_mfma_i32_16x16x64_i8 v[94:97], v[134:137], v[214:217], v[94:97]
	v_mfma_i32_16x16x64_i8 v[90:93], v[138:141], v[210:213], v[90:93]
	v_mfma_i32_16x16x64_i8 v[90:93], v[142:145], v[214:217], v[90:93]
	v_mfma_i32_16x16x64_i8 v[78:81], v[130:133], v[220:223], v[78:81]
	v_mfma_i32_16x16x64_i8 v[78:81], v[134:137], v[224:227], v[78:81]
	v_mfma_i32_16x16x64_i8 v[74:77], v[138:141], v[220:223], v[74:77]
	v_mfma_i32_16x16x64_i8 v[74:77], v[142:145], v[224:227], v[74:77]
	v_mfma_i32_16x16x64_i8 v[118:121], v[146:149], v[188:191], v[118:121]
	v_mfma_i32_16x16x64_i8 v[118:121], v[150:153], v[192:195], v[118:121]
	v_mfma_i32_16x16x64_i8 v[114:117], v[154:157], v[188:191], v[114:117]
	v_mfma_i32_16x16x64_i8 v[114:117], v[158:161], v[192:195], v[114:117]
	v_mfma_i32_16x16x64_i8 v[102:105], v[146:149], v[202:205], v[102:105]
	v_mfma_i32_16x16x64_i8 v[102:105], v[150:153], v[206:209], v[102:105]
	v_mfma_i32_16x16x64_i8 v[98:101], v[154:157], v[202:205], v[98:101]
	v_mfma_i32_16x16x64_i8 v[98:101], v[158:161], v[206:209], v[98:101]
	v_mfma_i32_16x16x64_i8 v[86:89], v[146:149], v[210:213], v[86:89]
	v_mfma_i32_16x16x64_i8 v[86:89], v[150:153], v[214:217], v[86:89]
	v_mfma_i32_16x16x64_i8 v[82:85], v[154:157], v[210:213], v[82:85]
	v_mfma_i32_16x16x64_i8 v[82:85], v[158:161], v[214:217], v[82:85]
	s_barrier
	s_setprio 2
	v_mfma_i32_16x16x64_i8 v[70:73], v[146:149], v[220:223], v[70:73]
	v_mfma_i32_16x16x64_i8 v[70:73], v[150:153], v[224:227], v[70:73]
	v_mfma_i32_16x16x64_i8 v[66:69], v[154:157], v[220:223], v[66:69]
	v_mfma_i32_16x16x64_i8 v[66:69], v[158:161], v[224:227], v[66:69]
	s_setprio 0
	s_add_i32 s34, s56, s9
	v_lshl_add_u64 v[174:175], v[174:175], 0, s[4:5]
	s_mov_b32 m0, s34
	ds_read_b128 v[188:191], v187 offset:49152
	ds_read_b128 v[192:195], v187 offset:50176
	ds_read_b128 v[202:205], v187 offset:51200
	ds_read_b128 v[206:209], v187 offset:52224
	ds_read_b128 v[210:213], v187 offset:53248
	ds_read_b128 v[214:217], v187 offset:54272
	ds_read_b128 v[220:223], v187 offset:55296
	ds_read_b128 v[224:227], v187 offset:56320
	global_load_lds_dwordx4 v[174:175], off
	s_add_i32 m0, s34, 0x2000
	s_add_u32 s30, s30, 0x80080
	v_lshl_add_u64 v[174:175], v[176:177], 0, s[4:5]
	s_addc_u32 s31, s31, 0
	s_add_i32 s34, s57, s9
	global_load_lds_dwordx4 v[174:175], off
	v_lshl_add_u64 v[174:175], s[30:31], 0, v[166:167]
	s_mov_b32 m0, s34
	s_nop 0
	global_load_lds_dwordx4 v[174:175], off
	v_lshl_add_u64 v[174:175], s[30:31], 0, v[162:163]
	s_add_i32 m0, s34, 0x2000
	s_nop 0
	global_load_lds_dwordx4 v[174:175], off
	v_lshl_add_u64 v[174:175], v[178:179], 0, s[4:5]
	s_mov_b32 m0, s39
	s_nop 0
	global_load_lds_dwordx4 v[174:175], off
	v_lshl_add_u64 v[174:175], v[180:181], 0, s[4:5]
	s_mov_b32 m0, s40
	s_nop 0
	global_load_lds_dwordx4 v[174:175], off
	s_waitcnt vmcnt(8)
	s_waitcnt lgkmcnt(0)
	s_barrier
	s_setprio 1
	s_waitcnt lgkmcnt(0)
	v_mfma_i32_16x16x64_i8 v[62:65], v[130:133], v[188:191], v[62:65]
	v_mfma_i32_16x16x64_i8 v[62:65], v[134:137], v[192:195], v[62:65]
	v_mfma_i32_16x16x64_i8 v[58:61], v[138:141], v[188:191], v[58:61]
	v_mfma_i32_16x16x64_i8 v[58:61], v[142:145], v[192:195], v[58:61]
	v_mfma_i32_16x16x64_i8 v[46:49], v[130:133], v[202:205], v[46:49]
	v_mfma_i32_16x16x64_i8 v[46:49], v[134:137], v[206:209], v[46:49]
	v_mfma_i32_16x16x64_i8 v[42:45], v[138:141], v[202:205], v[42:45]
	v_mfma_i32_16x16x64_i8 v[42:45], v[142:145], v[206:209], v[42:45]
	v_mfma_i32_16x16x64_i8 v[30:33], v[130:133], v[210:213], v[30:33]
	v_mfma_i32_16x16x64_i8 v[30:33], v[134:137], v[214:217], v[30:33]
	v_mfma_i32_16x16x64_i8 v[26:29], v[138:141], v[210:213], v[26:29]
	v_mfma_i32_16x16x64_i8 v[26:29], v[142:145], v[214:217], v[26:29]
	v_mfma_i32_16x16x64_i8 v[14:17], v[130:133], v[220:223], v[14:17]
	v_mfma_i32_16x16x64_i8 v[14:17], v[134:137], v[224:227], v[14:17]
	v_mfma_i32_16x16x64_i8 v[10:13], v[138:141], v[220:223], v[10:13]
	v_mfma_i32_16x16x64_i8 v[10:13], v[142:145], v[224:227], v[10:13]
	v_mfma_i32_16x16x64_i8 v[54:57], v[146:149], v[188:191], v[54:57]
	v_mfma_i32_16x16x64_i8 v[54:57], v[150:153], v[192:195], v[54:57]
	v_mfma_i32_16x16x64_i8 v[50:53], v[154:157], v[188:191], v[50:53]
	v_mfma_i32_16x16x64_i8 v[50:53], v[158:161], v[192:195], v[50:53]
	v_mfma_i32_16x16x64_i8 v[38:41], v[146:149], v[202:205], v[38:41]
	v_mfma_i32_16x16x64_i8 v[38:41], v[150:153], v[206:209], v[38:41]
	v_mfma_i32_16x16x64_i8 v[34:37], v[154:157], v[202:205], v[34:37]
	v_mfma_i32_16x16x64_i8 v[34:37], v[158:161], v[206:209], v[34:37]
	v_mfma_i32_16x16x64_i8 v[22:25], v[146:149], v[210:213], v[22:25]
	v_mfma_i32_16x16x64_i8 v[22:25], v[150:153], v[214:217], v[22:25]
	v_mfma_i32_16x16x64_i8 v[18:21], v[154:157], v[210:213], v[18:21]
	v_mfma_i32_16x16x64_i8 v[18:21], v[158:161], v[214:217], v[18:21]
	s_barrier
	s_setprio 2
	v_mfma_i32_16x16x64_i8 v[6:9], v[146:149], v[220:223], v[6:9]
	v_mfma_i32_16x16x64_i8 v[6:9], v[150:153], v[224:227], v[6:9]
	v_mfma_i32_16x16x64_i8 v[2:5], v[154:157], v[220:223], v[2:5]
	v_mfma_i32_16x16x64_i8 v[2:5], v[158:161], v[224:227], v[2:5]
	s_setprio 0
	s_add_i32 s45, s45, 2
	s_add_u32 s28, s28, 0x100
	s_addc_u32 s29, s29, 0
	s_add_u32 s43, s43, 0x100
	s_addc_u32 s44, s44, 0
	s_cmp_gt_u32 s45, 29
	s_cbranch_scc0 .LBB0_961
	s_nop 15
	s_nop 15
	s_and_b64 vcc, exec, s[6:7]
	s_cbranch_vccz .LBB0_964
	s_barrier

.LBB0_1058:
	ds_read_b128 v[128:131], v194
	ds_read_b128 v[132:135], v194 offset:1024
	ds_read_b128 v[136:139], v194 offset:2048
	ds_read_b128 v[140:143], v194 offset:3072
	ds_read_b128 v[144:147], v195
	ds_read_b128 v[148:151], v195 offset:1024
	ds_read_b128 v[152:155], v195 offset:2048
	ds_read_b128 v[156:159], v195 offset:3072
	s_add_u32 s2, s0, 0x100
	s_addc_u32 s3, s1, 0
	s_cmpk_eq_i32 s39, 0xa8
	s_cselect_b32 s37, s31, s3
	s_cselect_b32 s36, s30, s2
	s_cselect_b32 s5, s7, s38
	s_cselect_b32 s4, s6, s29
	v_lshl_add_u64 v[188:189], s[0:1], 0, v[168:169]
	s_add_i32 m0, s27, 0xc000
	ds_read_b128 v[172:175], v196
	ds_read_b128 v[176:179], v196 offset:1024
	ds_read_b128 v[180:183], v196 offset:2048
	ds_read_b128 v[184:187], v196 offset:3072
	ds_read_b128 v[200:203], v196 offset:4096
	ds_read_b128 v[204:207], v196 offset:5120
	ds_read_b128 v[208:211], v196 offset:6144
	ds_read_b128 v[212:215], v196 offset:7168
	global_load_lds_dwordx4 v[188:189], off
	v_lshl_add_u64 v[188:189], s[0:1], 0, v[170:171]
	s_add_i32 m0, s27, 0xe000
	s_nop 0
	global_load_lds_dwordx4 v[188:189], off
	s_waitcnt vmcnt(8)
	s_waitcnt lgkmcnt(0)
	s_barrier
	s_setprio 1
	s_waitcnt lgkmcnt(0)
	v_mfma_f32_16x16x32_bf16 v[12:15], v[128:131], v[172:175], v[12:15]
	v_mfma_f32_16x16x32_bf16 v[8:11], v[136:139], v[172:175], v[8:11]
	v_mfma_f32_16x16x32_bf16 v[36:39], v[128:131], v[180:183], v[36:39]
	v_mfma_f32_16x16x32_bf16 v[32:35], v[136:139], v[180:183], v[32:35]
	v_mfma_f32_16x16x32_bf16 v[44:47], v[128:131], v[200:203], v[44:47]
	v_mfma_f32_16x16x32_bf16 v[40:43], v[136:139], v[200:203], v[40:43]
	v_mfma_f32_16x16x32_bf16 v[64:67], v[128:131], v[208:211], v[64:67]
	v_mfma_f32_16x16x32_bf16 v[56:59], v[136:139], v[208:211], v[56:59]
	v_mfma_f32_16x16x32_bf16 v[12:15], v[132:135], v[176:179], v[12:15]
	v_mfma_f32_16x16x32_bf16 v[8:11], v[140:143], v[176:179], v[8:11]
	v_mfma_f32_16x16x32_bf16 v[36:39], v[132:135], v[184:187], v[36:39]
	v_mfma_f32_16x16x32_bf16 v[32:35], v[140:143], v[184:187], v[32:35]
	v_mfma_f32_16x16x32_bf16 v[44:47], v[132:135], v[204:207], v[44:47]
	v_mfma_f32_16x16x32_bf16 v[40:43], v[140:143], v[204:207], v[40:43]
	v_mfma_f32_16x16x32_bf16 v[64:67], v[132:135], v[212:215], v[64:67]
	v_mfma_f32_16x16x32_bf16 v[56:59], v[140:143], v[212:215], v[56:59]
	v_mfma_f32_16x16x32_bf16 v[4:7], v[144:147], v[172:175], v[4:7]
	v_mfma_f32_16x16x32_bf16 v[0:3], v[152:155], v[172:175], v[0:3]
	v_mfma_f32_16x16x32_bf16 v[24:27], v[144:147], v[180:183], v[24:27]
	v_mfma_f32_16x16x32_bf16 v[16:19], v[152:155], v[180:183], v[16:19]
	v_mfma_f32_16x16x32_bf16 v[28:31], v[144:147], v[200:203], v[28:31]
	v_mfma_f32_16x16x32_bf16 v[20:23], v[152:155], v[200:203], v[20:23]
	v_mfma_f32_16x16x32_bf16 v[52:55], v[144:147], v[208:211], v[52:55]
	v_mfma_f32_16x16x32_bf16 v[48:51], v[152:155], v[208:211], v[48:51]
	v_mfma_f32_16x16x32_bf16 v[4:7], v[148:151], v[176:179], v[4:7]
	v_mfma_f32_16x16x32_bf16 v[0:3], v[156:159], v[176:179], v[0:3]
	v_mfma_f32_16x16x32_bf16 v[24:27], v[148:151], v[184:187], v[24:27]
	v_mfma_f32_16x16x32_bf16 v[16:19], v[156:159], v[184:187], v[16:19]
	s_barrier
	s_setprio 2
	v_mfma_f32_16x16x32_bf16 v[28:31], v[148:151], v[204:207], v[28:31]
	v_mfma_f32_16x16x32_bf16 v[20:23], v[156:159], v[204:207], v[20:23]
	v_mfma_f32_16x16x32_bf16 v[52:55], v[148:151], v[212:215], v[52:55]
	v_mfma_f32_16x16x32_bf16 v[48:51], v[156:159], v[212:215], v[48:51]
	s_setprio 0
	s_add_i32 s0, s17, s25
	v_lshl_add_u64 v[188:189], s[4:5], 0, v[162:163]
	s_mov_b32 m0, s0
	ds_read_b128 v[172:175], v196 offset:16384
	ds_read_b128 v[176:179], v196 offset:17408
	ds_read_b128 v[180:183], v196 offset:18432
	ds_read_b128 v[184:187], v196 offset:19456
	ds_read_b128 v[200:203], v196 offset:20480
	ds_read_b128 v[204:207], v196 offset:21504
	ds_read_b128 v[208:211], v196 offset:22528
	ds_read_b128 v[212:215], v196 offset:23552
	global_load_lds_dwordx4 v[188:189], off
	s_add_i32 m0, s0, 0x2000
	s_add_u32 s0, s4, 0x2b0000
	v_lshl_add_u64 v[216:217], s[4:5], 0, v[166:167]
	s_addc_u32 s1, s5, 0
	s_add_i32 s40, s55, s25
	global_load_lds_dwordx4 v[216:217], off
	v_lshl_add_u64 v[220:221], s[0:1], 0, v[162:163]
	s_mov_b32 m0, s40
	v_lshl_add_u64 v[222:223], s[36:37], 0, v[164:165]
	global_load_lds_dwordx4 v[220:221], off
	v_lshl_add_u64 v[220:221], s[0:1], 0, v[166:167]
	s_add_i32 m0, s40, 0x2000
	s_nop 0
	global_load_lds_dwordx4 v[220:221], off
	v_lshl_add_u64 v[220:221], s[36:37], 0, v[160:161]
	s_mov_b32 m0, s27
	s_nop 0
	global_load_lds_dwordx4 v[220:221], off
	s_mov_b32 m0, s33
	s_nop 0
	global_load_lds_dwordx4 v[222:223], off
	s_waitcnt vmcnt(8)
	s_waitcnt lgkmcnt(0)
	s_barrier
	s_setprio 1
	s_waitcnt lgkmcnt(0)
	v_mfma_f32_16x16x32_bf16 v[76:79], v[128:131], v[172:175], v[76:79]
	v_mfma_f32_16x16x32_bf16 v[72:75], v[136:139], v[172:175], v[72:75]
	v_mfma_f32_16x16x32_bf16 v[92:95], v[128:131], v[180:183], v[92:95]
	v_mfma_f32_16x16x32_bf16 v[88:91], v[136:139], v[180:183], v[88:91]
	v_mfma_f32_16x16x32_bf16 v[108:111], v[128:131], v[200:203], v[108:111]
	v_mfma_f32_16x16x32_bf16 v[104:107], v[136:139], v[200:203], v[104:107]
	v_mfma_f32_16x16x32_bf16 v[124:127], v[128:131], v[208:211], v[124:127]
	v_mfma_f32_16x16x32_bf16 v[120:123], v[136:139], v[208:211], v[120:123]
	v_mfma_f32_16x16x32_bf16 v[76:79], v[132:135], v[176:179], v[76:79]
	v_mfma_f32_16x16x32_bf16 v[72:75], v[140:143], v[176:179], v[72:75]
	v_mfma_f32_16x16x32_bf16 v[92:95], v[132:135], v[184:187], v[92:95]
	v_mfma_f32_16x16x32_bf16 v[88:91], v[140:143], v[184:187], v[88:91]
	v_mfma_f32_16x16x32_bf16 v[108:111], v[132:135], v[204:207], v[108:111]
	v_mfma_f32_16x16x32_bf16 v[104:107], v[140:143], v[204:207], v[104:107]
	v_mfma_f32_16x16x32_bf16 v[124:127], v[132:135], v[212:215], v[124:127]
	v_mfma_f32_16x16x32_bf16 v[120:123], v[140:143], v[212:215], v[120:123]
	v_mfma_f32_16x16x32_bf16 v[68:71], v[144:147], v[172:175], v[68:71]
	v_mfma_f32_16x16x32_bf16 v[60:63], v[152:155], v[172:175], v[60:63]
	v_mfma_f32_16x16x32_bf16 v[84:87], v[144:147], v[180:183], v[84:87]
	v_mfma_f32_16x16x32_bf16 v[80:83], v[152:155], v[180:183], v[80:83]
	v_mfma_f32_16x16x32_bf16 v[100:103], v[144:147], v[200:203], v[100:103]
	v_mfma_f32_16x16x32_bf16 v[96:99], v[152:155], v[200:203], v[96:99]
	v_mfma_f32_16x16x32_bf16 v[116:119], v[144:147], v[208:211], v[116:119]
	v_mfma_f32_16x16x32_bf16 v[112:115], v[152:155], v[208:211], v[112:115]
	v_mfma_f32_16x16x32_bf16 v[68:71], v[148:151], v[176:179], v[68:71]
	v_mfma_f32_16x16x32_bf16 v[60:63], v[156:159], v[176:179], v[60:63]
	v_mfma_f32_16x16x32_bf16 v[84:87], v[148:151], v[184:187], v[84:87]
	v_mfma_f32_16x16x32_bf16 v[80:83], v[156:159], v[184:187], v[80:83]
	s_barrier
	s_setprio 2
	v_mfma_f32_16x16x32_bf16 v[100:103], v[148:151], v[204:207], v[100:103]
	v_mfma_f32_16x16x32_bf16 v[96:99], v[156:159], v[204:207], v[96:99]
	v_mfma_f32_16x16x32_bf16 v[116:119], v[148:151], v[212:215], v[116:119]
	v_mfma_f32_16x16x32_bf16 v[112:115], v[156:159], v[212:215], v[112:115]
	s_setprio 0
	v_add_u32_e32 v140, s56, v193
	v_add_u32_e32 v156, s57, v193
	ds_read_b128 v[128:131], v140
	ds_read_b128 v[132:135], v140 offset:1024
	ds_read_b128 v[136:139], v140 offset:2048
	ds_read_b128 v[140:143], v140 offset:3072
	ds_read_b128 v[144:147], v156
	ds_read_b128 v[148:151], v156 offset:1024
	ds_read_b128 v[152:155], v156 offset:2048
	ds_read_b128 v[156:159], v156 offset:3072
	s_add_u32 s0, s36, 0x2b0000
	s_addc_u32 s1, s37, 0
	s_mov_b32 m0, s46
	v_lshl_add_u64 v[224:225], s[0:1], 0, v[160:161]
	ds_read_b128 v[172:175], v196 offset:32768
	ds_read_b128 v[176:179], v196 offset:33792
	ds_read_b128 v[180:183], v196 offset:34816
	ds_read_b128 v[184:187], v196 offset:35840
	ds_read_b128 v[200:203], v196 offset:36864
	ds_read_b128 v[204:207], v196 offset:37888
	ds_read_b128 v[208:211], v196 offset:38912
	ds_read_b128 v[212:215], v196 offset:39936
	global_load_lds_dwordx4 v[224:225], off
	v_lshl_add_u64 v[224:225], s[0:1], 0, v[164:165]
	s_mov_b32 m0, s47
	s_nop 0
	global_load_lds_dwordx4 v[224:225], off
	s_waitcnt vmcnt(8)
	s_waitcnt lgkmcnt(0)
	s_barrier
	s_setprio 1
	s_waitcnt lgkmcnt(0)
	v_mfma_f32_16x16x32_bf16 v[12:15], v[128:131], v[172:175], v[12:15]
	v_mfma_f32_16x16x32_bf16 v[8:11], v[136:139], v[172:175], v[8:11]
	v_mfma_f32_16x16x32_bf16 v[36:39], v[128:131], v[180:183], v[36:39]
	v_mfma_f32_16x16x32_bf16 v[32:35], v[136:139], v[180:183], v[32:35]
	v_mfma_f32_16x16x32_bf16 v[44:47], v[128:131], v[200:203], v[44:47]
	v_mfma_f32_16x16x32_bf16 v[40:43], v[136:139], v[200:203], v[40:43]
	v_mfma_f32_16x16x32_bf16 v[64:67], v[128:131], v[208:211], v[64:67]
	v_mfma_f32_16x16x32_bf16 v[56:59], v[136:139], v[208:211], v[56:59]
	v_mfma_f32_16x16x32_bf16 v[12:15], v[132:135], v[176:179], v[12:15]
	v_mfma_f32_16x16x32_bf16 v[8:11], v[140:143], v[176:179], v[8:11]
	v_mfma_f32_16x16x32_bf16 v[36:39], v[132:135], v[184:187], v[36:39]
	v_mfma_f32_16x16x32_bf16 v[32:35], v[140:143], v[184:187], v[32:35]
	v_mfma_f32_16x16x32_bf16 v[44:47], v[132:135], v[204:207], v[44:47]
	v_mfma_f32_16x16x32_bf16 v[40:43], v[140:143], v[204:207], v[40:43]
	v_mfma_f32_16x16x32_bf16 v[64:67], v[132:135], v[212:215], v[64:67]
	v_mfma_f32_16x16x32_bf16 v[56:59], v[140:143], v[212:215], v[56:59]
	v_mfma_f32_16x16x32_bf16 v[4:7], v[144:147], v[172:175], v[4:7]
	v_mfma_f32_16x16x32_bf16 v[0:3], v[152:155], v[172:175], v[0:3]
	v_mfma_f32_16x16x32_bf16 v[24:27], v[144:147], v[180:183], v[24:27]
	v_mfma_f32_16x16x32_bf16 v[16:19], v[152:155], v[180:183], v[16:19]
	v_mfma_f32_16x16x32_bf16 v[28:31], v[144:147], v[200:203], v[28:31]
	v_mfma_f32_16x16x32_bf16 v[20:23], v[152:155], v[200:203], v[20:23]
	v_mfma_f32_16x16x32_bf16 v[52:55], v[144:147], v[208:211], v[52:55]
	v_mfma_f32_16x16x32_bf16 v[48:51], v[152:155], v[208:211], v[48:51]
	v_mfma_f32_16x16x32_bf16 v[4:7], v[148:151], v[176:179], v[4:7]
	v_mfma_f32_16x16x32_bf16 v[0:3], v[156:159], v[176:179], v[0:3]
	v_mfma_f32_16x16x32_bf16 v[24:27], v[148:151], v[184:187], v[24:27]
	v_mfma_f32_16x16x32_bf16 v[16:19], v[156:159], v[184:187], v[16:19]
	s_barrier
	s_setprio 2
	v_mfma_f32_16x16x32_bf16 v[28:31], v[148:151], v[204:207], v[28:31]
	v_mfma_f32_16x16x32_bf16 v[20:23], v[156:159], v[204:207], v[20:23]
	v_mfma_f32_16x16x32_bf16 v[52:55], v[148:151], v[212:215], v[52:55]
	v_mfma_f32_16x16x32_bf16 v[48:51], v[156:159], v[212:215], v[48:51]
	s_setprio 0
	s_add_i32 s0, s56, s25
	v_lshl_add_u64 v[188:189], v[188:189], 0, s[18:19]
	s_mov_b32 m0, s0
	ds_read_b128 v[172:175], v196 offset:49152
	ds_read_b128 v[176:179], v196 offset:50176
	ds_read_b128 v[180:183], v196 offset:51200
	ds_read_b128 v[184:187], v196 offset:52224
	ds_read_b128 v[200:203], v196 offset:53248
	ds_read_b128 v[204:207], v196 offset:54272
	ds_read_b128 v[208:211], v196 offset:55296
	ds_read_b128 v[212:215], v196 offset:56320
	global_load_lds_dwordx4 v[188:189], off
	s_add_i32 m0, s0, 0x2000
	s_add_u32 s0, s4, 0x2b0080
	v_lshl_add_u64 v[188:189], v[216:217], 0, s[18:19]
	s_addc_u32 s1, s5, 0
	s_add_i32 s4, s57, s25
	global_load_lds_dwordx4 v[188:189], off
	v_lshl_add_u64 v[188:189], s[0:1], 0, v[162:163]
	s_mov_b32 m0, s4
	s_nop 0
	global_load_lds_dwordx4 v[188:189], off
	v_lshl_add_u64 v[188:189], s[0:1], 0, v[166:167]
	s_add_i32 m0, s4, 0x2000
	s_nop 0
	global_load_lds_dwordx4 v[188:189], off
	v_lshl_add_u64 v[188:189], v[220:221], 0, s[18:19]
	s_mov_b32 m0, s52
	s_nop 0
	global_load_lds_dwordx4 v[188:189], off
	v_lshl_add_u64 v[188:189], v[222:223], 0, s[18:19]
	s_mov_b32 m0, s53
	s_nop 0
	global_load_lds_dwordx4 v[188:189], off
	s_waitcnt vmcnt(8)
	s_waitcnt lgkmcnt(0)
	s_barrier
	s_setprio 1
	s_waitcnt lgkmcnt(0)
	v_mfma_f32_16x16x32_bf16 v[76:79], v[128:131], v[172:175], v[76:79]
	v_mfma_f32_16x16x32_bf16 v[72:75], v[136:139], v[172:175], v[72:75]
	v_mfma_f32_16x16x32_bf16 v[92:95], v[128:131], v[180:183], v[92:95]
	v_mfma_f32_16x16x32_bf16 v[88:91], v[136:139], v[180:183], v[88:91]
	v_mfma_f32_16x16x32_bf16 v[108:111], v[128:131], v[200:203], v[108:111]
	v_mfma_f32_16x16x32_bf16 v[104:107], v[136:139], v[200:203], v[104:107]
	v_mfma_f32_16x16x32_bf16 v[124:127], v[128:131], v[208:211], v[124:127]
	v_mfma_f32_16x16x32_bf16 v[120:123], v[136:139], v[208:211], v[120:123]
	v_mfma_f32_16x16x32_bf16 v[76:79], v[132:135], v[176:179], v[76:79]
	v_mfma_f32_16x16x32_bf16 v[72:75], v[140:143], v[176:179], v[72:75]
	v_mfma_f32_16x16x32_bf16 v[92:95], v[132:135], v[184:187], v[92:95]
	v_mfma_f32_16x16x32_bf16 v[88:91], v[140:143], v[184:187], v[88:91]
	v_mfma_f32_16x16x32_bf16 v[108:111], v[132:135], v[204:207], v[108:111]
	v_mfma_f32_16x16x32_bf16 v[104:107], v[140:143], v[204:207], v[104:107]
	v_mfma_f32_16x16x32_bf16 v[124:127], v[132:135], v[212:215], v[124:127]
	v_mfma_f32_16x16x32_bf16 v[120:123], v[140:143], v[212:215], v[120:123]
	v_mfma_f32_16x16x32_bf16 v[68:71], v[144:147], v[172:175], v[68:71]
	v_mfma_f32_16x16x32_bf16 v[60:63], v[152:155], v[172:175], v[60:63]
	v_mfma_f32_16x16x32_bf16 v[84:87], v[144:147], v[180:183], v[84:87]
	v_mfma_f32_16x16x32_bf16 v[80:83], v[152:155], v[180:183], v[80:83]
	v_mfma_f32_16x16x32_bf16 v[100:103], v[144:147], v[200:203], v[100:103]
	v_mfma_f32_16x16x32_bf16 v[96:99], v[152:155], v[200:203], v[96:99]
	v_mfma_f32_16x16x32_bf16 v[116:119], v[144:147], v[208:211], v[116:119]
	v_mfma_f32_16x16x32_bf16 v[112:115], v[152:155], v[208:211], v[112:115]
	v_mfma_f32_16x16x32_bf16 v[68:71], v[148:151], v[176:179], v[68:71]
	v_mfma_f32_16x16x32_bf16 v[60:63], v[156:159], v[176:179], v[60:63]
	v_mfma_f32_16x16x32_bf16 v[84:87], v[148:151], v[184:187], v[84:87]
	v_mfma_f32_16x16x32_bf16 v[80:83], v[156:159], v[184:187], v[80:83]
	s_barrier
	s_setprio 2
	v_mfma_f32_16x16x32_bf16 v[100:103], v[148:151], v[204:207], v[100:103]
	v_mfma_f32_16x16x32_bf16 v[96:99], v[156:159], v[204:207], v[96:99]
	v_mfma_f32_16x16x32_bf16 v[116:119], v[148:151], v[212:215], v[116:119]
	v_mfma_f32_16x16x32_bf16 v[112:115], v[156:159], v[212:215], v[112:115]
	s_setprio 0
	s_add_i32 s39, s39, 2
	s_add_u32 s29, s29, 0x100
	s_addc_u32 s38, s38, 0
	s_cmpk_gt_u32 s39, 0xa9
	s_mov_b64 s[0:1], s[2:3]
	s_cbranch_scc0 .LBB0_1058
	s_and_b64 vcc, exec, s[20:21]
	s_cbranch_vccz .LBB0_1061
	s_barrier
